# LDS-DMA issue rebalanced to 4 pieces per K-loop load segment: the fourth segment's last two pieces are issued at the next iteration's loop top (guarded for a tile's first / last iteration), closing wa
# speedup vs baseline: 1.0135x; 1.0001x over previous
.LBB0_163:
	s_cmp_eq_i32 s55, -2
	s_cbranch_scc1 .Lbal_first_21
	s_mov_b32 m0, s45
	s_nop 0
	global_load_lds_dwordx4 v221, s[100:101]
	s_mov_b32 m0, s46
	s_nop 0
	global_load_lds_dwordx4 v205, s[100:101]
.Lbal_first_21:
	ds_read_b128 v[144:147], v151
	ds_read_b128 v[156:159], v151 offset:1024
	ds_read_b128 v[160:163], v151 offset:2048
	ds_read_b128 v[164:167], v151 offset:3072
	ds_read_b128 v[168:171], v152
	ds_read_b128 v[172:175], v152 offset:1024
	ds_read_b128 v[176:179], v152 offset:2048
	ds_read_b128 v[180:183], v152 offset:3072
	s_add_u32 s26, s24, 0xfffc0080
	s_addc_u32 s27, s25, -1
	s_cmp_eq_u32 s55, 12
	s_cselect_b32 s29, s19, s27
	s_cselect_b32 s28, s51, s26
	s_cselect_b32 s27, s17, s54
	s_cselect_b32 s26, s52, s53
	s_add_i32 m0, s38, 0xc000
	ds_read_b128 v[184:187], v153
	ds_read_b128 v[188:191], v153 offset:1024
	ds_read_b128 v[192:195], v153 offset:2048
	ds_read_b128 v[196:199], v153 offset:3072
	ds_read_b128 v[200:203], v153 offset:4096
	ds_read_b128 v[208:211], v153 offset:5120
	ds_read_b128 v[212:215], v153 offset:6144
	ds_read_b128 v[216:219], v153 offset:7168
	global_load_lds_dwordx4 v138, s[24:25]
	s_add_i32 m0, s38, 0xe000
	s_nop 0
	global_load_lds_dwordx4 v136, s[24:25]
	s_waitcnt vmcnt(8)
	s_waitcnt lgkmcnt(0)
	s_barrier
	s_waitcnt lgkmcnt(0)
	v_mfma_f32_16x16x32_bf16 v[124:127], v[144:147], v[184:187], v[124:127]
	v_mfma_f32_16x16x32_bf16 v[120:123], v[160:163], v[184:187], v[120:123]
	v_mfma_f32_16x16x32_bf16 v[108:111], v[144:147], v[192:195], v[108:111]
	v_mfma_f32_16x16x32_bf16 v[104:107], v[160:163], v[192:195], v[104:107]
	v_mfma_f32_16x16x32_bf16 v[92:95], v[144:147], v[200:203], v[92:95]
	v_mfma_f32_16x16x32_bf16 v[88:91], v[160:163], v[200:203], v[88:91]
	v_mfma_f32_16x16x32_bf16 v[76:79], v[144:147], v[212:215], v[76:79]
	v_mfma_f32_16x16x32_bf16 v[72:75], v[160:163], v[212:215], v[72:75]
	v_mfma_f32_16x16x32_bf16 v[124:127], v[156:159], v[188:191], v[124:127]
	v_mfma_f32_16x16x32_bf16 v[120:123], v[164:167], v[188:191], v[120:123]
	v_mfma_f32_16x16x32_bf16 v[108:111], v[156:159], v[196:199], v[108:111]
	v_mfma_f32_16x16x32_bf16 v[104:107], v[164:167], v[196:199], v[104:107]
	v_mfma_f32_16x16x32_bf16 v[92:95], v[156:159], v[208:211], v[92:95]
	v_mfma_f32_16x16x32_bf16 v[88:91], v[164:167], v[208:211], v[88:91]
	v_mfma_f32_16x16x32_bf16 v[76:79], v[156:159], v[216:219], v[76:79]
	v_mfma_f32_16x16x32_bf16 v[72:75], v[164:167], v[216:219], v[72:75]
	v_mfma_f32_16x16x32_bf16 v[116:119], v[168:171], v[184:187], v[116:119]
	v_mfma_f32_16x16x32_bf16 v[112:115], v[176:179], v[184:187], v[112:115]
	v_mfma_f32_16x16x32_bf16 v[100:103], v[168:171], v[192:195], v[100:103]
	v_mfma_f32_16x16x32_bf16 v[96:99], v[176:179], v[192:195], v[96:99]
	v_mfma_f32_16x16x32_bf16 v[84:87], v[168:171], v[200:203], v[84:87]
	v_mfma_f32_16x16x32_bf16 v[80:83], v[176:179], v[200:203], v[80:83]
	v_mfma_f32_16x16x32_bf16 v[68:71], v[168:171], v[212:215], v[68:71]
	v_mfma_f32_16x16x32_bf16 v[64:67], v[176:179], v[212:215], v[64:67]
	v_mfma_f32_16x16x32_bf16 v[116:119], v[172:175], v[188:191], v[116:119]
	v_mfma_f32_16x16x32_bf16 v[112:115], v[180:183], v[188:191], v[112:115]
	v_mfma_f32_16x16x32_bf16 v[100:103], v[172:175], v[196:199], v[100:103]
	v_mfma_f32_16x16x32_bf16 v[96:99], v[180:183], v[196:199], v[96:99]
	v_mfma_f32_16x16x32_bf16 v[84:87], v[172:175], v[208:211], v[84:87]
	v_mfma_f32_16x16x32_bf16 v[80:83], v[180:183], v[208:211], v[80:83]
	v_mfma_f32_16x16x32_bf16 v[68:71], v[172:175], v[216:219], v[68:71]
	v_mfma_f32_16x16x32_bf16 v[64:67], v[180:183], v[216:219], v[64:67]
	s_barrier
	s_add_i32 s56, s48, s35
	s_mov_b32 m0, s56
	ds_read_b128 v[184:187], v153 offset:16384
	ds_read_b128 v[188:191], v153 offset:17408
	ds_read_b128 v[192:195], v153 offset:18432
	ds_read_b128 v[196:199], v153 offset:19456
	ds_read_b128 v[200:203], v153 offset:20480
	ds_read_b128 v[208:211], v153 offset:21504
	ds_read_b128 v[212:215], v153 offset:22528
	ds_read_b128 v[216:219], v153 offset:23552
	global_load_lds_dwordx4 v132, s[26:27]
	s_add_i32 m0, s56, 0x2000
	s_add_u32 s56, s26, 0x40000
	s_mov_b64 s[98:99], s[26:27]
	s_addc_u32 s57, s27, 0
	s_add_i32 s58, s49, s35
	global_load_lds_dwordx4 v128, s[26:27]
	s_mov_b32 m0, s58
	s_mov_b64 s[100:101], s[28:29]
	global_load_lds_dwordx4 v132, s[56:57]
	s_add_i32 m0, s58, 0x2000
	s_nop 0
	global_load_lds_dwordx4 v128, s[56:57]
	s_waitcnt vmcnt(6)
	s_waitcnt lgkmcnt(0)
	s_barrier
	s_waitcnt lgkmcnt(0)
	v_mfma_f32_16x16x32_bf16 v[60:63], v[144:147], v[184:187], v[60:63]
	v_mfma_f32_16x16x32_bf16 v[56:59], v[160:163], v[184:187], v[56:59]
	v_mfma_f32_16x16x32_bf16 v[44:47], v[144:147], v[192:195], v[44:47]
	v_mfma_f32_16x16x32_bf16 v[40:43], v[160:163], v[192:195], v[40:43]
	v_mfma_f32_16x16x32_bf16 v[28:31], v[144:147], v[200:203], v[28:31]
	v_mfma_f32_16x16x32_bf16 v[24:27], v[160:163], v[200:203], v[24:27]
	v_mfma_f32_16x16x32_bf16 v[12:15], v[144:147], v[212:215], v[12:15]
	v_mfma_f32_16x16x32_bf16 v[8:11], v[160:163], v[212:215], v[8:11]
	v_mfma_f32_16x16x32_bf16 v[60:63], v[156:159], v[188:191], v[60:63]
	v_mfma_f32_16x16x32_bf16 v[56:59], v[164:167], v[188:191], v[56:59]
	v_mfma_f32_16x16x32_bf16 v[44:47], v[156:159], v[196:199], v[44:47]
	v_mfma_f32_16x16x32_bf16 v[40:43], v[164:167], v[196:199], v[40:43]
	v_mfma_f32_16x16x32_bf16 v[28:31], v[156:159], v[208:211], v[28:31]
	v_mfma_f32_16x16x32_bf16 v[24:27], v[164:167], v[208:211], v[24:27]
	v_mfma_f32_16x16x32_bf16 v[12:15], v[156:159], v[216:219], v[12:15]
	v_mfma_f32_16x16x32_bf16 v[8:11], v[164:167], v[216:219], v[8:11]
	v_mfma_f32_16x16x32_bf16 v[52:55], v[168:171], v[184:187], v[52:55]
	v_mfma_f32_16x16x32_bf16 v[48:51], v[176:179], v[184:187], v[48:51]
	v_mfma_f32_16x16x32_bf16 v[36:39], v[168:171], v[192:195], v[36:39]
	v_mfma_f32_16x16x32_bf16 v[32:35], v[176:179], v[192:195], v[32:35]
	v_mfma_f32_16x16x32_bf16 v[20:23], v[168:171], v[200:203], v[20:23]
	v_mfma_f32_16x16x32_bf16 v[16:19], v[176:179], v[200:203], v[16:19]
	v_mfma_f32_16x16x32_bf16 v[4:7], v[168:171], v[212:215], v[4:7]
	v_mfma_f32_16x16x32_bf16 v[0:3], v[176:179], v[212:215], v[0:3]
	v_mfma_f32_16x16x32_bf16 v[52:55], v[172:175], v[188:191], v[52:55]
	v_mfma_f32_16x16x32_bf16 v[48:51], v[180:183], v[188:191], v[48:51]
	v_mfma_f32_16x16x32_bf16 v[36:39], v[172:175], v[196:199], v[36:39]
	v_mfma_f32_16x16x32_bf16 v[32:35], v[180:183], v[196:199], v[32:35]
	v_mfma_f32_16x16x32_bf16 v[20:23], v[172:175], v[208:211], v[20:23]
	v_mfma_f32_16x16x32_bf16 v[16:19], v[180:183], v[208:211], v[16:19]
	v_mfma_f32_16x16x32_bf16 v[4:7], v[172:175], v[216:219], v[4:7]
	v_mfma_f32_16x16x32_bf16 v[0:3], v[180:183], v[216:219], v[0:3]
	s_barrier
	s_mov_b32 m0, s38
	s_nop 0
	global_load_lds_dwordx4 v134, s[28:29]
	s_mov_b32 m0, s39
	s_nop 0
	global_load_lds_dwordx4 v130, s[28:29]
	s_add_i32 s56, 0, 0x18000
	s_add_i32 s57, 0, 0x1c000
	v_add_u32_e32 v164, s56, v149
	v_add_u32_e32 v180, s57, v149
	ds_read_b128 v[144:147], v164
	ds_read_b128 v[156:159], v164 offset:1024
	ds_read_b128 v[160:163], v164 offset:2048
	ds_read_b128 v[164:167], v164 offset:3072
	ds_read_b128 v[168:171], v180
	ds_read_b128 v[172:175], v180 offset:1024
	ds_read_b128 v[176:179], v180 offset:2048
	ds_read_b128 v[180:183], v180 offset:3072
	s_add_u32 s28, s28, 0x40000
	s_addc_u32 s29, s29, 0
	s_mov_b32 m0, s40
	ds_read_b128 v[184:187], v153 offset:32768
	ds_read_b128 v[188:191], v153 offset:33792
	ds_read_b128 v[192:195], v153 offset:34816
	ds_read_b128 v[196:199], v153 offset:35840
	ds_read_b128 v[200:203], v153 offset:36864
	ds_read_b128 v[208:211], v153 offset:37888
	ds_read_b128 v[212:215], v153 offset:38912
	ds_read_b128 v[216:219], v153 offset:39936
	global_load_lds_dwordx4 v134, s[28:29]
	s_mov_b32 m0, s41
	s_nop 0
	global_load_lds_dwordx4 v130, s[28:29]
	s_waitcnt vmcnt(8)
	s_waitcnt lgkmcnt(0)
	s_barrier
	s_waitcnt lgkmcnt(0)
	v_mfma_f32_16x16x32_bf16 v[124:127], v[144:147], v[184:187], v[124:127]
	v_mfma_f32_16x16x32_bf16 v[120:123], v[160:163], v[184:187], v[120:123]
	v_mfma_f32_16x16x32_bf16 v[108:111], v[144:147], v[192:195], v[108:111]
	v_mfma_f32_16x16x32_bf16 v[104:107], v[160:163], v[192:195], v[104:107]
	v_mfma_f32_16x16x32_bf16 v[92:95], v[144:147], v[200:203], v[92:95]
	v_mfma_f32_16x16x32_bf16 v[88:91], v[160:163], v[200:203], v[88:91]
	v_mfma_f32_16x16x32_bf16 v[76:79], v[144:147], v[212:215], v[76:79]
	v_mfma_f32_16x16x32_bf16 v[72:75], v[160:163], v[212:215], v[72:75]
	v_mfma_f32_16x16x32_bf16 v[124:127], v[156:159], v[188:191], v[124:127]
	v_mfma_f32_16x16x32_bf16 v[120:123], v[164:167], v[188:191], v[120:123]
	v_mfma_f32_16x16x32_bf16 v[108:111], v[156:159], v[196:199], v[108:111]
	v_mfma_f32_16x16x32_bf16 v[104:107], v[164:167], v[196:199], v[104:107]
	v_mfma_f32_16x16x32_bf16 v[92:95], v[156:159], v[208:211], v[92:95]
	v_mfma_f32_16x16x32_bf16 v[88:91], v[164:167], v[208:211], v[88:91]
	v_mfma_f32_16x16x32_bf16 v[76:79], v[156:159], v[216:219], v[76:79]
	v_mfma_f32_16x16x32_bf16 v[72:75], v[164:167], v[216:219], v[72:75]
	v_mfma_f32_16x16x32_bf16 v[116:119], v[168:171], v[184:187], v[116:119]
	v_mfma_f32_16x16x32_bf16 v[112:115], v[176:179], v[184:187], v[112:115]
	v_mfma_f32_16x16x32_bf16 v[100:103], v[168:171], v[192:195], v[100:103]
	v_mfma_f32_16x16x32_bf16 v[96:99], v[176:179], v[192:195], v[96:99]
	v_mfma_f32_16x16x32_bf16 v[84:87], v[168:171], v[200:203], v[84:87]
	v_mfma_f32_16x16x32_bf16 v[80:83], v[176:179], v[200:203], v[80:83]
	v_mfma_f32_16x16x32_bf16 v[68:71], v[168:171], v[212:215], v[68:71]
	v_mfma_f32_16x16x32_bf16 v[64:67], v[176:179], v[212:215], v[64:67]
	v_mfma_f32_16x16x32_bf16 v[116:119], v[172:175], v[188:191], v[116:119]
	v_mfma_f32_16x16x32_bf16 v[112:115], v[180:183], v[188:191], v[112:115]
	v_mfma_f32_16x16x32_bf16 v[100:103], v[172:175], v[196:199], v[100:103]
	v_mfma_f32_16x16x32_bf16 v[96:99], v[180:183], v[196:199], v[96:99]
	v_mfma_f32_16x16x32_bf16 v[84:87], v[172:175], v[208:211], v[84:87]
	v_mfma_f32_16x16x32_bf16 v[80:83], v[180:183], v[208:211], v[80:83]
	v_mfma_f32_16x16x32_bf16 v[68:71], v[172:175], v[216:219], v[68:71]
	v_mfma_f32_16x16x32_bf16 v[64:67], v[180:183], v[216:219], v[64:67]
	s_barrier
	s_add_i32 s28, s56, s35
	s_mov_b32 m0, s28
	ds_read_b128 v[184:187], v153 offset:49152
	ds_read_b128 v[188:191], v153 offset:50176
	ds_read_b128 v[192:195], v153 offset:51200
	ds_read_b128 v[196:199], v153 offset:52224
	ds_read_b128 v[200:203], v153 offset:53248
	ds_read_b128 v[208:211], v153 offset:54272
	ds_read_b128 v[212:215], v153 offset:55296
	ds_read_b128 v[216:219], v153 offset:56320
	global_load_lds_dwordx4 v220, s[26:27]
	s_add_i32 m0, s28, 0x2000
	s_add_u32 s26, s26, 0x40080
	s_addc_u32 s27, s27, 0
	s_add_i32 s28, s57, s35
	global_load_lds_dwordx4 v204, s[98:99]
	s_mov_b32 m0, s28
	s_nop 0
	global_load_lds_dwordx4 v132, s[26:27]
	s_add_i32 m0, s28, 0x2000
	s_nop 0
	global_load_lds_dwordx4 v128, s[26:27]
	s_cmp_lg_u32 s55, 12
	s_cbranch_scc1 .Lbal_last_21
	s_mov_b32 m0, s45
	s_nop 0
	global_load_lds_dwordx4 v221, s[100:101]
	s_mov_b32 m0, s46
	s_nop 0
	global_load_lds_dwordx4 v205, s[100:101]
.Lbal_last_21:
	s_waitcnt vmcnt(6)
	s_waitcnt lgkmcnt(0)
	s_barrier
	s_waitcnt lgkmcnt(0)
	v_mfma_f32_16x16x32_bf16 v[60:63], v[144:147], v[184:187], v[60:63]
	v_mfma_f32_16x16x32_bf16 v[56:59], v[160:163], v[184:187], v[56:59]
	v_mfma_f32_16x16x32_bf16 v[44:47], v[144:147], v[192:195], v[44:47]
	v_mfma_f32_16x16x32_bf16 v[40:43], v[160:163], v[192:195], v[40:43]
	v_mfma_f32_16x16x32_bf16 v[28:31], v[144:147], v[200:203], v[28:31]
	v_mfma_f32_16x16x32_bf16 v[24:27], v[160:163], v[200:203], v[24:27]
	v_mfma_f32_16x16x32_bf16 v[12:15], v[144:147], v[212:215], v[12:15]
	v_mfma_f32_16x16x32_bf16 v[8:11], v[160:163], v[212:215], v[8:11]
	v_mfma_f32_16x16x32_bf16 v[60:63], v[156:159], v[188:191], v[60:63]
	v_mfma_f32_16x16x32_bf16 v[56:59], v[164:167], v[188:191], v[56:59]
	v_mfma_f32_16x16x32_bf16 v[44:47], v[156:159], v[196:199], v[44:47]
	v_mfma_f32_16x16x32_bf16 v[40:43], v[164:167], v[196:199], v[40:43]
	v_mfma_f32_16x16x32_bf16 v[28:31], v[156:159], v[208:211], v[28:31]
	v_mfma_f32_16x16x32_bf16 v[24:27], v[164:167], v[208:211], v[24:27]
	v_mfma_f32_16x16x32_bf16 v[12:15], v[156:159], v[216:219], v[12:15]
	v_mfma_f32_16x16x32_bf16 v[8:11], v[164:167], v[216:219], v[8:11]
	v_mfma_f32_16x16x32_bf16 v[52:55], v[168:171], v[184:187], v[52:55]
	v_mfma_f32_16x16x32_bf16 v[48:51], v[176:179], v[184:187], v[48:51]
	v_mfma_f32_16x16x32_bf16 v[36:39], v[168:171], v[192:195], v[36:39]
	v_mfma_f32_16x16x32_bf16 v[32:35], v[176:179], v[192:195], v[32:35]
	v_mfma_f32_16x16x32_bf16 v[20:23], v[168:171], v[200:203], v[20:23]
	v_mfma_f32_16x16x32_bf16 v[16:19], v[176:179], v[200:203], v[16:19]
	v_mfma_f32_16x16x32_bf16 v[4:7], v[168:171], v[212:215], v[4:7]
	v_mfma_f32_16x16x32_bf16 v[0:3], v[176:179], v[212:215], v[0:3]
	v_mfma_f32_16x16x32_bf16 v[52:55], v[172:175], v[188:191], v[52:55]
	v_mfma_f32_16x16x32_bf16 v[48:51], v[180:183], v[188:191], v[48:51]
	v_mfma_f32_16x16x32_bf16 v[36:39], v[172:175], v[196:199], v[36:39]
	v_mfma_f32_16x16x32_bf16 v[32:35], v[180:183], v[196:199], v[32:35]
	v_mfma_f32_16x16x32_bf16 v[20:23], v[172:175], v[208:211], v[20:23]
	v_mfma_f32_16x16x32_bf16 v[16:19], v[180:183], v[208:211], v[16:19]
	v_mfma_f32_16x16x32_bf16 v[4:7], v[172:175], v[216:219], v[4:7]
	v_mfma_f32_16x16x32_bf16 v[0:3], v[180:183], v[216:219], v[0:3]
	s_barrier
	s_add_i32 s55, s55, 2
	s_add_u32 s53, s53, 0x100
	s_addc_u32 s54, s54, 0
	s_add_u32 s24, s24, 0x100
	s_addc_u32 s25, s25, 0
	s_cmp_gt_u32 s55, 13
	s_cbranch_scc0 .LBB0_163
	s_setprio 0
	s_and_b64 vcc, exec, s[14:15]
	s_cbranch_vccz .LBB0_166
	s_barrier

.LBB0_606:
	s_cmp_eq_i32 s58, -2
	s_cbranch_scc1 .Lbal_first_20
	s_mov_b32 m0, s49
	s_nop 0
	global_load_lds_dwordx4 v212, s[36:37]
	s_mov_b32 m0, s50
	s_nop 0
	global_load_lds_dwordx4 v213, s[36:37]
.Lbal_first_20:
	ds_read_b128 v[140:143], v147
	ds_read_b128 v[150:153], v147 offset:1024
	ds_read_b128 v[154:157], v147 offset:2048
	ds_read_b128 v[158:161], v147 offset:3072
	ds_read_b128 v[162:165], v148
	ds_read_b128 v[166:169], v148 offset:1024
	ds_read_b128 v[170:173], v148 offset:2048
	ds_read_b128 v[174:177], v148 offset:3072
	s_add_u32 s30, s28, 0x100
	s_addc_u32 s31, s29, 0
	s_cmp_eq_u32 s58, 12
	s_cselect_b32 s37, s21, s31
	s_cselect_b32 s36, s27, s30
	s_cselect_b32 s35, s19, s57
	s_cselect_b32 s34, s55, s56
	s_add_i32 m0, s44, 0xc000
	ds_read_b128 v[178:181], v149
	ds_read_b128 v[182:185], v149 offset:1024
	ds_read_b128 v[186:189], v149 offset:2048
	ds_read_b128 v[190:193], v149 offset:3072
	ds_read_b128 v[194:197], v149 offset:4096
	ds_read_b128 v[198:201], v149 offset:5120
	ds_read_b128 v[202:205], v149 offset:6144
	ds_read_b128 v[208:211], v149 offset:7168
	global_load_lds_dwordx4 v134, s[28:29]
	s_add_i32 m0, s44, 0xe000
	s_nop 0
	global_load_lds_dwordx4 v132, s[28:29]
	s_waitcnt vmcnt(8)
	s_waitcnt lgkmcnt(0)
	s_barrier
	s_waitcnt lgkmcnt(0)
	v_mfma_f32_16x16x32_bf16 v[124:127], v[140:143], v[178:181], v[124:127]
	v_mfma_f32_16x16x32_bf16 v[120:123], v[154:157], v[178:181], v[120:123]
	v_mfma_f32_16x16x32_bf16 v[108:111], v[140:143], v[186:189], v[108:111]
	v_mfma_f32_16x16x32_bf16 v[104:107], v[154:157], v[186:189], v[104:107]
	v_mfma_f32_16x16x32_bf16 v[92:95], v[140:143], v[194:197], v[92:95]
	v_mfma_f32_16x16x32_bf16 v[88:91], v[154:157], v[194:197], v[88:91]
	v_mfma_f32_16x16x32_bf16 v[76:79], v[140:143], v[202:205], v[76:79]
	v_mfma_f32_16x16x32_bf16 v[72:75], v[154:157], v[202:205], v[72:75]
	v_mfma_f32_16x16x32_bf16 v[124:127], v[150:153], v[182:185], v[124:127]
	v_mfma_f32_16x16x32_bf16 v[120:123], v[158:161], v[182:185], v[120:123]
	v_mfma_f32_16x16x32_bf16 v[108:111], v[150:153], v[190:193], v[108:111]
	v_mfma_f32_16x16x32_bf16 v[104:107], v[158:161], v[190:193], v[104:107]
	v_mfma_f32_16x16x32_bf16 v[92:95], v[150:153], v[198:201], v[92:95]
	v_mfma_f32_16x16x32_bf16 v[88:91], v[158:161], v[198:201], v[88:91]
	v_mfma_f32_16x16x32_bf16 v[76:79], v[150:153], v[208:211], v[76:79]
	v_mfma_f32_16x16x32_bf16 v[72:75], v[158:161], v[208:211], v[72:75]
	v_mfma_f32_16x16x32_bf16 v[116:119], v[162:165], v[178:181], v[116:119]
	v_mfma_f32_16x16x32_bf16 v[112:115], v[170:173], v[178:181], v[112:115]
	v_mfma_f32_16x16x32_bf16 v[100:103], v[162:165], v[186:189], v[100:103]
	v_mfma_f32_16x16x32_bf16 v[96:99], v[170:173], v[186:189], v[96:99]
	v_mfma_f32_16x16x32_bf16 v[84:87], v[162:165], v[194:197], v[84:87]
	v_mfma_f32_16x16x32_bf16 v[80:83], v[170:173], v[194:197], v[80:83]
	v_mfma_f32_16x16x32_bf16 v[68:71], v[162:165], v[202:205], v[68:71]
	v_mfma_f32_16x16x32_bf16 v[64:67], v[170:173], v[202:205], v[64:67]
	v_mfma_f32_16x16x32_bf16 v[116:119], v[166:169], v[182:185], v[116:119]
	v_mfma_f32_16x16x32_bf16 v[112:115], v[174:177], v[182:185], v[112:115]
	v_mfma_f32_16x16x32_bf16 v[100:103], v[166:169], v[190:193], v[100:103]
	v_mfma_f32_16x16x32_bf16 v[96:99], v[174:177], v[190:193], v[96:99]
	v_mfma_f32_16x16x32_bf16 v[84:87], v[166:169], v[198:201], v[84:87]
	v_mfma_f32_16x16x32_bf16 v[80:83], v[174:177], v[198:201], v[80:83]
	v_mfma_f32_16x16x32_bf16 v[68:71], v[166:169], v[208:211], v[68:71]
	v_mfma_f32_16x16x32_bf16 v[64:67], v[174:177], v[208:211], v[64:67]
	s_barrier
	s_add_i32 s28, s52, s43
	s_mov_b32 m0, s28
	ds_read_b128 v[178:181], v149 offset:16384
	ds_read_b128 v[182:185], v149 offset:17408
	ds_read_b128 v[186:189], v149 offset:18432
	ds_read_b128 v[190:193], v149 offset:19456
	ds_read_b128 v[194:197], v149 offset:20480
	ds_read_b128 v[198:201], v149 offset:21504
	ds_read_b128 v[202:205], v149 offset:22528
	ds_read_b128 v[208:211], v149 offset:23552
	global_load_lds_dwordx4 v128, s[34:35]
	s_add_i32 m0, s28, 0x2000
	s_add_u32 s28, s34, 0x40000
	s_mov_b64 s[98:99], s[34:35]
	s_addc_u32 s29, s35, 0
	s_add_i32 s59, s53, s43
	global_load_lds_dwordx4 v130, s[34:35]
	s_mov_b32 m0, s59
	s_nop 0
	global_load_lds_dwordx4 v128, s[28:29]
	s_add_i32 m0, s59, 0x2000
	s_nop 0
	global_load_lds_dwordx4 v130, s[28:29]
	s_waitcnt vmcnt(6)
	s_waitcnt lgkmcnt(0)
	s_barrier
	s_waitcnt lgkmcnt(0)
	v_mfma_f32_16x16x32_bf16 v[60:63], v[140:143], v[178:181], v[60:63]
	v_mfma_f32_16x16x32_bf16 v[56:59], v[154:157], v[178:181], v[56:59]
	v_mfma_f32_16x16x32_bf16 v[44:47], v[140:143], v[186:189], v[44:47]
	v_mfma_f32_16x16x32_bf16 v[40:43], v[154:157], v[186:189], v[40:43]
	v_mfma_f32_16x16x32_bf16 v[28:31], v[140:143], v[194:197], v[28:31]
	v_mfma_f32_16x16x32_bf16 v[24:27], v[154:157], v[194:197], v[24:27]
	v_mfma_f32_16x16x32_bf16 v[12:15], v[140:143], v[202:205], v[12:15]
	v_mfma_f32_16x16x32_bf16 v[8:11], v[154:157], v[202:205], v[8:11]
	v_mfma_f32_16x16x32_bf16 v[60:63], v[150:153], v[182:185], v[60:63]
	v_mfma_f32_16x16x32_bf16 v[56:59], v[158:161], v[182:185], v[56:59]
	v_mfma_f32_16x16x32_bf16 v[44:47], v[150:153], v[190:193], v[44:47]
	v_mfma_f32_16x16x32_bf16 v[40:43], v[158:161], v[190:193], v[40:43]
	v_mfma_f32_16x16x32_bf16 v[28:31], v[150:153], v[198:201], v[28:31]
	v_mfma_f32_16x16x32_bf16 v[24:27], v[158:161], v[198:201], v[24:27]
	v_mfma_f32_16x16x32_bf16 v[12:15], v[150:153], v[208:211], v[12:15]
	v_mfma_f32_16x16x32_bf16 v[8:11], v[158:161], v[208:211], v[8:11]
	v_mfma_f32_16x16x32_bf16 v[52:55], v[162:165], v[178:181], v[52:55]
	v_mfma_f32_16x16x32_bf16 v[48:51], v[170:173], v[178:181], v[48:51]
	v_mfma_f32_16x16x32_bf16 v[36:39], v[162:165], v[186:189], v[36:39]
	v_mfma_f32_16x16x32_bf16 v[32:35], v[170:173], v[186:189], v[32:35]
	v_mfma_f32_16x16x32_bf16 v[20:23], v[162:165], v[194:197], v[20:23]
	v_mfma_f32_16x16x32_bf16 v[16:19], v[170:173], v[194:197], v[16:19]
	v_mfma_f32_16x16x32_bf16 v[4:7], v[162:165], v[202:205], v[4:7]
	v_mfma_f32_16x16x32_bf16 v[0:3], v[170:173], v[202:205], v[0:3]
	v_mfma_f32_16x16x32_bf16 v[52:55], v[166:169], v[182:185], v[52:55]
	v_mfma_f32_16x16x32_bf16 v[48:51], v[174:177], v[182:185], v[48:51]
	v_mfma_f32_16x16x32_bf16 v[36:39], v[166:169], v[190:193], v[36:39]
	v_mfma_f32_16x16x32_bf16 v[32:35], v[174:177], v[190:193], v[32:35]
	v_mfma_f32_16x16x32_bf16 v[20:23], v[166:169], v[198:201], v[20:23]
	v_mfma_f32_16x16x32_bf16 v[16:19], v[174:177], v[198:201], v[16:19]
	v_mfma_f32_16x16x32_bf16 v[4:7], v[166:169], v[208:211], v[4:7]
	v_mfma_f32_16x16x32_bf16 v[0:3], v[174:177], v[208:211], v[0:3]
	s_barrier
	s_mov_b32 m0, s44
	s_nop 0
	global_load_lds_dwordx4 v128, s[36:37]
	s_mov_b32 m0, s45
	s_nop 0
	global_load_lds_dwordx4 v130, s[36:37]
	s_add_i32 s59, 0, 0x18000
	s_add_i32 s60, 0, 0x1c000
	v_add_u32_e32 v158, s59, v145
	v_add_u32_e32 v174, s60, v145
	ds_read_b128 v[140:143], v158
	ds_read_b128 v[150:153], v158 offset:1024
	ds_read_b128 v[154:157], v158 offset:2048
	ds_read_b128 v[158:161], v158 offset:3072
	ds_read_b128 v[162:165], v174
	ds_read_b128 v[166:169], v174 offset:1024
	ds_read_b128 v[170:173], v174 offset:2048
	ds_read_b128 v[174:177], v174 offset:3072
	s_add_u32 s28, s36, 0x40000
	s_addc_u32 s29, s37, 0
	s_mov_b32 m0, s46
	ds_read_b128 v[178:181], v149 offset:32768
	ds_read_b128 v[182:185], v149 offset:33792
	ds_read_b128 v[186:189], v149 offset:34816
	ds_read_b128 v[190:193], v149 offset:35840
	ds_read_b128 v[194:197], v149 offset:36864
	ds_read_b128 v[198:201], v149 offset:37888
	ds_read_b128 v[202:205], v149 offset:38912
	ds_read_b128 v[208:211], v149 offset:39936
	global_load_lds_dwordx4 v128, s[28:29]
	s_mov_b32 m0, s47
	s_nop 0
	global_load_lds_dwordx4 v130, s[28:29]
	s_waitcnt vmcnt(8)
	s_waitcnt lgkmcnt(0)
	s_barrier
	s_waitcnt lgkmcnt(0)
	v_mfma_f32_16x16x32_bf16 v[124:127], v[140:143], v[178:181], v[124:127]
	v_mfma_f32_16x16x32_bf16 v[120:123], v[154:157], v[178:181], v[120:123]
	v_mfma_f32_16x16x32_bf16 v[108:111], v[140:143], v[186:189], v[108:111]
	v_mfma_f32_16x16x32_bf16 v[104:107], v[154:157], v[186:189], v[104:107]
	v_mfma_f32_16x16x32_bf16 v[92:95], v[140:143], v[194:197], v[92:95]
	v_mfma_f32_16x16x32_bf16 v[88:91], v[154:157], v[194:197], v[88:91]
	v_mfma_f32_16x16x32_bf16 v[76:79], v[140:143], v[202:205], v[76:79]
	v_mfma_f32_16x16x32_bf16 v[72:75], v[154:157], v[202:205], v[72:75]
	v_mfma_f32_16x16x32_bf16 v[124:127], v[150:153], v[182:185], v[124:127]
	v_mfma_f32_16x16x32_bf16 v[120:123], v[158:161], v[182:185], v[120:123]
	v_mfma_f32_16x16x32_bf16 v[108:111], v[150:153], v[190:193], v[108:111]
	v_mfma_f32_16x16x32_bf16 v[104:107], v[158:161], v[190:193], v[104:107]
	v_mfma_f32_16x16x32_bf16 v[92:95], v[150:153], v[198:201], v[92:95]
	v_mfma_f32_16x16x32_bf16 v[88:91], v[158:161], v[198:201], v[88:91]
	v_mfma_f32_16x16x32_bf16 v[76:79], v[150:153], v[208:211], v[76:79]
	v_mfma_f32_16x16x32_bf16 v[72:75], v[158:161], v[208:211], v[72:75]
	v_mfma_f32_16x16x32_bf16 v[116:119], v[162:165], v[178:181], v[116:119]
	v_mfma_f32_16x16x32_bf16 v[112:115], v[170:173], v[178:181], v[112:115]
	v_mfma_f32_16x16x32_bf16 v[100:103], v[162:165], v[186:189], v[100:103]
	v_mfma_f32_16x16x32_bf16 v[96:99], v[170:173], v[186:189], v[96:99]
	v_mfma_f32_16x16x32_bf16 v[84:87], v[162:165], v[194:197], v[84:87]
	v_mfma_f32_16x16x32_bf16 v[80:83], v[170:173], v[194:197], v[80:83]
	v_mfma_f32_16x16x32_bf16 v[68:71], v[162:165], v[202:205], v[68:71]
	v_mfma_f32_16x16x32_bf16 v[64:67], v[170:173], v[202:205], v[64:67]
	v_mfma_f32_16x16x32_bf16 v[116:119], v[166:169], v[182:185], v[116:119]
	v_mfma_f32_16x16x32_bf16 v[112:115], v[174:177], v[182:185], v[112:115]
	v_mfma_f32_16x16x32_bf16 v[100:103], v[166:169], v[190:193], v[100:103]
	v_mfma_f32_16x16x32_bf16 v[96:99], v[174:177], v[190:193], v[96:99]
	v_mfma_f32_16x16x32_bf16 v[84:87], v[166:169], v[198:201], v[84:87]
	v_mfma_f32_16x16x32_bf16 v[80:83], v[174:177], v[198:201], v[80:83]
	v_mfma_f32_16x16x32_bf16 v[68:71], v[166:169], v[208:211], v[68:71]
	v_mfma_f32_16x16x32_bf16 v[64:67], v[174:177], v[208:211], v[64:67]
	s_barrier
	s_add_i32 s28, s59, s43
	s_mov_b32 m0, s28
	ds_read_b128 v[178:181], v149 offset:49152
	ds_read_b128 v[182:185], v149 offset:50176
	ds_read_b128 v[186:189], v149 offset:51200
	ds_read_b128 v[190:193], v149 offset:52224
	ds_read_b128 v[194:197], v149 offset:53248
	ds_read_b128 v[198:201], v149 offset:54272
	ds_read_b128 v[202:205], v149 offset:55296
	ds_read_b128 v[208:211], v149 offset:56320
	global_load_lds_dwordx4 v212, s[34:35]
	s_add_i32 m0, s28, 0x2000
	s_add_u32 s28, s34, 0x40080
	s_addc_u32 s29, s35, 0
	s_add_i32 s34, s60, s43
	global_load_lds_dwordx4 v213, s[98:99]
	s_mov_b32 m0, s34
	s_nop 0
	global_load_lds_dwordx4 v128, s[28:29]
	s_add_i32 m0, s34, 0x2000
	s_nop 0
	global_load_lds_dwordx4 v130, s[28:29]
	s_cmp_lg_u32 s58, 12
	s_cbranch_scc1 .Lbal_last_20
	s_mov_b32 m0, s49
	s_nop 0
	global_load_lds_dwordx4 v212, s[36:37]
	s_mov_b32 m0, s50
	s_nop 0
	global_load_lds_dwordx4 v213, s[36:37]
.Lbal_last_20:
	s_waitcnt vmcnt(6)
	s_waitcnt lgkmcnt(0)
	s_barrier
	s_waitcnt lgkmcnt(0)
	v_mfma_f32_16x16x32_bf16 v[60:63], v[140:143], v[178:181], v[60:63]
	v_mfma_f32_16x16x32_bf16 v[56:59], v[154:157], v[178:181], v[56:59]
	v_mfma_f32_16x16x32_bf16 v[44:47], v[140:143], v[186:189], v[44:47]
	v_mfma_f32_16x16x32_bf16 v[40:43], v[154:157], v[186:189], v[40:43]
	v_mfma_f32_16x16x32_bf16 v[28:31], v[140:143], v[194:197], v[28:31]
	v_mfma_f32_16x16x32_bf16 v[24:27], v[154:157], v[194:197], v[24:27]
	v_mfma_f32_16x16x32_bf16 v[12:15], v[140:143], v[202:205], v[12:15]
	v_mfma_f32_16x16x32_bf16 v[8:11], v[154:157], v[202:205], v[8:11]
	v_mfma_f32_16x16x32_bf16 v[60:63], v[150:153], v[182:185], v[60:63]
	v_mfma_f32_16x16x32_bf16 v[56:59], v[158:161], v[182:185], v[56:59]
	v_mfma_f32_16x16x32_bf16 v[44:47], v[150:153], v[190:193], v[44:47]
	v_mfma_f32_16x16x32_bf16 v[40:43], v[158:161], v[190:193], v[40:43]
	v_mfma_f32_16x16x32_bf16 v[28:31], v[150:153], v[198:201], v[28:31]
	v_mfma_f32_16x16x32_bf16 v[24:27], v[158:161], v[198:201], v[24:27]
	v_mfma_f32_16x16x32_bf16 v[12:15], v[150:153], v[208:211], v[12:15]
	v_mfma_f32_16x16x32_bf16 v[8:11], v[158:161], v[208:211], v[8:11]
	v_mfma_f32_16x16x32_bf16 v[52:55], v[162:165], v[178:181], v[52:55]
	v_mfma_f32_16x16x32_bf16 v[48:51], v[170:173], v[178:181], v[48:51]
	v_mfma_f32_16x16x32_bf16 v[36:39], v[162:165], v[186:189], v[36:39]
	v_mfma_f32_16x16x32_bf16 v[32:35], v[170:173], v[186:189], v[32:35]
	v_mfma_f32_16x16x32_bf16 v[20:23], v[162:165], v[194:197], v[20:23]
	v_mfma_f32_16x16x32_bf16 v[16:19], v[170:173], v[194:197], v[16:19]
	v_mfma_f32_16x16x32_bf16 v[4:7], v[162:165], v[202:205], v[4:7]
	v_mfma_f32_16x16x32_bf16 v[0:3], v[170:173], v[202:205], v[0:3]
	v_mfma_f32_16x16x32_bf16 v[52:55], v[166:169], v[182:185], v[52:55]
	v_mfma_f32_16x16x32_bf16 v[48:51], v[174:177], v[182:185], v[48:51]
	v_mfma_f32_16x16x32_bf16 v[36:39], v[166:169], v[190:193], v[36:39]
	v_mfma_f32_16x16x32_bf16 v[32:35], v[174:177], v[190:193], v[32:35]
	v_mfma_f32_16x16x32_bf16 v[20:23], v[166:169], v[198:201], v[20:23]
	v_mfma_f32_16x16x32_bf16 v[16:19], v[174:177], v[198:201], v[16:19]
	v_mfma_f32_16x16x32_bf16 v[4:7], v[166:169], v[208:211], v[4:7]
	v_mfma_f32_16x16x32_bf16 v[0:3], v[174:177], v[208:211], v[0:3]
	s_barrier
	s_add_i32 s58, s58, 2
	s_add_u32 s56, s56, 0x100
	s_addc_u32 s57, s57, 0
	s_cmp_gt_u32 s58, 13
	s_mov_b64 s[28:29], s[30:31]
	s_cbranch_scc0 .LBB0_606
	s_setprio 0
	s_and_b64 vcc, exec, s[16:17]
	s_cbranch_vccz .LBB0_609
	s_barrier

.LBB0_699:
	s_cmp_eq_i32 s53, -2
	s_cbranch_scc1 .Lbal_first_19
	s_mov_b32 m0, s44
	s_nop 0
	global_load_lds_dwordx4 v204, s[100:101]
	s_mov_b32 m0, s45
	s_nop 0
	global_load_lds_dwordx4 v220, s[100:101]
.Lbal_first_19:
	ds_read_b128 v[144:147], v151
	ds_read_b128 v[156:159], v151 offset:1024
	ds_read_b128 v[160:163], v151 offset:2048
	ds_read_b128 v[164:167], v151 offset:3072
	ds_read_b128 v[168:171], v152
	ds_read_b128 v[172:175], v152 offset:1024
	ds_read_b128 v[176:179], v152 offset:2048
	ds_read_b128 v[180:183], v152 offset:3072
	s_add_u32 s28, s26, 0xfffc0080
	s_addc_u32 s29, s27, -1
	s_cmp_eq_u32 s53, 12
	s_cselect_b32 s31, s21, s29
	s_cselect_b32 s30, s49, s28
	s_cselect_b32 s29, s19, s52
	s_cselect_b32 s28, s50, s51
	s_add_i32 m0, s39, 0xc000
	ds_read_b128 v[184:187], v153
	ds_read_b128 v[188:191], v153 offset:1024
	ds_read_b128 v[192:195], v153 offset:2048
	ds_read_b128 v[196:199], v153 offset:3072
	ds_read_b128 v[200:203], v153 offset:4096
	ds_read_b128 v[208:211], v153 offset:5120
	ds_read_b128 v[212:215], v153 offset:6144
	ds_read_b128 v[216:219], v153 offset:7168
	global_load_lds_dwordx4 v138, s[26:27]
	s_add_i32 m0, s39, 0xe000
	s_nop 0
	global_load_lds_dwordx4 v136, s[26:27]
	s_waitcnt vmcnt(8)
	s_waitcnt lgkmcnt(0)
	s_barrier
	s_waitcnt lgkmcnt(0)
	v_mfma_f32_16x16x32_bf16 v[124:127], v[144:147], v[184:187], v[124:127]
	v_mfma_f32_16x16x32_bf16 v[120:123], v[160:163], v[184:187], v[120:123]
	v_mfma_f32_16x16x32_bf16 v[108:111], v[144:147], v[192:195], v[108:111]
	v_mfma_f32_16x16x32_bf16 v[104:107], v[160:163], v[192:195], v[104:107]
	v_mfma_f32_16x16x32_bf16 v[92:95], v[144:147], v[200:203], v[92:95]
	v_mfma_f32_16x16x32_bf16 v[88:91], v[160:163], v[200:203], v[88:91]
	v_mfma_f32_16x16x32_bf16 v[76:79], v[144:147], v[212:215], v[76:79]
	v_mfma_f32_16x16x32_bf16 v[72:75], v[160:163], v[212:215], v[72:75]
	v_mfma_f32_16x16x32_bf16 v[124:127], v[156:159], v[188:191], v[124:127]
	v_mfma_f32_16x16x32_bf16 v[120:123], v[164:167], v[188:191], v[120:123]
	v_mfma_f32_16x16x32_bf16 v[108:111], v[156:159], v[196:199], v[108:111]
	v_mfma_f32_16x16x32_bf16 v[104:107], v[164:167], v[196:199], v[104:107]
	v_mfma_f32_16x16x32_bf16 v[92:95], v[156:159], v[208:211], v[92:95]
	v_mfma_f32_16x16x32_bf16 v[88:91], v[164:167], v[208:211], v[88:91]
	v_mfma_f32_16x16x32_bf16 v[76:79], v[156:159], v[216:219], v[76:79]
	v_mfma_f32_16x16x32_bf16 v[72:75], v[164:167], v[216:219], v[72:75]
	v_mfma_f32_16x16x32_bf16 v[116:119], v[168:171], v[184:187], v[116:119]
	v_mfma_f32_16x16x32_bf16 v[112:115], v[176:179], v[184:187], v[112:115]
	v_mfma_f32_16x16x32_bf16 v[100:103], v[168:171], v[192:195], v[100:103]
	v_mfma_f32_16x16x32_bf16 v[96:99], v[176:179], v[192:195], v[96:99]
	v_mfma_f32_16x16x32_bf16 v[84:87], v[168:171], v[200:203], v[84:87]
	v_mfma_f32_16x16x32_bf16 v[80:83], v[176:179], v[200:203], v[80:83]
	v_mfma_f32_16x16x32_bf16 v[68:71], v[168:171], v[212:215], v[68:71]
	v_mfma_f32_16x16x32_bf16 v[64:67], v[176:179], v[212:215], v[64:67]
	v_mfma_f32_16x16x32_bf16 v[116:119], v[172:175], v[188:191], v[116:119]
	v_mfma_f32_16x16x32_bf16 v[112:115], v[180:183], v[188:191], v[112:115]
	v_mfma_f32_16x16x32_bf16 v[100:103], v[172:175], v[196:199], v[100:103]
	v_mfma_f32_16x16x32_bf16 v[96:99], v[180:183], v[196:199], v[96:99]
	v_mfma_f32_16x16x32_bf16 v[84:87], v[172:175], v[208:211], v[84:87]
	v_mfma_f32_16x16x32_bf16 v[80:83], v[180:183], v[208:211], v[80:83]
	v_mfma_f32_16x16x32_bf16 v[68:71], v[172:175], v[216:219], v[68:71]
	v_mfma_f32_16x16x32_bf16 v[64:67], v[180:183], v[216:219], v[64:67]
	s_barrier
	s_add_i32 s54, s46, s38
	s_mov_b32 m0, s54
	ds_read_b128 v[184:187], v153 offset:16384
	ds_read_b128 v[188:191], v153 offset:17408
	ds_read_b128 v[192:195], v153 offset:18432
	ds_read_b128 v[196:199], v153 offset:19456
	ds_read_b128 v[200:203], v153 offset:20480
	ds_read_b128 v[208:211], v153 offset:21504
	ds_read_b128 v[212:215], v153 offset:22528
	ds_read_b128 v[216:219], v153 offset:23552
	global_load_lds_dwordx4 v130, s[28:29]
	s_add_i32 m0, s54, 0x2000
	s_add_u32 s54, s28, 0x40000
	s_mov_b64 s[98:99], s[28:29]
	s_addc_u32 s55, s29, 0
	s_add_i32 s56, s47, s38
	global_load_lds_dwordx4 v134, s[28:29]
	s_mov_b32 m0, s56
	s_mov_b64 s[100:101], s[30:31]
	global_load_lds_dwordx4 v130, s[54:55]
	s_add_i32 m0, s56, 0x2000
	s_nop 0
	global_load_lds_dwordx4 v134, s[54:55]
	s_waitcnt vmcnt(6)
	s_waitcnt lgkmcnt(0)
	s_barrier
	s_waitcnt lgkmcnt(0)
	v_mfma_f32_16x16x32_bf16 v[60:63], v[144:147], v[184:187], v[60:63]
	v_mfma_f32_16x16x32_bf16 v[56:59], v[160:163], v[184:187], v[56:59]
	v_mfma_f32_16x16x32_bf16 v[44:47], v[144:147], v[192:195], v[44:47]
	v_mfma_f32_16x16x32_bf16 v[40:43], v[160:163], v[192:195], v[40:43]
	v_mfma_f32_16x16x32_bf16 v[28:31], v[144:147], v[200:203], v[28:31]
	v_mfma_f32_16x16x32_bf16 v[24:27], v[160:163], v[200:203], v[24:27]
	v_mfma_f32_16x16x32_bf16 v[12:15], v[144:147], v[212:215], v[12:15]
	v_mfma_f32_16x16x32_bf16 v[8:11], v[160:163], v[212:215], v[8:11]
	v_mfma_f32_16x16x32_bf16 v[60:63], v[156:159], v[188:191], v[60:63]
	v_mfma_f32_16x16x32_bf16 v[56:59], v[164:167], v[188:191], v[56:59]
	v_mfma_f32_16x16x32_bf16 v[44:47], v[156:159], v[196:199], v[44:47]
	v_mfma_f32_16x16x32_bf16 v[40:43], v[164:167], v[196:199], v[40:43]
	v_mfma_f32_16x16x32_bf16 v[28:31], v[156:159], v[208:211], v[28:31]
	v_mfma_f32_16x16x32_bf16 v[24:27], v[164:167], v[208:211], v[24:27]
	v_mfma_f32_16x16x32_bf16 v[12:15], v[156:159], v[216:219], v[12:15]
	v_mfma_f32_16x16x32_bf16 v[8:11], v[164:167], v[216:219], v[8:11]
	v_mfma_f32_16x16x32_bf16 v[52:55], v[168:171], v[184:187], v[52:55]
	v_mfma_f32_16x16x32_bf16 v[48:51], v[176:179], v[184:187], v[48:51]
	v_mfma_f32_16x16x32_bf16 v[36:39], v[168:171], v[192:195], v[36:39]
	v_mfma_f32_16x16x32_bf16 v[32:35], v[176:179], v[192:195], v[32:35]
	v_mfma_f32_16x16x32_bf16 v[20:23], v[168:171], v[200:203], v[20:23]
	v_mfma_f32_16x16x32_bf16 v[16:19], v[176:179], v[200:203], v[16:19]
	v_mfma_f32_16x16x32_bf16 v[4:7], v[168:171], v[212:215], v[4:7]
	v_mfma_f32_16x16x32_bf16 v[0:3], v[176:179], v[212:215], v[0:3]
	v_mfma_f32_16x16x32_bf16 v[52:55], v[172:175], v[188:191], v[52:55]
	v_mfma_f32_16x16x32_bf16 v[48:51], v[180:183], v[188:191], v[48:51]
	v_mfma_f32_16x16x32_bf16 v[36:39], v[172:175], v[196:199], v[36:39]
	v_mfma_f32_16x16x32_bf16 v[32:35], v[180:183], v[196:199], v[32:35]
	v_mfma_f32_16x16x32_bf16 v[20:23], v[172:175], v[208:211], v[20:23]
	v_mfma_f32_16x16x32_bf16 v[16:19], v[180:183], v[208:211], v[16:19]
	v_mfma_f32_16x16x32_bf16 v[4:7], v[172:175], v[216:219], v[4:7]
	v_mfma_f32_16x16x32_bf16 v[0:3], v[180:183], v[216:219], v[0:3]
	s_barrier
	s_mov_b32 m0, s39
	s_nop 0
	global_load_lds_dwordx4 v128, s[30:31]
	s_mov_b32 m0, s40
	s_nop 0
	global_load_lds_dwordx4 v132, s[30:31]
	s_add_i32 s54, 0, 0x18000
	v_add_u32_e32 v155, s54, v149
	s_add_i32 s55, 0, 0x1c000
	ds_read_b128 v[144:147], v155
	ds_read_b128 v[156:159], v155 offset:1024
	ds_read_b128 v[160:163], v155 offset:2048
	ds_read_b128 v[164:167], v155 offset:3072
	v_add_u32_e32 v155, s55, v149
	ds_read_b128 v[168:171], v155
	ds_read_b128 v[172:175], v155 offset:1024
	ds_read_b128 v[176:179], v155 offset:2048
	ds_read_b128 v[180:183], v155 offset:3072
	s_add_u32 s30, s30, 0x40000
	s_addc_u32 s31, s31, 0
	s_mov_b32 m0, s41
	ds_read_b128 v[184:187], v153 offset:32768
	ds_read_b128 v[188:191], v153 offset:33792
	ds_read_b128 v[192:195], v153 offset:34816
	ds_read_b128 v[196:199], v153 offset:35840
	ds_read_b128 v[200:203], v153 offset:36864
	ds_read_b128 v[208:211], v153 offset:37888
	ds_read_b128 v[212:215], v153 offset:38912
	ds_read_b128 v[216:219], v153 offset:39936
	global_load_lds_dwordx4 v128, s[30:31]
	s_mov_b32 m0, s42
	s_nop 0
	global_load_lds_dwordx4 v132, s[30:31]
	s_waitcnt vmcnt(8)
	s_waitcnt lgkmcnt(0)
	s_barrier
	s_waitcnt lgkmcnt(0)
	v_mfma_f32_16x16x32_bf16 v[124:127], v[144:147], v[184:187], v[124:127]
	v_mfma_f32_16x16x32_bf16 v[120:123], v[160:163], v[184:187], v[120:123]
	v_mfma_f32_16x16x32_bf16 v[108:111], v[144:147], v[192:195], v[108:111]
	v_mfma_f32_16x16x32_bf16 v[104:107], v[160:163], v[192:195], v[104:107]
	v_mfma_f32_16x16x32_bf16 v[92:95], v[144:147], v[200:203], v[92:95]
	v_mfma_f32_16x16x32_bf16 v[88:91], v[160:163], v[200:203], v[88:91]
	v_mfma_f32_16x16x32_bf16 v[76:79], v[144:147], v[212:215], v[76:79]
	v_mfma_f32_16x16x32_bf16 v[72:75], v[160:163], v[212:215], v[72:75]
	v_mfma_f32_16x16x32_bf16 v[124:127], v[156:159], v[188:191], v[124:127]
	v_mfma_f32_16x16x32_bf16 v[120:123], v[164:167], v[188:191], v[120:123]
	v_mfma_f32_16x16x32_bf16 v[108:111], v[156:159], v[196:199], v[108:111]
	v_mfma_f32_16x16x32_bf16 v[104:107], v[164:167], v[196:199], v[104:107]
	v_mfma_f32_16x16x32_bf16 v[92:95], v[156:159], v[208:211], v[92:95]
	v_mfma_f32_16x16x32_bf16 v[88:91], v[164:167], v[208:211], v[88:91]
	v_mfma_f32_16x16x32_bf16 v[76:79], v[156:159], v[216:219], v[76:79]
	v_mfma_f32_16x16x32_bf16 v[72:75], v[164:167], v[216:219], v[72:75]
	v_mfma_f32_16x16x32_bf16 v[116:119], v[168:171], v[184:187], v[116:119]
	v_mfma_f32_16x16x32_bf16 v[112:115], v[176:179], v[184:187], v[112:115]
	v_mfma_f32_16x16x32_bf16 v[100:103], v[168:171], v[192:195], v[100:103]
	v_mfma_f32_16x16x32_bf16 v[96:99], v[176:179], v[192:195], v[96:99]
	v_mfma_f32_16x16x32_bf16 v[84:87], v[168:171], v[200:203], v[84:87]
	v_mfma_f32_16x16x32_bf16 v[80:83], v[176:179], v[200:203], v[80:83]
	v_mfma_f32_16x16x32_bf16 v[68:71], v[168:171], v[212:215], v[68:71]
	v_mfma_f32_16x16x32_bf16 v[64:67], v[176:179], v[212:215], v[64:67]
	v_mfma_f32_16x16x32_bf16 v[116:119], v[172:175], v[188:191], v[116:119]
	v_mfma_f32_16x16x32_bf16 v[112:115], v[180:183], v[188:191], v[112:115]
	v_mfma_f32_16x16x32_bf16 v[100:103], v[172:175], v[196:199], v[100:103]
	v_mfma_f32_16x16x32_bf16 v[96:99], v[180:183], v[196:199], v[96:99]
	v_mfma_f32_16x16x32_bf16 v[84:87], v[172:175], v[208:211], v[84:87]
	v_mfma_f32_16x16x32_bf16 v[80:83], v[180:183], v[208:211], v[80:83]
	v_mfma_f32_16x16x32_bf16 v[68:71], v[172:175], v[216:219], v[68:71]
	v_mfma_f32_16x16x32_bf16 v[64:67], v[180:183], v[216:219], v[64:67]
	s_barrier
	s_add_i32 s30, s54, s38
	s_mov_b32 m0, s30
	ds_read_b128 v[184:187], v153 offset:49152
	ds_read_b128 v[188:191], v153 offset:50176
	ds_read_b128 v[192:195], v153 offset:51200
	ds_read_b128 v[196:199], v153 offset:52224
	ds_read_b128 v[200:203], v153 offset:53248
	ds_read_b128 v[208:211], v153 offset:54272
	ds_read_b128 v[212:215], v153 offset:55296
	ds_read_b128 v[216:219], v153 offset:56320
	global_load_lds_dwordx4 v205, s[28:29]
	s_add_i32 m0, s30, 0x2000
	s_add_u32 s28, s28, 0x40080
	s_addc_u32 s29, s29, 0
	s_add_i32 s30, s55, s38
	global_load_lds_dwordx4 v221, s[98:99]
	s_mov_b32 m0, s30
	s_nop 0
	global_load_lds_dwordx4 v130, s[28:29]
	s_add_i32 m0, s30, 0x2000
	s_nop 0
	global_load_lds_dwordx4 v134, s[28:29]
	s_cmp_lg_u32 s53, 12
	s_cbranch_scc1 .Lbal_last_19
	s_mov_b32 m0, s44
	s_nop 0
	global_load_lds_dwordx4 v204, s[100:101]
	s_mov_b32 m0, s45
	s_nop 0
	global_load_lds_dwordx4 v220, s[100:101]
.Lbal_last_19:
	s_waitcnt vmcnt(6)
	s_waitcnt lgkmcnt(0)
	s_barrier
	s_waitcnt lgkmcnt(0)
	v_mfma_f32_16x16x32_bf16 v[60:63], v[144:147], v[184:187], v[60:63]
	v_mfma_f32_16x16x32_bf16 v[56:59], v[160:163], v[184:187], v[56:59]
	v_mfma_f32_16x16x32_bf16 v[44:47], v[144:147], v[192:195], v[44:47]
	v_mfma_f32_16x16x32_bf16 v[40:43], v[160:163], v[192:195], v[40:43]
	v_mfma_f32_16x16x32_bf16 v[28:31], v[144:147], v[200:203], v[28:31]
	v_mfma_f32_16x16x32_bf16 v[24:27], v[160:163], v[200:203], v[24:27]
	v_mfma_f32_16x16x32_bf16 v[12:15], v[144:147], v[212:215], v[12:15]
	v_mfma_f32_16x16x32_bf16 v[8:11], v[160:163], v[212:215], v[8:11]
	v_mfma_f32_16x16x32_bf16 v[60:63], v[156:159], v[188:191], v[60:63]
	v_mfma_f32_16x16x32_bf16 v[56:59], v[164:167], v[188:191], v[56:59]
	v_mfma_f32_16x16x32_bf16 v[44:47], v[156:159], v[196:199], v[44:47]
	v_mfma_f32_16x16x32_bf16 v[40:43], v[164:167], v[196:199], v[40:43]
	v_mfma_f32_16x16x32_bf16 v[28:31], v[156:159], v[208:211], v[28:31]
	v_mfma_f32_16x16x32_bf16 v[24:27], v[164:167], v[208:211], v[24:27]
	v_mfma_f32_16x16x32_bf16 v[12:15], v[156:159], v[216:219], v[12:15]
	v_mfma_f32_16x16x32_bf16 v[8:11], v[164:167], v[216:219], v[8:11]
	v_mfma_f32_16x16x32_bf16 v[52:55], v[168:171], v[184:187], v[52:55]
	v_mfma_f32_16x16x32_bf16 v[48:51], v[176:179], v[184:187], v[48:51]
	v_mfma_f32_16x16x32_bf16 v[36:39], v[168:171], v[192:195], v[36:39]
	v_mfma_f32_16x16x32_bf16 v[32:35], v[176:179], v[192:195], v[32:35]
	v_mfma_f32_16x16x32_bf16 v[20:23], v[168:171], v[200:203], v[20:23]
	v_mfma_f32_16x16x32_bf16 v[16:19], v[176:179], v[200:203], v[16:19]
	v_mfma_f32_16x16x32_bf16 v[4:7], v[168:171], v[212:215], v[4:7]
	v_mfma_f32_16x16x32_bf16 v[0:3], v[176:179], v[212:215], v[0:3]
	v_mfma_f32_16x16x32_bf16 v[52:55], v[172:175], v[188:191], v[52:55]
	v_mfma_f32_16x16x32_bf16 v[48:51], v[180:183], v[188:191], v[48:51]
	v_mfma_f32_16x16x32_bf16 v[36:39], v[172:175], v[196:199], v[36:39]
	v_mfma_f32_16x16x32_bf16 v[32:35], v[180:183], v[196:199], v[32:35]
	v_mfma_f32_16x16x32_bf16 v[20:23], v[172:175], v[208:211], v[20:23]
	v_mfma_f32_16x16x32_bf16 v[16:19], v[180:183], v[208:211], v[16:19]
	v_mfma_f32_16x16x32_bf16 v[4:7], v[172:175], v[216:219], v[4:7]
	v_mfma_f32_16x16x32_bf16 v[0:3], v[180:183], v[216:219], v[0:3]
	s_barrier
	s_add_i32 s53, s53, 2
	s_add_u32 s51, s51, 0x100
	s_addc_u32 s52, s52, 0
	s_add_u32 s26, s26, 0x100
	s_addc_u32 s27, s27, 0
	s_cmp_gt_u32 s53, 13
	s_cbranch_scc0 .LBB0_699
	s_setprio 0
	s_and_b64 vcc, exec, s[16:17]
	s_cbranch_vccz .LBB0_702
	s_barrier

.Lbal_first_18:
	ds_read_b128 v[140:143], v147
	ds_read_b128 v[150:153], v147 offset:1024
	ds_read_b128 v[154:157], v147 offset:2048
	ds_read_b128 v[158:161], v147 offset:3072
	ds_read_b128 v[162:165], v148
	ds_read_b128 v[166:169], v148 offset:1024
	ds_read_b128 v[170:173], v148 offset:2048
	ds_read_b128 v[174:177], v148 offset:3072
	s_add_u32 s30, s28, 0x100
	s_addc_u32 s31, s29, 0
	s_cmp_eq_u32 s58, 60
	s_cselect_b32 s37, s21, s31
	s_cselect_b32 s36, s27, s30
	s_cselect_b32 s35, s19, s57
	s_cselect_b32 s34, s55, s56
	s_add_i32 m0, s44, 0xc000
	ds_read_b128 v[178:181], v149
	ds_read_b128 v[182:185], v149 offset:1024
	ds_read_b128 v[186:189], v149 offset:2048
	ds_read_b128 v[190:193], v149 offset:3072
	ds_read_b128 v[194:197], v149 offset:4096
	ds_read_b128 v[198:201], v149 offset:5120
	ds_read_b128 v[202:205], v149 offset:6144
	ds_read_b128 v[208:211], v149 offset:7168
	global_load_lds_dwordx4 v134, s[28:29]
	s_add_i32 m0, s44, 0xe000
	s_nop 0
	global_load_lds_dwordx4 v132, s[28:29]
	s_waitcnt vmcnt(8)
	s_waitcnt lgkmcnt(0)
	s_barrier
	s_waitcnt lgkmcnt(0)
	v_mfma_f32_16x16x32_bf16 v[124:127], v[140:143], v[178:181], v[124:127]
	v_mfma_f32_16x16x32_bf16 v[120:123], v[154:157], v[178:181], v[120:123]
	v_mfma_f32_16x16x32_bf16 v[108:111], v[140:143], v[186:189], v[108:111]
	v_mfma_f32_16x16x32_bf16 v[104:107], v[154:157], v[186:189], v[104:107]
	v_mfma_f32_16x16x32_bf16 v[92:95], v[140:143], v[194:197], v[92:95]
	v_mfma_f32_16x16x32_bf16 v[88:91], v[154:157], v[194:197], v[88:91]
	v_mfma_f32_16x16x32_bf16 v[76:79], v[140:143], v[202:205], v[76:79]
	v_mfma_f32_16x16x32_bf16 v[72:75], v[154:157], v[202:205], v[72:75]
	v_mfma_f32_16x16x32_bf16 v[124:127], v[150:153], v[182:185], v[124:127]
	v_mfma_f32_16x16x32_bf16 v[120:123], v[158:161], v[182:185], v[120:123]
	v_mfma_f32_16x16x32_bf16 v[108:111], v[150:153], v[190:193], v[108:111]
	v_mfma_f32_16x16x32_bf16 v[104:107], v[158:161], v[190:193], v[104:107]
	v_mfma_f32_16x16x32_bf16 v[92:95], v[150:153], v[198:201], v[92:95]
	v_mfma_f32_16x16x32_bf16 v[88:91], v[158:161], v[198:201], v[88:91]
	v_mfma_f32_16x16x32_bf16 v[76:79], v[150:153], v[208:211], v[76:79]
	v_mfma_f32_16x16x32_bf16 v[72:75], v[158:161], v[208:211], v[72:75]
	v_mfma_f32_16x16x32_bf16 v[116:119], v[162:165], v[178:181], v[116:119]
	v_mfma_f32_16x16x32_bf16 v[112:115], v[170:173], v[178:181], v[112:115]
	v_mfma_f32_16x16x32_bf16 v[100:103], v[162:165], v[186:189], v[100:103]
	v_mfma_f32_16x16x32_bf16 v[96:99], v[170:173], v[186:189], v[96:99]
	v_mfma_f32_16x16x32_bf16 v[84:87], v[162:165], v[194:197], v[84:87]
	v_mfma_f32_16x16x32_bf16 v[80:83], v[170:173], v[194:197], v[80:83]
	v_mfma_f32_16x16x32_bf16 v[68:71], v[162:165], v[202:205], v[68:71]
	v_mfma_f32_16x16x32_bf16 v[64:67], v[170:173], v[202:205], v[64:67]
	v_mfma_f32_16x16x32_bf16 v[116:119], v[166:169], v[182:185], v[116:119]
	v_mfma_f32_16x16x32_bf16 v[112:115], v[174:177], v[182:185], v[112:115]
	v_mfma_f32_16x16x32_bf16 v[100:103], v[166:169], v[190:193], v[100:103]
	v_mfma_f32_16x16x32_bf16 v[96:99], v[174:177], v[190:193], v[96:99]
	v_mfma_f32_16x16x32_bf16 v[84:87], v[166:169], v[198:201], v[84:87]
	v_mfma_f32_16x16x32_bf16 v[80:83], v[174:177], v[198:201], v[80:83]
	v_mfma_f32_16x16x32_bf16 v[68:71], v[166:169], v[208:211], v[68:71]
	v_mfma_f32_16x16x32_bf16 v[64:67], v[174:177], v[208:211], v[64:67]
	s_barrier
	s_add_i32 s28, s52, s43
	s_mov_b32 m0, s28
	ds_read_b128 v[178:181], v149 offset:16384
	ds_read_b128 v[182:185], v149 offset:17408
	ds_read_b128 v[186:189], v149 offset:18432
	ds_read_b128 v[190:193], v149 offset:19456
	ds_read_b128 v[194:197], v149 offset:20480
	ds_read_b128 v[198:201], v149 offset:21504
	ds_read_b128 v[202:205], v149 offset:22528
	ds_read_b128 v[208:211], v149 offset:23552
	global_load_lds_dwordx4 v128, s[34:35]
	s_add_i32 m0, s28, 0x2000
	s_add_u32 s28, s34, 0x100000
	s_mov_b64 s[98:99], s[34:35]
	s_addc_u32 s29, s35, 0
	s_add_i32 s59, s53, s43
	global_load_lds_dwordx4 v130, s[34:35]
	s_mov_b32 m0, s59
	s_nop 0
	global_load_lds_dwordx4 v128, s[28:29]
	s_add_i32 m0, s59, 0x2000
	s_nop 0
	global_load_lds_dwordx4 v130, s[28:29]
	s_waitcnt vmcnt(6)
	s_waitcnt lgkmcnt(0)
	s_barrier
	s_waitcnt lgkmcnt(0)
	v_mfma_f32_16x16x32_bf16 v[60:63], v[140:143], v[178:181], v[60:63]
	v_mfma_f32_16x16x32_bf16 v[56:59], v[154:157], v[178:181], v[56:59]
	v_mfma_f32_16x16x32_bf16 v[44:47], v[140:143], v[186:189], v[44:47]
	v_mfma_f32_16x16x32_bf16 v[40:43], v[154:157], v[186:189], v[40:43]
	v_mfma_f32_16x16x32_bf16 v[28:31], v[140:143], v[194:197], v[28:31]
	v_mfma_f32_16x16x32_bf16 v[24:27], v[154:157], v[194:197], v[24:27]
	v_mfma_f32_16x16x32_bf16 v[12:15], v[140:143], v[202:205], v[12:15]
	v_mfma_f32_16x16x32_bf16 v[8:11], v[154:157], v[202:205], v[8:11]
	v_mfma_f32_16x16x32_bf16 v[60:63], v[150:153], v[182:185], v[60:63]
	v_mfma_f32_16x16x32_bf16 v[56:59], v[158:161], v[182:185], v[56:59]
	v_mfma_f32_16x16x32_bf16 v[44:47], v[150:153], v[190:193], v[44:47]
	v_mfma_f32_16x16x32_bf16 v[40:43], v[158:161], v[190:193], v[40:43]
	v_mfma_f32_16x16x32_bf16 v[28:31], v[150:153], v[198:201], v[28:31]
	v_mfma_f32_16x16x32_bf16 v[24:27], v[158:161], v[198:201], v[24:27]
	v_mfma_f32_16x16x32_bf16 v[12:15], v[150:153], v[208:211], v[12:15]
	v_mfma_f32_16x16x32_bf16 v[8:11], v[158:161], v[208:211], v[8:11]
	v_mfma_f32_16x16x32_bf16 v[52:55], v[162:165], v[178:181], v[52:55]
	v_mfma_f32_16x16x32_bf16 v[48:51], v[170:173], v[178:181], v[48:51]
	v_mfma_f32_16x16x32_bf16 v[36:39], v[162:165], v[186:189], v[36:39]
	v_mfma_f32_16x16x32_bf16 v[32:35], v[170:173], v[186:189], v[32:35]
	v_mfma_f32_16x16x32_bf16 v[20:23], v[162:165], v[194:197], v[20:23]
	v_mfma_f32_16x16x32_bf16 v[16:19], v[170:173], v[194:197], v[16:19]
	v_mfma_f32_16x16x32_bf16 v[4:7], v[162:165], v[202:205], v[4:7]
	v_mfma_f32_16x16x32_bf16 v[0:3], v[170:173], v[202:205], v[0:3]
	v_mfma_f32_16x16x32_bf16 v[52:55], v[166:169], v[182:185], v[52:55]
	v_mfma_f32_16x16x32_bf16 v[48:51], v[174:177], v[182:185], v[48:51]
	v_mfma_f32_16x16x32_bf16 v[36:39], v[166:169], v[190:193], v[36:39]
	v_mfma_f32_16x16x32_bf16 v[32:35], v[174:177], v[190:193], v[32:35]
	v_mfma_f32_16x16x32_bf16 v[20:23], v[166:169], v[198:201], v[20:23]
	v_mfma_f32_16x16x32_bf16 v[16:19], v[174:177], v[198:201], v[16:19]
	v_mfma_f32_16x16x32_bf16 v[4:7], v[166:169], v[208:211], v[4:7]
	v_mfma_f32_16x16x32_bf16 v[0:3], v[174:177], v[208:211], v[0:3]
	s_barrier
	s_mov_b32 m0, s44
	s_nop 0
	global_load_lds_dwordx4 v128, s[36:37]
	s_mov_b32 m0, s45
	s_nop 0
	global_load_lds_dwordx4 v130, s[36:37]
	s_add_i32 s59, 0, 0x18000
	s_add_i32 s60, 0, 0x1c000
	v_add_u32_e32 v158, s59, v145
	v_add_u32_e32 v174, s60, v145
	ds_read_b128 v[140:143], v158
	ds_read_b128 v[150:153], v158 offset:1024
	ds_read_b128 v[154:157], v158 offset:2048
	ds_read_b128 v[158:161], v158 offset:3072
	ds_read_b128 v[162:165], v174
	ds_read_b128 v[166:169], v174 offset:1024
	ds_read_b128 v[170:173], v174 offset:2048
	ds_read_b128 v[174:177], v174 offset:3072
	s_add_u32 s28, s36, 0x100000
	s_addc_u32 s29, s37, 0
	s_mov_b32 m0, s46
	ds_read_b128 v[178:181], v149 offset:32768
	ds_read_b128 v[182:185], v149 offset:33792
	ds_read_b128 v[186:189], v149 offset:34816
	ds_read_b128 v[190:193], v149 offset:35840
	ds_read_b128 v[194:197], v149 offset:36864
	ds_read_b128 v[198:201], v149 offset:37888
	ds_read_b128 v[202:205], v149 offset:38912
	ds_read_b128 v[208:211], v149 offset:39936
	global_load_lds_dwordx4 v128, s[28:29]
	s_mov_b32 m0, s47
	s_nop 0
	global_load_lds_dwordx4 v130, s[28:29]
	s_waitcnt vmcnt(8)
	s_waitcnt lgkmcnt(0)
	s_barrier
	s_waitcnt lgkmcnt(0)
	v_mfma_f32_16x16x32_bf16 v[124:127], v[140:143], v[178:181], v[124:127]
	v_mfma_f32_16x16x32_bf16 v[120:123], v[154:157], v[178:181], v[120:123]
	v_mfma_f32_16x16x32_bf16 v[108:111], v[140:143], v[186:189], v[108:111]
	v_mfma_f32_16x16x32_bf16 v[104:107], v[154:157], v[186:189], v[104:107]
	v_mfma_f32_16x16x32_bf16 v[92:95], v[140:143], v[194:197], v[92:95]
	v_mfma_f32_16x16x32_bf16 v[88:91], v[154:157], v[194:197], v[88:91]
	v_mfma_f32_16x16x32_bf16 v[76:79], v[140:143], v[202:205], v[76:79]
	v_mfma_f32_16x16x32_bf16 v[72:75], v[154:157], v[202:205], v[72:75]
	v_mfma_f32_16x16x32_bf16 v[124:127], v[150:153], v[182:185], v[124:127]
	v_mfma_f32_16x16x32_bf16 v[120:123], v[158:161], v[182:185], v[120:123]
	v_mfma_f32_16x16x32_bf16 v[108:111], v[150:153], v[190:193], v[108:111]
	v_mfma_f32_16x16x32_bf16 v[104:107], v[158:161], v[190:193], v[104:107]
	v_mfma_f32_16x16x32_bf16 v[92:95], v[150:153], v[198:201], v[92:95]
	v_mfma_f32_16x16x32_bf16 v[88:91], v[158:161], v[198:201], v[88:91]
	v_mfma_f32_16x16x32_bf16 v[76:79], v[150:153], v[208:211], v[76:79]
	v_mfma_f32_16x16x32_bf16 v[72:75], v[158:161], v[208:211], v[72:75]
	v_mfma_f32_16x16x32_bf16 v[116:119], v[162:165], v[178:181], v[116:119]
	v_mfma_f32_16x16x32_bf16 v[112:115], v[170:173], v[178:181], v[112:115]
	v_mfma_f32_16x16x32_bf16 v[100:103], v[162:165], v[186:189], v[100:103]
	v_mfma_f32_16x16x32_bf16 v[96:99], v[170:173], v[186:189], v[96:99]
	v_mfma_f32_16x16x32_bf16 v[84:87], v[162:165], v[194:197], v[84:87]
	v_mfma_f32_16x16x32_bf16 v[80:83], v[170:173], v[194:197], v[80:83]
	v_mfma_f32_16x16x32_bf16 v[68:71], v[162:165], v[202:205], v[68:71]
	v_mfma_f32_16x16x32_bf16 v[64:67], v[170:173], v[202:205], v[64:67]
	v_mfma_f32_16x16x32_bf16 v[116:119], v[166:169], v[182:185], v[116:119]
	v_mfma_f32_16x16x32_bf16 v[112:115], v[174:177], v[182:185], v[112:115]
	v_mfma_f32_16x16x32_bf16 v[100:103], v[166:169], v[190:193], v[100:103]
	v_mfma_f32_16x16x32_bf16 v[96:99], v[174:177], v[190:193], v[96:99]
	v_mfma_f32_16x16x32_bf16 v[84:87], v[166:169], v[198:201], v[84:87]
	v_mfma_f32_16x16x32_bf16 v[80:83], v[174:177], v[198:201], v[80:83]
	v_mfma_f32_16x16x32_bf16 v[68:71], v[166:169], v[208:211], v[68:71]
	v_mfma_f32_16x16x32_bf16 v[64:67], v[174:177], v[208:211], v[64:67]
	s_barrier
	s_add_i32 s28, s59, s43
	s_mov_b32 m0, s28
	ds_read_b128 v[178:181], v149 offset:49152
	ds_read_b128 v[182:185], v149 offset:50176
	ds_read_b128 v[186:189], v149 offset:51200
	ds_read_b128 v[190:193], v149 offset:52224
	ds_read_b128 v[194:197], v149 offset:53248
	ds_read_b128 v[198:201], v149 offset:54272
	ds_read_b128 v[202:205], v149 offset:55296
	ds_read_b128 v[208:211], v149 offset:56320
	global_load_lds_dwordx4 v212, s[34:35]
	s_add_i32 m0, s28, 0x2000
	s_add_u32 s28, s34, 0x100080
	s_addc_u32 s29, s35, 0
	s_add_i32 s34, s60, s43
	global_load_lds_dwordx4 v213, s[98:99]
	s_mov_b32 m0, s34
	s_nop 0
	global_load_lds_dwordx4 v128, s[28:29]
	s_add_i32 m0, s34, 0x2000
	s_nop 0
	global_load_lds_dwordx4 v130, s[28:29]
	s_cmp_lg_u32 s58, 60
	s_cbranch_scc1 .Lbal_last_18
	s_mov_b32 m0, s49
	s_nop 0
	global_load_lds_dwordx4 v212, s[36:37]
	s_mov_b32 m0, s50
	s_nop 0
	global_load_lds_dwordx4 v213, s[36:37]
.Lbal_last_18:
	s_waitcnt vmcnt(6)
	s_waitcnt lgkmcnt(0)
	s_barrier
	s_waitcnt lgkmcnt(0)
	v_mfma_f32_16x16x32_bf16 v[60:63], v[140:143], v[178:181], v[60:63]
	v_mfma_f32_16x16x32_bf16 v[56:59], v[154:157], v[178:181], v[56:59]
	v_mfma_f32_16x16x32_bf16 v[44:47], v[140:143], v[186:189], v[44:47]
	v_mfma_f32_16x16x32_bf16 v[40:43], v[154:157], v[186:189], v[40:43]
	v_mfma_f32_16x16x32_bf16 v[28:31], v[140:143], v[194:197], v[28:31]
	v_mfma_f32_16x16x32_bf16 v[24:27], v[154:157], v[194:197], v[24:27]
	v_mfma_f32_16x16x32_bf16 v[12:15], v[140:143], v[202:205], v[12:15]
	v_mfma_f32_16x16x32_bf16 v[8:11], v[154:157], v[202:205], v[8:11]
	v_mfma_f32_16x16x32_bf16 v[60:63], v[150:153], v[182:185], v[60:63]
	v_mfma_f32_16x16x32_bf16 v[56:59], v[158:161], v[182:185], v[56:59]
	v_mfma_f32_16x16x32_bf16 v[44:47], v[150:153], v[190:193], v[44:47]
	v_mfma_f32_16x16x32_bf16 v[40:43], v[158:161], v[190:193], v[40:43]
	v_mfma_f32_16x16x32_bf16 v[28:31], v[150:153], v[198:201], v[28:31]
	v_mfma_f32_16x16x32_bf16 v[24:27], v[158:161], v[198:201], v[24:27]
	v_mfma_f32_16x16x32_bf16 v[12:15], v[150:153], v[208:211], v[12:15]
	v_mfma_f32_16x16x32_bf16 v[8:11], v[158:161], v[208:211], v[8:11]
	v_mfma_f32_16x16x32_bf16 v[52:55], v[162:165], v[178:181], v[52:55]
	v_mfma_f32_16x16x32_bf16 v[48:51], v[170:173], v[178:181], v[48:51]
	v_mfma_f32_16x16x32_bf16 v[36:39], v[162:165], v[186:189], v[36:39]
	v_mfma_f32_16x16x32_bf16 v[32:35], v[170:173], v[186:189], v[32:35]
	v_mfma_f32_16x16x32_bf16 v[20:23], v[162:165], v[194:197], v[20:23]
	v_mfma_f32_16x16x32_bf16 v[16:19], v[170:173], v[194:197], v[16:19]
	v_mfma_f32_16x16x32_bf16 v[4:7], v[162:165], v[202:205], v[4:7]
	v_mfma_f32_16x16x32_bf16 v[0:3], v[170:173], v[202:205], v[0:3]
	v_mfma_f32_16x16x32_bf16 v[52:55], v[166:169], v[182:185], v[52:55]
	v_mfma_f32_16x16x32_bf16 v[48:51], v[174:177], v[182:185], v[48:51]
	v_mfma_f32_16x16x32_bf16 v[36:39], v[166:169], v[190:193], v[36:39]
	v_mfma_f32_16x16x32_bf16 v[32:35], v[174:177], v[190:193], v[32:35]
	v_mfma_f32_16x16x32_bf16 v[20:23], v[166:169], v[198:201], v[20:23]
	v_mfma_f32_16x16x32_bf16 v[16:19], v[174:177], v[198:201], v[16:19]
	v_mfma_f32_16x16x32_bf16 v[4:7], v[166:169], v[208:211], v[4:7]
	v_mfma_f32_16x16x32_bf16 v[0:3], v[174:177], v[208:211], v[0:3]
	s_barrier
	s_add_i32 s58, s58, 2
	s_add_u32 s56, s56, 0x100
	s_addc_u32 s57, s57, 0
	s_cmp_gt_u32 s58, 61
	s_mov_b64 s[28:29], s[30:31]
	s_cbranch_scc0 .LBB0_778
	s_setprio 0
	s_and_b64 vcc, exec, s[16:17]
	s_cbranch_vccz .LBB0_781
	s_barrier

.LBB0_895:
	s_cmp_eq_i32 s61, -2
	s_cbranch_scc1 .Lbal_first_17
	s_mov_b32 m0, s51
	s_nop 0
	global_load_lds_dwordx4 v148, s[100:101]
	s_mov_b32 m0, s52
	s_nop 0
	global_load_lds_dwordx4 v149, s[100:101]
.Lbal_first_17:
	ds_read_b128 v[140:143], v153
	ds_read_b128 v[144:147], v153 offset:1024
	ds_read_b128 v[158:161], v153 offset:2048
	ds_read_b128 v[162:165], v153 offset:3072
	ds_read_b128 v[166:169], v154
	ds_read_b128 v[170:173], v154 offset:1024
	ds_read_b128 v[174:177], v154 offset:2048
	ds_read_b128 v[178:181], v154 offset:3072
	s_add_u32 s38, s36, 0xfffc0080
	s_addc_u32 s39, s37, -1
	s_cmp_eq_u32 s61, 12
	s_cselect_b32 s41, s3, s39
	s_cselect_b32 s40, s29, s38
	s_cselect_b32 s39, s27, s60
	s_cselect_b32 s38, s58, s59
	s_add_i32 m0, s46, 0xc000
	ds_read_b128 v[182:185], v155
	ds_read_b128 v[186:189], v155 offset:1024
	ds_read_b128 v[190:193], v155 offset:2048
	ds_read_b128 v[194:197], v155 offset:3072
	ds_read_b128 v[198:201], v155 offset:4096
	ds_read_b128 v[202:205], v155 offset:5120
	ds_read_b128 v[208:211], v155 offset:6144
	ds_read_b128 v[212:215], v155 offset:7168
	global_load_lds_dwordx4 v134, s[36:37]
	s_add_i32 m0, s46, 0xe000
	s_nop 0
	global_load_lds_dwordx4 v132, s[36:37]
	s_waitcnt vmcnt(8)
	s_waitcnt lgkmcnt(0)
	s_barrier
	s_waitcnt lgkmcnt(0)
	v_mfma_f32_16x16x32_bf16 v[124:127], v[140:143], v[182:185], v[124:127]
	v_mfma_f32_16x16x32_bf16 v[120:123], v[158:161], v[182:185], v[120:123]
	v_mfma_f32_16x16x32_bf16 v[108:111], v[140:143], v[190:193], v[108:111]
	v_mfma_f32_16x16x32_bf16 v[104:107], v[158:161], v[190:193], v[104:107]
	v_mfma_f32_16x16x32_bf16 v[92:95], v[140:143], v[198:201], v[92:95]
	v_mfma_f32_16x16x32_bf16 v[88:91], v[158:161], v[198:201], v[88:91]
	v_mfma_f32_16x16x32_bf16 v[76:79], v[140:143], v[208:211], v[76:79]
	v_mfma_f32_16x16x32_bf16 v[72:75], v[158:161], v[208:211], v[72:75]
	v_mfma_f32_16x16x32_bf16 v[124:127], v[144:147], v[186:189], v[124:127]
	v_mfma_f32_16x16x32_bf16 v[120:123], v[162:165], v[186:189], v[120:123]
	v_mfma_f32_16x16x32_bf16 v[108:111], v[144:147], v[194:197], v[108:111]
	v_mfma_f32_16x16x32_bf16 v[104:107], v[162:165], v[194:197], v[104:107]
	v_mfma_f32_16x16x32_bf16 v[92:95], v[144:147], v[202:205], v[92:95]
	v_mfma_f32_16x16x32_bf16 v[88:91], v[162:165], v[202:205], v[88:91]
	v_mfma_f32_16x16x32_bf16 v[76:79], v[144:147], v[212:215], v[76:79]
	v_mfma_f32_16x16x32_bf16 v[72:75], v[162:165], v[212:215], v[72:75]
	v_mfma_f32_16x16x32_bf16 v[116:119], v[166:169], v[182:185], v[116:119]
	v_mfma_f32_16x16x32_bf16 v[112:115], v[174:177], v[182:185], v[112:115]
	v_mfma_f32_16x16x32_bf16 v[100:103], v[166:169], v[190:193], v[100:103]
	v_mfma_f32_16x16x32_bf16 v[96:99], v[174:177], v[190:193], v[96:99]
	v_mfma_f32_16x16x32_bf16 v[84:87], v[166:169], v[198:201], v[84:87]
	v_mfma_f32_16x16x32_bf16 v[80:83], v[174:177], v[198:201], v[80:83]
	v_mfma_f32_16x16x32_bf16 v[68:71], v[166:169], v[208:211], v[68:71]
	v_mfma_f32_16x16x32_bf16 v[64:67], v[174:177], v[208:211], v[64:67]
	v_mfma_f32_16x16x32_bf16 v[116:119], v[170:173], v[186:189], v[116:119]
	v_mfma_f32_16x16x32_bf16 v[112:115], v[178:181], v[186:189], v[112:115]
	v_mfma_f32_16x16x32_bf16 v[100:103], v[170:173], v[194:197], v[100:103]
	v_mfma_f32_16x16x32_bf16 v[96:99], v[178:181], v[194:197], v[96:99]
	v_mfma_f32_16x16x32_bf16 v[84:87], v[170:173], v[202:205], v[84:87]
	v_mfma_f32_16x16x32_bf16 v[80:83], v[178:181], v[202:205], v[80:83]
	v_mfma_f32_16x16x32_bf16 v[68:71], v[170:173], v[212:215], v[68:71]
	v_mfma_f32_16x16x32_bf16 v[64:67], v[178:181], v[212:215], v[64:67]
	s_barrier
	s_add_i32 s62, s54, s45
	s_mov_b32 m0, s62
	ds_read_b128 v[182:185], v155 offset:16384
	ds_read_b128 v[186:189], v155 offset:17408
	ds_read_b128 v[190:193], v155 offset:18432
	ds_read_b128 v[194:197], v155 offset:19456
	ds_read_b128 v[198:201], v155 offset:20480
	ds_read_b128 v[202:205], v155 offset:21504
	ds_read_b128 v[208:211], v155 offset:22528
	ds_read_b128 v[212:215], v155 offset:23552
	global_load_lds_dwordx4 v128, s[38:39]
	s_add_i32 m0, s62, 0x2000
	s_add_u32 s62, s38, 0x40000
	s_mov_b64 s[98:99], s[38:39]
	s_addc_u32 s63, s39, 0
	s_add_i32 s64, s55, s45
	global_load_lds_dwordx4 v130, s[38:39]
	s_mov_b32 m0, s64
	s_mov_b64 s[100:101], s[40:41]
	global_load_lds_dwordx4 v128, s[62:63]
	s_add_i32 m0, s64, 0x2000
	s_nop 0
	global_load_lds_dwordx4 v130, s[62:63]
	s_waitcnt vmcnt(6)
	s_waitcnt lgkmcnt(0)
	s_barrier
	s_waitcnt lgkmcnt(0)
	v_mfma_f32_16x16x32_bf16 v[60:63], v[140:143], v[182:185], v[60:63]
	v_mfma_f32_16x16x32_bf16 v[56:59], v[158:161], v[182:185], v[56:59]
	v_mfma_f32_16x16x32_bf16 v[44:47], v[140:143], v[190:193], v[44:47]
	v_mfma_f32_16x16x32_bf16 v[40:43], v[158:161], v[190:193], v[40:43]
	v_mfma_f32_16x16x32_bf16 v[28:31], v[140:143], v[198:201], v[28:31]
	v_mfma_f32_16x16x32_bf16 v[24:27], v[158:161], v[198:201], v[24:27]
	v_mfma_f32_16x16x32_bf16 v[12:15], v[140:143], v[208:211], v[12:15]
	v_mfma_f32_16x16x32_bf16 v[8:11], v[158:161], v[208:211], v[8:11]
	v_mfma_f32_16x16x32_bf16 v[60:63], v[144:147], v[186:189], v[60:63]
	v_mfma_f32_16x16x32_bf16 v[56:59], v[162:165], v[186:189], v[56:59]
	v_mfma_f32_16x16x32_bf16 v[44:47], v[144:147], v[194:197], v[44:47]
	v_mfma_f32_16x16x32_bf16 v[40:43], v[162:165], v[194:197], v[40:43]
	v_mfma_f32_16x16x32_bf16 v[28:31], v[144:147], v[202:205], v[28:31]
	v_mfma_f32_16x16x32_bf16 v[24:27], v[162:165], v[202:205], v[24:27]
	v_mfma_f32_16x16x32_bf16 v[12:15], v[144:147], v[212:215], v[12:15]
	v_mfma_f32_16x16x32_bf16 v[8:11], v[162:165], v[212:215], v[8:11]
	v_mfma_f32_16x16x32_bf16 v[52:55], v[166:169], v[182:185], v[52:55]
	v_mfma_f32_16x16x32_bf16 v[48:51], v[174:177], v[182:185], v[48:51]
	v_mfma_f32_16x16x32_bf16 v[36:39], v[166:169], v[190:193], v[36:39]
	v_mfma_f32_16x16x32_bf16 v[32:35], v[174:177], v[190:193], v[32:35]
	v_mfma_f32_16x16x32_bf16 v[20:23], v[166:169], v[198:201], v[20:23]
	v_mfma_f32_16x16x32_bf16 v[16:19], v[174:177], v[198:201], v[16:19]
	v_mfma_f32_16x16x32_bf16 v[4:7], v[166:169], v[208:211], v[4:7]
	v_mfma_f32_16x16x32_bf16 v[0:3], v[174:177], v[208:211], v[0:3]
	v_mfma_f32_16x16x32_bf16 v[52:55], v[170:173], v[186:189], v[52:55]
	v_mfma_f32_16x16x32_bf16 v[48:51], v[178:181], v[186:189], v[48:51]
	v_mfma_f32_16x16x32_bf16 v[36:39], v[170:173], v[194:197], v[36:39]
	v_mfma_f32_16x16x32_bf16 v[32:35], v[178:181], v[194:197], v[32:35]
	v_mfma_f32_16x16x32_bf16 v[20:23], v[170:173], v[202:205], v[20:23]
	v_mfma_f32_16x16x32_bf16 v[16:19], v[178:181], v[202:205], v[16:19]
	v_mfma_f32_16x16x32_bf16 v[4:7], v[170:173], v[212:215], v[4:7]
	v_mfma_f32_16x16x32_bf16 v[0:3], v[178:181], v[212:215], v[0:3]
	s_barrier
	s_mov_b32 m0, s46
	s_nop 0
	global_load_lds_dwordx4 v128, s[40:41]
	s_mov_b32 m0, s47
	s_nop 0
	global_load_lds_dwordx4 v130, s[40:41]
	s_add_i32 s62, 0, 0x18000
	v_add_u32_e32 v157, s62, v151
	s_add_i32 s63, 0, 0x1c000
	ds_read_b128 v[140:143], v157
	ds_read_b128 v[144:147], v157 offset:1024
	ds_read_b128 v[158:161], v157 offset:2048
	ds_read_b128 v[162:165], v157 offset:3072
	v_add_u32_e32 v157, s63, v151
	ds_read_b128 v[166:169], v157
	ds_read_b128 v[170:173], v157 offset:1024
	ds_read_b128 v[174:177], v157 offset:2048
	ds_read_b128 v[178:181], v157 offset:3072
	s_add_u32 s40, s40, 0x40000
	s_addc_u32 s41, s41, 0
	s_mov_b32 m0, s48
	ds_read_b128 v[182:185], v155 offset:32768
	ds_read_b128 v[186:189], v155 offset:33792
	ds_read_b128 v[190:193], v155 offset:34816
	ds_read_b128 v[194:197], v155 offset:35840
	ds_read_b128 v[198:201], v155 offset:36864
	ds_read_b128 v[202:205], v155 offset:37888
	ds_read_b128 v[208:211], v155 offset:38912
	ds_read_b128 v[212:215], v155 offset:39936
	global_load_lds_dwordx4 v128, s[40:41]
	s_mov_b32 m0, s49
	s_nop 0
	global_load_lds_dwordx4 v130, s[40:41]
	s_waitcnt vmcnt(8)
	s_waitcnt lgkmcnt(0)
	s_barrier
	s_waitcnt lgkmcnt(0)
	v_mfma_f32_16x16x32_bf16 v[124:127], v[140:143], v[182:185], v[124:127]
	v_mfma_f32_16x16x32_bf16 v[120:123], v[158:161], v[182:185], v[120:123]
	v_mfma_f32_16x16x32_bf16 v[108:111], v[140:143], v[190:193], v[108:111]
	v_mfma_f32_16x16x32_bf16 v[104:107], v[158:161], v[190:193], v[104:107]
	v_mfma_f32_16x16x32_bf16 v[92:95], v[140:143], v[198:201], v[92:95]
	v_mfma_f32_16x16x32_bf16 v[88:91], v[158:161], v[198:201], v[88:91]
	v_mfma_f32_16x16x32_bf16 v[76:79], v[140:143], v[208:211], v[76:79]
	v_mfma_f32_16x16x32_bf16 v[72:75], v[158:161], v[208:211], v[72:75]
	v_mfma_f32_16x16x32_bf16 v[124:127], v[144:147], v[186:189], v[124:127]
	v_mfma_f32_16x16x32_bf16 v[120:123], v[162:165], v[186:189], v[120:123]
	v_mfma_f32_16x16x32_bf16 v[108:111], v[144:147], v[194:197], v[108:111]
	v_mfma_f32_16x16x32_bf16 v[104:107], v[162:165], v[194:197], v[104:107]
	v_mfma_f32_16x16x32_bf16 v[92:95], v[144:147], v[202:205], v[92:95]
	v_mfma_f32_16x16x32_bf16 v[88:91], v[162:165], v[202:205], v[88:91]
	v_mfma_f32_16x16x32_bf16 v[76:79], v[144:147], v[212:215], v[76:79]
	v_mfma_f32_16x16x32_bf16 v[72:75], v[162:165], v[212:215], v[72:75]
	v_mfma_f32_16x16x32_bf16 v[116:119], v[166:169], v[182:185], v[116:119]
	v_mfma_f32_16x16x32_bf16 v[112:115], v[174:177], v[182:185], v[112:115]
	v_mfma_f32_16x16x32_bf16 v[100:103], v[166:169], v[190:193], v[100:103]
	v_mfma_f32_16x16x32_bf16 v[96:99], v[174:177], v[190:193], v[96:99]
	v_mfma_f32_16x16x32_bf16 v[84:87], v[166:169], v[198:201], v[84:87]
	v_mfma_f32_16x16x32_bf16 v[80:83], v[174:177], v[198:201], v[80:83]
	v_mfma_f32_16x16x32_bf16 v[68:71], v[166:169], v[208:211], v[68:71]
	v_mfma_f32_16x16x32_bf16 v[64:67], v[174:177], v[208:211], v[64:67]
	v_mfma_f32_16x16x32_bf16 v[116:119], v[170:173], v[186:189], v[116:119]
	v_mfma_f32_16x16x32_bf16 v[112:115], v[178:181], v[186:189], v[112:115]
	v_mfma_f32_16x16x32_bf16 v[100:103], v[170:173], v[194:197], v[100:103]
	v_mfma_f32_16x16x32_bf16 v[96:99], v[178:181], v[194:197], v[96:99]
	v_mfma_f32_16x16x32_bf16 v[84:87], v[170:173], v[202:205], v[84:87]
	v_mfma_f32_16x16x32_bf16 v[80:83], v[178:181], v[202:205], v[80:83]
	v_mfma_f32_16x16x32_bf16 v[68:71], v[170:173], v[212:215], v[68:71]
	v_mfma_f32_16x16x32_bf16 v[64:67], v[178:181], v[212:215], v[64:67]
	s_barrier
	s_add_i32 s40, s62, s45
	s_mov_b32 m0, s40
	ds_read_b128 v[182:185], v155 offset:49152
	ds_read_b128 v[186:189], v155 offset:50176
	ds_read_b128 v[190:193], v155 offset:51200
	ds_read_b128 v[194:197], v155 offset:52224
	ds_read_b128 v[198:201], v155 offset:53248
	ds_read_b128 v[202:205], v155 offset:54272
	ds_read_b128 v[208:211], v155 offset:55296
	ds_read_b128 v[212:215], v155 offset:56320
	global_load_lds_dwordx4 v148, s[38:39]
	s_add_i32 m0, s40, 0x2000
	s_add_u32 s38, s38, 0x40080
	s_addc_u32 s39, s39, 0
	s_add_i32 s40, s63, s45
	global_load_lds_dwordx4 v149, s[98:99]
	s_mov_b32 m0, s40
	s_nop 0
	global_load_lds_dwordx4 v128, s[38:39]
	s_add_i32 m0, s40, 0x2000
	s_nop 0
	global_load_lds_dwordx4 v130, s[38:39]
	s_cmp_lg_u32 s61, 12
	s_cbranch_scc1 .Lbal_last_17
	s_mov_b32 m0, s51
	s_nop 0
	global_load_lds_dwordx4 v148, s[100:101]
	s_mov_b32 m0, s52
	s_nop 0
	global_load_lds_dwordx4 v149, s[100:101]
.Lbal_last_17:
	s_waitcnt vmcnt(6)
	s_waitcnt lgkmcnt(0)
	s_barrier
	s_waitcnt lgkmcnt(0)
	v_mfma_f32_16x16x32_bf16 v[60:63], v[140:143], v[182:185], v[60:63]
	v_mfma_f32_16x16x32_bf16 v[56:59], v[158:161], v[182:185], v[56:59]
	v_mfma_f32_16x16x32_bf16 v[44:47], v[140:143], v[190:193], v[44:47]
	v_mfma_f32_16x16x32_bf16 v[40:43], v[158:161], v[190:193], v[40:43]
	v_mfma_f32_16x16x32_bf16 v[28:31], v[140:143], v[198:201], v[28:31]
	v_mfma_f32_16x16x32_bf16 v[24:27], v[158:161], v[198:201], v[24:27]
	v_mfma_f32_16x16x32_bf16 v[12:15], v[140:143], v[208:211], v[12:15]
	v_mfma_f32_16x16x32_bf16 v[8:11], v[158:161], v[208:211], v[8:11]
	v_mfma_f32_16x16x32_bf16 v[60:63], v[144:147], v[186:189], v[60:63]
	v_mfma_f32_16x16x32_bf16 v[56:59], v[162:165], v[186:189], v[56:59]
	v_mfma_f32_16x16x32_bf16 v[44:47], v[144:147], v[194:197], v[44:47]
	v_mfma_f32_16x16x32_bf16 v[40:43], v[162:165], v[194:197], v[40:43]
	v_mfma_f32_16x16x32_bf16 v[28:31], v[144:147], v[202:205], v[28:31]
	v_mfma_f32_16x16x32_bf16 v[24:27], v[162:165], v[202:205], v[24:27]
	v_mfma_f32_16x16x32_bf16 v[12:15], v[144:147], v[212:215], v[12:15]
	v_mfma_f32_16x16x32_bf16 v[8:11], v[162:165], v[212:215], v[8:11]
	v_mfma_f32_16x16x32_bf16 v[52:55], v[166:169], v[182:185], v[52:55]
	v_mfma_f32_16x16x32_bf16 v[48:51], v[174:177], v[182:185], v[48:51]
	v_mfma_f32_16x16x32_bf16 v[36:39], v[166:169], v[190:193], v[36:39]
	v_mfma_f32_16x16x32_bf16 v[32:35], v[174:177], v[190:193], v[32:35]
	v_mfma_f32_16x16x32_bf16 v[20:23], v[166:169], v[198:201], v[20:23]
	v_mfma_f32_16x16x32_bf16 v[16:19], v[174:177], v[198:201], v[16:19]
	v_mfma_f32_16x16x32_bf16 v[4:7], v[166:169], v[208:211], v[4:7]
	v_mfma_f32_16x16x32_bf16 v[0:3], v[174:177], v[208:211], v[0:3]
	v_mfma_f32_16x16x32_bf16 v[52:55], v[170:173], v[186:189], v[52:55]
	v_mfma_f32_16x16x32_bf16 v[48:51], v[178:181], v[186:189], v[48:51]
	v_mfma_f32_16x16x32_bf16 v[36:39], v[170:173], v[194:197], v[36:39]
	v_mfma_f32_16x16x32_bf16 v[32:35], v[178:181], v[194:197], v[32:35]
	v_mfma_f32_16x16x32_bf16 v[20:23], v[170:173], v[202:205], v[20:23]
	v_mfma_f32_16x16x32_bf16 v[16:19], v[178:181], v[202:205], v[16:19]
	v_mfma_f32_16x16x32_bf16 v[4:7], v[170:173], v[212:215], v[4:7]
	v_mfma_f32_16x16x32_bf16 v[0:3], v[178:181], v[212:215], v[0:3]
	s_barrier
	s_add_i32 s61, s61, 2
	s_add_u32 s59, s59, 0x100
	s_addc_u32 s60, s60, 0
	s_add_u32 s36, s36, 0x100
	s_addc_u32 s37, s37, 0
	s_cmp_gt_u32 s61, 13
	s_cbranch_scc0 .LBB0_895
	s_setprio 0
	s_and_b64 vcc, exec, s[24:25]
	s_cbranch_vccz .LBB0_898
	s_barrier

.LBB0_988:
	s_cmp_eq_i32 s53, -2
	s_cbranch_scc1 .Lbal_first_16
	s_mov_b32 m0, s43
	s_nop 0
	global_load_lds_dwordx4 v204, s[100:101]
	s_mov_b32 m0, s44
	s_nop 0
	global_load_lds_dwordx4 v220, s[100:101]
.Lbal_first_16:
	ds_read_b128 v[144:147], v151
	ds_read_b128 v[156:159], v151 offset:1024
	ds_read_b128 v[160:163], v151 offset:2048
	ds_read_b128 v[164:167], v151 offset:3072
	ds_read_b128 v[168:171], v152
	ds_read_b128 v[172:175], v152 offset:1024
	ds_read_b128 v[176:179], v152 offset:2048
	ds_read_b128 v[180:183], v152 offset:3072
	s_add_u32 s26, s6, 0xfffc0080
	s_addc_u32 s27, s7, -1
	s_cmp_eq_u32 s53, 12
	s_cselect_b32 s29, s19, s27
	s_cselect_b32 s28, s49, s26
	s_cselect_b32 s27, s17, s52
	s_cselect_b32 s26, s50, s51
	s_add_i32 m0, s25, 0xc000
	ds_read_b128 v[184:187], v153
	ds_read_b128 v[188:191], v153 offset:1024
	ds_read_b128 v[192:195], v153 offset:2048
	ds_read_b128 v[196:199], v153 offset:3072
	ds_read_b128 v[200:203], v153 offset:4096
	ds_read_b128 v[208:211], v153 offset:5120
	ds_read_b128 v[212:215], v153 offset:6144
	ds_read_b128 v[216:219], v153 offset:7168
	global_load_lds_dwordx4 v138, s[6:7]
	s_add_i32 m0, s25, 0xe000
	s_nop 0
	global_load_lds_dwordx4 v136, s[6:7]
	s_waitcnt vmcnt(8)
	s_waitcnt lgkmcnt(0)
	s_barrier
	s_waitcnt lgkmcnt(0)
	v_mfma_f32_16x16x32_bf16 v[124:127], v[144:147], v[184:187], v[124:127]
	v_mfma_f32_16x16x32_bf16 v[120:123], v[160:163], v[184:187], v[120:123]
	v_mfma_f32_16x16x32_bf16 v[108:111], v[144:147], v[192:195], v[108:111]
	v_mfma_f32_16x16x32_bf16 v[104:107], v[160:163], v[192:195], v[104:107]
	v_mfma_f32_16x16x32_bf16 v[92:95], v[144:147], v[200:203], v[92:95]
	v_mfma_f32_16x16x32_bf16 v[88:91], v[160:163], v[200:203], v[88:91]
	v_mfma_f32_16x16x32_bf16 v[76:79], v[144:147], v[212:215], v[76:79]
	v_mfma_f32_16x16x32_bf16 v[72:75], v[160:163], v[212:215], v[72:75]
	v_mfma_f32_16x16x32_bf16 v[124:127], v[156:159], v[188:191], v[124:127]
	v_mfma_f32_16x16x32_bf16 v[120:123], v[164:167], v[188:191], v[120:123]
	v_mfma_f32_16x16x32_bf16 v[108:111], v[156:159], v[196:199], v[108:111]
	v_mfma_f32_16x16x32_bf16 v[104:107], v[164:167], v[196:199], v[104:107]
	v_mfma_f32_16x16x32_bf16 v[92:95], v[156:159], v[208:211], v[92:95]
	v_mfma_f32_16x16x32_bf16 v[88:91], v[164:167], v[208:211], v[88:91]
	v_mfma_f32_16x16x32_bf16 v[76:79], v[156:159], v[216:219], v[76:79]
	v_mfma_f32_16x16x32_bf16 v[72:75], v[164:167], v[216:219], v[72:75]
	v_mfma_f32_16x16x32_bf16 v[116:119], v[168:171], v[184:187], v[116:119]
	v_mfma_f32_16x16x32_bf16 v[112:115], v[176:179], v[184:187], v[112:115]
	v_mfma_f32_16x16x32_bf16 v[100:103], v[168:171], v[192:195], v[100:103]
	v_mfma_f32_16x16x32_bf16 v[96:99], v[176:179], v[192:195], v[96:99]
	v_mfma_f32_16x16x32_bf16 v[84:87], v[168:171], v[200:203], v[84:87]
	v_mfma_f32_16x16x32_bf16 v[80:83], v[176:179], v[200:203], v[80:83]
	v_mfma_f32_16x16x32_bf16 v[68:71], v[168:171], v[212:215], v[68:71]
	v_mfma_f32_16x16x32_bf16 v[64:67], v[176:179], v[212:215], v[64:67]
	v_mfma_f32_16x16x32_bf16 v[116:119], v[172:175], v[188:191], v[116:119]
	v_mfma_f32_16x16x32_bf16 v[112:115], v[180:183], v[188:191], v[112:115]
	v_mfma_f32_16x16x32_bf16 v[100:103], v[172:175], v[196:199], v[100:103]
	v_mfma_f32_16x16x32_bf16 v[96:99], v[180:183], v[196:199], v[96:99]
	v_mfma_f32_16x16x32_bf16 v[84:87], v[172:175], v[208:211], v[84:87]
	v_mfma_f32_16x16x32_bf16 v[80:83], v[180:183], v[208:211], v[80:83]
	v_mfma_f32_16x16x32_bf16 v[68:71], v[172:175], v[216:219], v[68:71]
	v_mfma_f32_16x16x32_bf16 v[64:67], v[180:183], v[216:219], v[64:67]
	s_barrier
	s_add_i32 s54, s45, s38
	s_mov_b32 m0, s54
	ds_read_b128 v[184:187], v153 offset:16384
	ds_read_b128 v[188:191], v153 offset:17408
	ds_read_b128 v[192:195], v153 offset:18432
	ds_read_b128 v[196:199], v153 offset:19456
	ds_read_b128 v[200:203], v153 offset:20480
	ds_read_b128 v[208:211], v153 offset:21504
	ds_read_b128 v[212:215], v153 offset:22528
	ds_read_b128 v[216:219], v153 offset:23552
	global_load_lds_dwordx4 v130, s[26:27]
	s_add_i32 m0, s54, 0x2000
	s_add_u32 s54, s26, 0x40000
	s_mov_b64 s[98:99], s[26:27]
	s_addc_u32 s55, s27, 0
	s_add_i32 s56, s46, s38
	global_load_lds_dwordx4 v134, s[26:27]
	s_mov_b32 m0, s56
	s_mov_b64 s[100:101], s[28:29]
	global_load_lds_dwordx4 v130, s[54:55]
	s_add_i32 m0, s56, 0x2000
	s_nop 0
	global_load_lds_dwordx4 v134, s[54:55]
	s_waitcnt vmcnt(6)
	s_waitcnt lgkmcnt(0)
	s_barrier
	s_waitcnt lgkmcnt(0)
	v_mfma_f32_16x16x32_bf16 v[60:63], v[144:147], v[184:187], v[60:63]
	v_mfma_f32_16x16x32_bf16 v[56:59], v[160:163], v[184:187], v[56:59]
	v_mfma_f32_16x16x32_bf16 v[44:47], v[144:147], v[192:195], v[44:47]
	v_mfma_f32_16x16x32_bf16 v[40:43], v[160:163], v[192:195], v[40:43]
	v_mfma_f32_16x16x32_bf16 v[28:31], v[144:147], v[200:203], v[28:31]
	v_mfma_f32_16x16x32_bf16 v[24:27], v[160:163], v[200:203], v[24:27]
	v_mfma_f32_16x16x32_bf16 v[12:15], v[144:147], v[212:215], v[12:15]
	v_mfma_f32_16x16x32_bf16 v[8:11], v[160:163], v[212:215], v[8:11]
	v_mfma_f32_16x16x32_bf16 v[60:63], v[156:159], v[188:191], v[60:63]
	v_mfma_f32_16x16x32_bf16 v[56:59], v[164:167], v[188:191], v[56:59]
	v_mfma_f32_16x16x32_bf16 v[44:47], v[156:159], v[196:199], v[44:47]
	v_mfma_f32_16x16x32_bf16 v[40:43], v[164:167], v[196:199], v[40:43]
	v_mfma_f32_16x16x32_bf16 v[28:31], v[156:159], v[208:211], v[28:31]
	v_mfma_f32_16x16x32_bf16 v[24:27], v[164:167], v[208:211], v[24:27]
	v_mfma_f32_16x16x32_bf16 v[12:15], v[156:159], v[216:219], v[12:15]
	v_mfma_f32_16x16x32_bf16 v[8:11], v[164:167], v[216:219], v[8:11]
	v_mfma_f32_16x16x32_bf16 v[52:55], v[168:171], v[184:187], v[52:55]
	v_mfma_f32_16x16x32_bf16 v[48:51], v[176:179], v[184:187], v[48:51]
	v_mfma_f32_16x16x32_bf16 v[36:39], v[168:171], v[192:195], v[36:39]
	v_mfma_f32_16x16x32_bf16 v[32:35], v[176:179], v[192:195], v[32:35]
	v_mfma_f32_16x16x32_bf16 v[20:23], v[168:171], v[200:203], v[20:23]
	v_mfma_f32_16x16x32_bf16 v[16:19], v[176:179], v[200:203], v[16:19]
	v_mfma_f32_16x16x32_bf16 v[4:7], v[168:171], v[212:215], v[4:7]
	v_mfma_f32_16x16x32_bf16 v[0:3], v[176:179], v[212:215], v[0:3]
	v_mfma_f32_16x16x32_bf16 v[52:55], v[172:175], v[188:191], v[52:55]
	v_mfma_f32_16x16x32_bf16 v[48:51], v[180:183], v[188:191], v[48:51]
	v_mfma_f32_16x16x32_bf16 v[36:39], v[172:175], v[196:199], v[36:39]
	v_mfma_f32_16x16x32_bf16 v[32:35], v[180:183], v[196:199], v[32:35]
	v_mfma_f32_16x16x32_bf16 v[20:23], v[172:175], v[208:211], v[20:23]
	v_mfma_f32_16x16x32_bf16 v[16:19], v[180:183], v[208:211], v[16:19]
	v_mfma_f32_16x16x32_bf16 v[4:7], v[172:175], v[216:219], v[4:7]
	v_mfma_f32_16x16x32_bf16 v[0:3], v[180:183], v[216:219], v[0:3]
	s_barrier
	s_mov_b32 m0, s25
	s_nop 0
	global_load_lds_dwordx4 v128, s[28:29]
	s_mov_b32 m0, s39
	s_nop 0
	global_load_lds_dwordx4 v132, s[28:29]
	s_add_i32 s54, 0, 0x18000
	v_add_u32_e32 v155, s54, v149
	s_add_i32 s55, 0, 0x1c000
	ds_read_b128 v[144:147], v155
	ds_read_b128 v[156:159], v155 offset:1024
	ds_read_b128 v[160:163], v155 offset:2048
	ds_read_b128 v[164:167], v155 offset:3072
	v_add_u32_e32 v155, s55, v149
	ds_read_b128 v[168:171], v155
	ds_read_b128 v[172:175], v155 offset:1024
	ds_read_b128 v[176:179], v155 offset:2048
	ds_read_b128 v[180:183], v155 offset:3072
	s_add_u32 s28, s28, 0x40000
	s_addc_u32 s29, s29, 0
	s_mov_b32 m0, s40
	ds_read_b128 v[184:187], v153 offset:32768
	ds_read_b128 v[188:191], v153 offset:33792
	ds_read_b128 v[192:195], v153 offset:34816
	ds_read_b128 v[196:199], v153 offset:35840
	ds_read_b128 v[200:203], v153 offset:36864
	ds_read_b128 v[208:211], v153 offset:37888
	ds_read_b128 v[212:215], v153 offset:38912
	ds_read_b128 v[216:219], v153 offset:39936
	global_load_lds_dwordx4 v128, s[28:29]
	s_mov_b32 m0, s41
	s_nop 0
	global_load_lds_dwordx4 v132, s[28:29]
	s_waitcnt vmcnt(8)
	s_waitcnt lgkmcnt(0)
	s_barrier
	s_waitcnt lgkmcnt(0)
	v_mfma_f32_16x16x32_bf16 v[124:127], v[144:147], v[184:187], v[124:127]
	v_mfma_f32_16x16x32_bf16 v[120:123], v[160:163], v[184:187], v[120:123]
	v_mfma_f32_16x16x32_bf16 v[108:111], v[144:147], v[192:195], v[108:111]
	v_mfma_f32_16x16x32_bf16 v[104:107], v[160:163], v[192:195], v[104:107]
	v_mfma_f32_16x16x32_bf16 v[92:95], v[144:147], v[200:203], v[92:95]
	v_mfma_f32_16x16x32_bf16 v[88:91], v[160:163], v[200:203], v[88:91]
	v_mfma_f32_16x16x32_bf16 v[76:79], v[144:147], v[212:215], v[76:79]
	v_mfma_f32_16x16x32_bf16 v[72:75], v[160:163], v[212:215], v[72:75]
	v_mfma_f32_16x16x32_bf16 v[124:127], v[156:159], v[188:191], v[124:127]
	v_mfma_f32_16x16x32_bf16 v[120:123], v[164:167], v[188:191], v[120:123]
	v_mfma_f32_16x16x32_bf16 v[108:111], v[156:159], v[196:199], v[108:111]
	v_mfma_f32_16x16x32_bf16 v[104:107], v[164:167], v[196:199], v[104:107]
	v_mfma_f32_16x16x32_bf16 v[92:95], v[156:159], v[208:211], v[92:95]
	v_mfma_f32_16x16x32_bf16 v[88:91], v[164:167], v[208:211], v[88:91]
	v_mfma_f32_16x16x32_bf16 v[76:79], v[156:159], v[216:219], v[76:79]
	v_mfma_f32_16x16x32_bf16 v[72:75], v[164:167], v[216:219], v[72:75]
	v_mfma_f32_16x16x32_bf16 v[116:119], v[168:171], v[184:187], v[116:119]
	v_mfma_f32_16x16x32_bf16 v[112:115], v[176:179], v[184:187], v[112:115]
	v_mfma_f32_16x16x32_bf16 v[100:103], v[168:171], v[192:195], v[100:103]
	v_mfma_f32_16x16x32_bf16 v[96:99], v[176:179], v[192:195], v[96:99]
	v_mfma_f32_16x16x32_bf16 v[84:87], v[168:171], v[200:203], v[84:87]
	v_mfma_f32_16x16x32_bf16 v[80:83], v[176:179], v[200:203], v[80:83]
	v_mfma_f32_16x16x32_bf16 v[68:71], v[168:171], v[212:215], v[68:71]
	v_mfma_f32_16x16x32_bf16 v[64:67], v[176:179], v[212:215], v[64:67]
	v_mfma_f32_16x16x32_bf16 v[116:119], v[172:175], v[188:191], v[116:119]
	v_mfma_f32_16x16x32_bf16 v[112:115], v[180:183], v[188:191], v[112:115]
	v_mfma_f32_16x16x32_bf16 v[100:103], v[172:175], v[196:199], v[100:103]
	v_mfma_f32_16x16x32_bf16 v[96:99], v[180:183], v[196:199], v[96:99]
	v_mfma_f32_16x16x32_bf16 v[84:87], v[172:175], v[208:211], v[84:87]
	v_mfma_f32_16x16x32_bf16 v[80:83], v[180:183], v[208:211], v[80:83]
	v_mfma_f32_16x16x32_bf16 v[68:71], v[172:175], v[216:219], v[68:71]
	v_mfma_f32_16x16x32_bf16 v[64:67], v[180:183], v[216:219], v[64:67]
	s_barrier
	s_add_i32 s28, s54, s38
	s_mov_b32 m0, s28
	ds_read_b128 v[184:187], v153 offset:49152
	ds_read_b128 v[188:191], v153 offset:50176
	ds_read_b128 v[192:195], v153 offset:51200
	ds_read_b128 v[196:199], v153 offset:52224
	ds_read_b128 v[200:203], v153 offset:53248
	ds_read_b128 v[208:211], v153 offset:54272
	ds_read_b128 v[212:215], v153 offset:55296
	ds_read_b128 v[216:219], v153 offset:56320
	global_load_lds_dwordx4 v205, s[26:27]
	s_add_i32 m0, s28, 0x2000
	s_add_u32 s26, s26, 0x40080
	s_addc_u32 s27, s27, 0
	s_add_i32 s28, s55, s38
	global_load_lds_dwordx4 v221, s[98:99]
	s_mov_b32 m0, s28
	s_nop 0
	global_load_lds_dwordx4 v130, s[26:27]
	s_add_i32 m0, s28, 0x2000
	s_nop 0
	global_load_lds_dwordx4 v134, s[26:27]
	s_cmp_lg_u32 s53, 12
	s_cbranch_scc1 .Lbal_last_16
	s_mov_b32 m0, s43
	s_nop 0
	global_load_lds_dwordx4 v204, s[100:101]
	s_mov_b32 m0, s44
	s_nop 0
	global_load_lds_dwordx4 v220, s[100:101]
.Lbal_last_16:
	s_waitcnt vmcnt(6)
	s_waitcnt lgkmcnt(0)
	s_barrier
	s_waitcnt lgkmcnt(0)
	v_mfma_f32_16x16x32_bf16 v[60:63], v[144:147], v[184:187], v[60:63]
	v_mfma_f32_16x16x32_bf16 v[56:59], v[160:163], v[184:187], v[56:59]
	v_mfma_f32_16x16x32_bf16 v[44:47], v[144:147], v[192:195], v[44:47]
	v_mfma_f32_16x16x32_bf16 v[40:43], v[160:163], v[192:195], v[40:43]
	v_mfma_f32_16x16x32_bf16 v[28:31], v[144:147], v[200:203], v[28:31]
	v_mfma_f32_16x16x32_bf16 v[24:27], v[160:163], v[200:203], v[24:27]
	v_mfma_f32_16x16x32_bf16 v[12:15], v[144:147], v[212:215], v[12:15]
	v_mfma_f32_16x16x32_bf16 v[8:11], v[160:163], v[212:215], v[8:11]
	v_mfma_f32_16x16x32_bf16 v[60:63], v[156:159], v[188:191], v[60:63]
	v_mfma_f32_16x16x32_bf16 v[56:59], v[164:167], v[188:191], v[56:59]
	v_mfma_f32_16x16x32_bf16 v[44:47], v[156:159], v[196:199], v[44:47]
	v_mfma_f32_16x16x32_bf16 v[40:43], v[164:167], v[196:199], v[40:43]
	v_mfma_f32_16x16x32_bf16 v[28:31], v[156:159], v[208:211], v[28:31]
	v_mfma_f32_16x16x32_bf16 v[24:27], v[164:167], v[208:211], v[24:27]
	v_mfma_f32_16x16x32_bf16 v[12:15], v[156:159], v[216:219], v[12:15]
	v_mfma_f32_16x16x32_bf16 v[8:11], v[164:167], v[216:219], v[8:11]
	v_mfma_f32_16x16x32_bf16 v[52:55], v[168:171], v[184:187], v[52:55]
	v_mfma_f32_16x16x32_bf16 v[48:51], v[176:179], v[184:187], v[48:51]
	v_mfma_f32_16x16x32_bf16 v[36:39], v[168:171], v[192:195], v[36:39]
	v_mfma_f32_16x16x32_bf16 v[32:35], v[176:179], v[192:195], v[32:35]
	v_mfma_f32_16x16x32_bf16 v[20:23], v[168:171], v[200:203], v[20:23]
	v_mfma_f32_16x16x32_bf16 v[16:19], v[176:179], v[200:203], v[16:19]
	v_mfma_f32_16x16x32_bf16 v[4:7], v[168:171], v[212:215], v[4:7]
	v_mfma_f32_16x16x32_bf16 v[0:3], v[176:179], v[212:215], v[0:3]
	v_mfma_f32_16x16x32_bf16 v[52:55], v[172:175], v[188:191], v[52:55]
	v_mfma_f32_16x16x32_bf16 v[48:51], v[180:183], v[188:191], v[48:51]
	v_mfma_f32_16x16x32_bf16 v[36:39], v[172:175], v[196:199], v[36:39]
	v_mfma_f32_16x16x32_bf16 v[32:35], v[180:183], v[196:199], v[32:35]
	v_mfma_f32_16x16x32_bf16 v[20:23], v[172:175], v[208:211], v[20:23]
	v_mfma_f32_16x16x32_bf16 v[16:19], v[180:183], v[208:211], v[16:19]
	v_mfma_f32_16x16x32_bf16 v[4:7], v[172:175], v[216:219], v[4:7]
	v_mfma_f32_16x16x32_bf16 v[0:3], v[180:183], v[216:219], v[0:3]
	s_barrier
	s_add_i32 s53, s53, 2
	s_add_u32 s51, s51, 0x100
	s_addc_u32 s52, s52, 0
	s_add_u32 s6, s6, 0x100
	s_addc_u32 s7, s7, 0
	s_cmp_gt_u32 s53, 13
	s_cbranch_scc0 .LBB0_988
	s_setprio 0
	s_and_b64 vcc, exec, s[14:15]
	s_cbranch_vccz .LBB0_991
	s_barrier

.LBB0_1193:
	s_cmp_eq_i32 s50, -2
	s_cbranch_scc1 .Lbal_first_15
	s_mov_b32 m0, s41
	s_nop 0
	global_load_lds_dwordx4 v216, s[100:101]
	s_mov_b32 m0, s42
	s_nop 0
	global_load_lds_dwordx4 v218, s[100:101]
.Lbal_first_15:
	ds_read_b128 v[144:147], v151
	ds_read_b128 v[154:157], v151 offset:1024
	ds_read_b128 v[158:161], v151 offset:2048
	ds_read_b128 v[162:165], v151 offset:3072
	ds_read_b128 v[166:169], v152
	ds_read_b128 v[170:173], v152 offset:1024
	ds_read_b128 v[174:177], v152 offset:2048
	ds_read_b128 v[178:181], v152 offset:3072
	s_add_u32 s26, s24, 0xfffe0080
	s_addc_u32 s27, s25, -1
	s_cmp_eq_u32 s50, 4
	s_cselect_b32 s29, s17, s27
	s_cselect_b32 s28, s46, s26
	s_cselect_b32 s27, s15, s49
	s_cselect_b32 s26, s47, s48
	s_add_i32 m0, s23, 0xc000
	ds_read_b128 v[182:185], v153
	ds_read_b128 v[186:189], v153 offset:1024
	ds_read_b128 v[190:193], v153 offset:2048
	ds_read_b128 v[194:197], v153 offset:3072
	ds_read_b128 v[198:201], v153 offset:4096
	ds_read_b128 v[202:205], v153 offset:5120
	ds_read_b128 v[208:211], v153 offset:6144
	ds_read_b128 v[212:215], v153 offset:7168
	global_load_lds_dwordx4 v138, s[24:25]
	s_add_i32 m0, s23, 0xe000
	s_nop 0
	global_load_lds_dwordx4 v136, s[24:25]
	s_waitcnt vmcnt(8)
	s_waitcnt lgkmcnt(0)
	s_barrier
	s_waitcnt lgkmcnt(0)
	v_mfma_f32_16x16x32_bf16 v[124:127], v[144:147], v[182:185], v[124:127]
	v_mfma_f32_16x16x32_bf16 v[120:123], v[158:161], v[182:185], v[120:123]
	v_mfma_f32_16x16x32_bf16 v[108:111], v[144:147], v[190:193], v[108:111]
	v_mfma_f32_16x16x32_bf16 v[104:107], v[158:161], v[190:193], v[104:107]
	v_mfma_f32_16x16x32_bf16 v[92:95], v[144:147], v[198:201], v[92:95]
	v_mfma_f32_16x16x32_bf16 v[88:91], v[158:161], v[198:201], v[88:91]
	v_mfma_f32_16x16x32_bf16 v[76:79], v[144:147], v[208:211], v[76:79]
	v_mfma_f32_16x16x32_bf16 v[72:75], v[158:161], v[208:211], v[72:75]
	v_mfma_f32_16x16x32_bf16 v[124:127], v[154:157], v[186:189], v[124:127]
	v_mfma_f32_16x16x32_bf16 v[120:123], v[162:165], v[186:189], v[120:123]
	v_mfma_f32_16x16x32_bf16 v[108:111], v[154:157], v[194:197], v[108:111]
	v_mfma_f32_16x16x32_bf16 v[104:107], v[162:165], v[194:197], v[104:107]
	v_mfma_f32_16x16x32_bf16 v[92:95], v[154:157], v[202:205], v[92:95]
	v_mfma_f32_16x16x32_bf16 v[88:91], v[162:165], v[202:205], v[88:91]
	v_mfma_f32_16x16x32_bf16 v[76:79], v[154:157], v[212:215], v[76:79]
	v_mfma_f32_16x16x32_bf16 v[72:75], v[162:165], v[212:215], v[72:75]
	v_mfma_f32_16x16x32_bf16 v[116:119], v[166:169], v[182:185], v[116:119]
	v_mfma_f32_16x16x32_bf16 v[112:115], v[174:177], v[182:185], v[112:115]
	v_mfma_f32_16x16x32_bf16 v[100:103], v[166:169], v[190:193], v[100:103]
	v_mfma_f32_16x16x32_bf16 v[96:99], v[174:177], v[190:193], v[96:99]
	v_mfma_f32_16x16x32_bf16 v[84:87], v[166:169], v[198:201], v[84:87]
	v_mfma_f32_16x16x32_bf16 v[80:83], v[174:177], v[198:201], v[80:83]
	v_mfma_f32_16x16x32_bf16 v[68:71], v[166:169], v[208:211], v[68:71]
	v_mfma_f32_16x16x32_bf16 v[64:67], v[174:177], v[208:211], v[64:67]
	v_mfma_f32_16x16x32_bf16 v[116:119], v[170:173], v[186:189], v[116:119]
	v_mfma_f32_16x16x32_bf16 v[112:115], v[178:181], v[186:189], v[112:115]
	v_mfma_f32_16x16x32_bf16 v[100:103], v[170:173], v[194:197], v[100:103]
	v_mfma_f32_16x16x32_bf16 v[96:99], v[178:181], v[194:197], v[96:99]
	v_mfma_f32_16x16x32_bf16 v[84:87], v[170:173], v[202:205], v[84:87]
	v_mfma_f32_16x16x32_bf16 v[80:83], v[178:181], v[202:205], v[80:83]
	v_mfma_f32_16x16x32_bf16 v[68:71], v[170:173], v[212:215], v[68:71]
	v_mfma_f32_16x16x32_bf16 v[64:67], v[178:181], v[212:215], v[64:67]
	s_barrier
	s_add_i32 s51, s43, s36
	s_mov_b32 m0, s51
	ds_read_b128 v[182:185], v153 offset:16384
	ds_read_b128 v[186:189], v153 offset:17408
	ds_read_b128 v[190:193], v153 offset:18432
	ds_read_b128 v[194:197], v153 offset:19456
	ds_read_b128 v[198:201], v153 offset:20480
	ds_read_b128 v[202:205], v153 offset:21504
	ds_read_b128 v[208:211], v153 offset:22528
	ds_read_b128 v[212:215], v153 offset:23552
	global_load_lds_dwordx4 v130, s[26:27]
	s_add_i32 m0, s51, 0x2000
	s_add_u32 s52, s26, 0x20000
	s_mov_b64 s[98:99], s[26:27]
	s_addc_u32 s53, s27, 0
	s_add_i32 s51, s44, s36
	global_load_lds_dwordx4 v134, s[26:27]
	s_mov_b32 m0, s51
	s_mov_b64 s[100:101], s[28:29]
	global_load_lds_dwordx4 v130, s[52:53]
	s_add_i32 m0, s51, 0x2000
	s_nop 0
	global_load_lds_dwordx4 v134, s[52:53]
	s_waitcnt vmcnt(6)
	s_waitcnt lgkmcnt(0)
	s_barrier
	s_waitcnt lgkmcnt(0)
	v_mfma_f32_16x16x32_bf16 v[60:63], v[144:147], v[182:185], v[60:63]
	v_mfma_f32_16x16x32_bf16 v[56:59], v[158:161], v[182:185], v[56:59]
	v_mfma_f32_16x16x32_bf16 v[44:47], v[144:147], v[190:193], v[44:47]
	v_mfma_f32_16x16x32_bf16 v[40:43], v[158:161], v[190:193], v[40:43]
	v_mfma_f32_16x16x32_bf16 v[28:31], v[144:147], v[198:201], v[28:31]
	v_mfma_f32_16x16x32_bf16 v[24:27], v[158:161], v[198:201], v[24:27]
	v_mfma_f32_16x16x32_bf16 v[12:15], v[144:147], v[208:211], v[12:15]
	v_mfma_f32_16x16x32_bf16 v[8:11], v[158:161], v[208:211], v[8:11]
	v_mfma_f32_16x16x32_bf16 v[60:63], v[154:157], v[186:189], v[60:63]
	v_mfma_f32_16x16x32_bf16 v[56:59], v[162:165], v[186:189], v[56:59]
	v_mfma_f32_16x16x32_bf16 v[44:47], v[154:157], v[194:197], v[44:47]
	v_mfma_f32_16x16x32_bf16 v[40:43], v[162:165], v[194:197], v[40:43]
	v_mfma_f32_16x16x32_bf16 v[28:31], v[154:157], v[202:205], v[28:31]
	v_mfma_f32_16x16x32_bf16 v[24:27], v[162:165], v[202:205], v[24:27]
	v_mfma_f32_16x16x32_bf16 v[12:15], v[154:157], v[212:215], v[12:15]
	v_mfma_f32_16x16x32_bf16 v[8:11], v[162:165], v[212:215], v[8:11]
	v_mfma_f32_16x16x32_bf16 v[52:55], v[166:169], v[182:185], v[52:55]
	v_mfma_f32_16x16x32_bf16 v[48:51], v[174:177], v[182:185], v[48:51]
	v_mfma_f32_16x16x32_bf16 v[36:39], v[166:169], v[190:193], v[36:39]
	v_mfma_f32_16x16x32_bf16 v[32:35], v[174:177], v[190:193], v[32:35]
	v_mfma_f32_16x16x32_bf16 v[20:23], v[166:169], v[198:201], v[20:23]
	v_mfma_f32_16x16x32_bf16 v[16:19], v[174:177], v[198:201], v[16:19]
	v_mfma_f32_16x16x32_bf16 v[4:7], v[166:169], v[208:211], v[4:7]
	v_mfma_f32_16x16x32_bf16 v[0:3], v[174:177], v[208:211], v[0:3]
	v_mfma_f32_16x16x32_bf16 v[52:55], v[170:173], v[186:189], v[52:55]
	v_mfma_f32_16x16x32_bf16 v[48:51], v[178:181], v[186:189], v[48:51]
	v_mfma_f32_16x16x32_bf16 v[36:39], v[170:173], v[194:197], v[36:39]
	v_mfma_f32_16x16x32_bf16 v[32:35], v[178:181], v[194:197], v[32:35]
	v_mfma_f32_16x16x32_bf16 v[20:23], v[170:173], v[202:205], v[20:23]
	v_mfma_f32_16x16x32_bf16 v[16:19], v[178:181], v[202:205], v[16:19]
	v_mfma_f32_16x16x32_bf16 v[4:7], v[170:173], v[212:215], v[4:7]
	v_mfma_f32_16x16x32_bf16 v[0:3], v[178:181], v[212:215], v[0:3]
	s_barrier
	s_mov_b32 m0, s23
	s_nop 0
	global_load_lds_dwordx4 v128, s[28:29]
	s_mov_b32 m0, s37
	s_nop 0
	global_load_lds_dwordx4 v132, s[28:29]
	s_add_i32 s51, 0, 0x18000
	s_add_i32 s52, 0, 0x1c000
	v_add_u32_e32 v162, s51, v149
	v_add_u32_e32 v178, s52, v149
	ds_read_b128 v[144:147], v162
	ds_read_b128 v[154:157], v162 offset:1024
	ds_read_b128 v[158:161], v162 offset:2048
	ds_read_b128 v[162:165], v162 offset:3072
	ds_read_b128 v[166:169], v178
	ds_read_b128 v[170:173], v178 offset:1024
	ds_read_b128 v[174:177], v178 offset:2048
	ds_read_b128 v[178:181], v178 offset:3072
	s_add_u32 s28, s28, 0x20000
	s_addc_u32 s29, s29, 0
	s_mov_b32 m0, s38
	ds_read_b128 v[182:185], v153 offset:32768
	ds_read_b128 v[186:189], v153 offset:33792
	ds_read_b128 v[190:193], v153 offset:34816
	ds_read_b128 v[194:197], v153 offset:35840
	ds_read_b128 v[198:201], v153 offset:36864
	ds_read_b128 v[202:205], v153 offset:37888
	ds_read_b128 v[208:211], v153 offset:38912
	ds_read_b128 v[212:215], v153 offset:39936
	global_load_lds_dwordx4 v128, s[28:29]
	s_mov_b32 m0, s39
	s_nop 0
	global_load_lds_dwordx4 v132, s[28:29]
	s_waitcnt vmcnt(8)
	s_waitcnt lgkmcnt(0)
	s_barrier
	s_waitcnt lgkmcnt(0)
	v_mfma_f32_16x16x32_bf16 v[124:127], v[144:147], v[182:185], v[124:127]
	v_mfma_f32_16x16x32_bf16 v[120:123], v[158:161], v[182:185], v[120:123]
	v_mfma_f32_16x16x32_bf16 v[108:111], v[144:147], v[190:193], v[108:111]
	v_mfma_f32_16x16x32_bf16 v[104:107], v[158:161], v[190:193], v[104:107]
	v_mfma_f32_16x16x32_bf16 v[92:95], v[144:147], v[198:201], v[92:95]
	v_mfma_f32_16x16x32_bf16 v[88:91], v[158:161], v[198:201], v[88:91]
	v_mfma_f32_16x16x32_bf16 v[76:79], v[144:147], v[208:211], v[76:79]
	v_mfma_f32_16x16x32_bf16 v[72:75], v[158:161], v[208:211], v[72:75]
	v_mfma_f32_16x16x32_bf16 v[124:127], v[154:157], v[186:189], v[124:127]
	v_mfma_f32_16x16x32_bf16 v[120:123], v[162:165], v[186:189], v[120:123]
	v_mfma_f32_16x16x32_bf16 v[108:111], v[154:157], v[194:197], v[108:111]
	v_mfma_f32_16x16x32_bf16 v[104:107], v[162:165], v[194:197], v[104:107]
	v_mfma_f32_16x16x32_bf16 v[92:95], v[154:157], v[202:205], v[92:95]
	v_mfma_f32_16x16x32_bf16 v[88:91], v[162:165], v[202:205], v[88:91]
	v_mfma_f32_16x16x32_bf16 v[76:79], v[154:157], v[212:215], v[76:79]
	v_mfma_f32_16x16x32_bf16 v[72:75], v[162:165], v[212:215], v[72:75]
	v_mfma_f32_16x16x32_bf16 v[116:119], v[166:169], v[182:185], v[116:119]
	v_mfma_f32_16x16x32_bf16 v[112:115], v[174:177], v[182:185], v[112:115]
	v_mfma_f32_16x16x32_bf16 v[100:103], v[166:169], v[190:193], v[100:103]
	v_mfma_f32_16x16x32_bf16 v[96:99], v[174:177], v[190:193], v[96:99]
	v_mfma_f32_16x16x32_bf16 v[84:87], v[166:169], v[198:201], v[84:87]
	v_mfma_f32_16x16x32_bf16 v[80:83], v[174:177], v[198:201], v[80:83]
	v_mfma_f32_16x16x32_bf16 v[68:71], v[166:169], v[208:211], v[68:71]
	v_mfma_f32_16x16x32_bf16 v[64:67], v[174:177], v[208:211], v[64:67]
	v_mfma_f32_16x16x32_bf16 v[116:119], v[170:173], v[186:189], v[116:119]
	v_mfma_f32_16x16x32_bf16 v[112:115], v[178:181], v[186:189], v[112:115]
	v_mfma_f32_16x16x32_bf16 v[100:103], v[170:173], v[194:197], v[100:103]
	v_mfma_f32_16x16x32_bf16 v[96:99], v[178:181], v[194:197], v[96:99]
	v_mfma_f32_16x16x32_bf16 v[84:87], v[170:173], v[202:205], v[84:87]
	v_mfma_f32_16x16x32_bf16 v[80:83], v[178:181], v[202:205], v[80:83]
	v_mfma_f32_16x16x32_bf16 v[68:71], v[170:173], v[212:215], v[68:71]
	v_mfma_f32_16x16x32_bf16 v[64:67], v[178:181], v[212:215], v[64:67]
	s_barrier
	s_add_i32 s28, s51, s36
	s_mov_b32 m0, s28
	ds_read_b128 v[182:185], v153 offset:49152
	ds_read_b128 v[186:189], v153 offset:50176
	ds_read_b128 v[190:193], v153 offset:51200
	ds_read_b128 v[194:197], v153 offset:52224
	ds_read_b128 v[198:201], v153 offset:53248
	ds_read_b128 v[202:205], v153 offset:54272
	ds_read_b128 v[208:211], v153 offset:55296
	ds_read_b128 v[212:215], v153 offset:56320
	global_load_lds_dwordx4 v217, s[26:27]
	s_add_i32 m0, s28, 0x2000
	s_add_u32 s26, s26, 0x20080
	s_addc_u32 s27, s27, 0
	s_add_i32 s28, s52, s36
	global_load_lds_dwordx4 v219, s[98:99]
	s_mov_b32 m0, s28
	s_nop 0
	global_load_lds_dwordx4 v130, s[26:27]
	s_add_i32 m0, s28, 0x2000
	s_nop 0
	global_load_lds_dwordx4 v134, s[26:27]
	s_cmp_lg_u32 s50, 4
	s_cbranch_scc1 .Lbal_last_15
	s_mov_b32 m0, s41
	s_nop 0
	global_load_lds_dwordx4 v216, s[100:101]
	s_mov_b32 m0, s42
	s_nop 0
	global_load_lds_dwordx4 v218, s[100:101]
.Lbal_last_15:
	s_waitcnt vmcnt(6)
	s_waitcnt lgkmcnt(0)
	s_barrier
	s_waitcnt lgkmcnt(0)
	v_mfma_f32_16x16x32_bf16 v[60:63], v[144:147], v[182:185], v[60:63]
	v_mfma_f32_16x16x32_bf16 v[56:59], v[158:161], v[182:185], v[56:59]
	v_mfma_f32_16x16x32_bf16 v[44:47], v[144:147], v[190:193], v[44:47]
	v_mfma_f32_16x16x32_bf16 v[40:43], v[158:161], v[190:193], v[40:43]
	v_mfma_f32_16x16x32_bf16 v[28:31], v[144:147], v[198:201], v[28:31]
	v_mfma_f32_16x16x32_bf16 v[24:27], v[158:161], v[198:201], v[24:27]
	v_mfma_f32_16x16x32_bf16 v[12:15], v[144:147], v[208:211], v[12:15]
	v_mfma_f32_16x16x32_bf16 v[8:11], v[158:161], v[208:211], v[8:11]
	v_mfma_f32_16x16x32_bf16 v[60:63], v[154:157], v[186:189], v[60:63]
	v_mfma_f32_16x16x32_bf16 v[56:59], v[162:165], v[186:189], v[56:59]
	v_mfma_f32_16x16x32_bf16 v[44:47], v[154:157], v[194:197], v[44:47]
	v_mfma_f32_16x16x32_bf16 v[40:43], v[162:165], v[194:197], v[40:43]
	v_mfma_f32_16x16x32_bf16 v[28:31], v[154:157], v[202:205], v[28:31]
	v_mfma_f32_16x16x32_bf16 v[24:27], v[162:165], v[202:205], v[24:27]
	v_mfma_f32_16x16x32_bf16 v[12:15], v[154:157], v[212:215], v[12:15]
	v_mfma_f32_16x16x32_bf16 v[8:11], v[162:165], v[212:215], v[8:11]
	v_mfma_f32_16x16x32_bf16 v[52:55], v[166:169], v[182:185], v[52:55]
	v_mfma_f32_16x16x32_bf16 v[48:51], v[174:177], v[182:185], v[48:51]
	v_mfma_f32_16x16x32_bf16 v[36:39], v[166:169], v[190:193], v[36:39]
	v_mfma_f32_16x16x32_bf16 v[32:35], v[174:177], v[190:193], v[32:35]
	v_mfma_f32_16x16x32_bf16 v[20:23], v[166:169], v[198:201], v[20:23]
	v_mfma_f32_16x16x32_bf16 v[16:19], v[174:177], v[198:201], v[16:19]
	v_mfma_f32_16x16x32_bf16 v[4:7], v[166:169], v[208:211], v[4:7]
	v_mfma_f32_16x16x32_bf16 v[0:3], v[174:177], v[208:211], v[0:3]
	v_mfma_f32_16x16x32_bf16 v[52:55], v[170:173], v[186:189], v[52:55]
	v_mfma_f32_16x16x32_bf16 v[48:51], v[178:181], v[186:189], v[48:51]
	v_mfma_f32_16x16x32_bf16 v[36:39], v[170:173], v[194:197], v[36:39]
	v_mfma_f32_16x16x32_bf16 v[32:35], v[178:181], v[194:197], v[32:35]
	v_mfma_f32_16x16x32_bf16 v[20:23], v[170:173], v[202:205], v[20:23]
	v_mfma_f32_16x16x32_bf16 v[16:19], v[178:181], v[202:205], v[16:19]
	v_mfma_f32_16x16x32_bf16 v[4:7], v[170:173], v[212:215], v[4:7]
	v_mfma_f32_16x16x32_bf16 v[0:3], v[178:181], v[212:215], v[0:3]
	s_barrier
	s_add_i32 s50, s50, 2
	s_add_u32 s48, s48, 0x100
	s_addc_u32 s49, s49, 0
	s_add_u32 s24, s24, 0x100
	s_addc_u32 s25, s25, 0
	s_cmp_gt_u32 s50, 5
	s_cbranch_scc0 .LBB0_1193
	s_setprio 0
	s_and_b64 vcc, exec, s[12:13]
	s_cbranch_vccz .LBB0_1196
	s_barrier

.Lbal_first_13:
	ds_read_b128 v[144:147], v151
	ds_read_b128 v[156:159], v151 offset:1024
	ds_read_b128 v[160:163], v151 offset:2048
	ds_read_b128 v[164:167], v151 offset:3072
	ds_read_b128 v[168:171], v152
	ds_read_b128 v[172:175], v152 offset:1024
	ds_read_b128 v[176:179], v152 offset:2048
	ds_read_b128 v[180:183], v152 offset:3072
	s_add_u32 s26, s24, 0xfffc0080
	s_addc_u32 s27, s25, -1
	s_cmp_eq_u32 s53, 12
	s_cselect_b32 s29, s19, s27
	s_cselect_b32 s28, s49, s26
	s_cselect_b32 s27, s17, s52
	s_cselect_b32 s26, s50, s51
	s_add_i32 m0, s39, 0xc000
	ds_read_b128 v[184:187], v153
	ds_read_b128 v[188:191], v153 offset:1024
	ds_read_b128 v[192:195], v153 offset:2048
	ds_read_b128 v[196:199], v153 offset:3072
	ds_read_b128 v[200:203], v153 offset:4096
	ds_read_b128 v[208:211], v153 offset:5120
	ds_read_b128 v[212:215], v153 offset:6144
	ds_read_b128 v[216:219], v153 offset:7168
	global_load_lds_dwordx4 v138, s[24:25]
	s_add_i32 m0, s39, 0xe000
	s_nop 0
	global_load_lds_dwordx4 v136, s[24:25]
	s_waitcnt vmcnt(8)
	s_waitcnt lgkmcnt(0)
	s_barrier
	s_waitcnt lgkmcnt(0)
	v_mfma_f32_16x16x32_bf16 v[124:127], v[144:147], v[184:187], v[124:127]
	v_mfma_f32_16x16x32_bf16 v[120:123], v[160:163], v[184:187], v[120:123]
	v_mfma_f32_16x16x32_bf16 v[108:111], v[144:147], v[192:195], v[108:111]
	v_mfma_f32_16x16x32_bf16 v[104:107], v[160:163], v[192:195], v[104:107]
	v_mfma_f32_16x16x32_bf16 v[92:95], v[144:147], v[200:203], v[92:95]
	v_mfma_f32_16x16x32_bf16 v[88:91], v[160:163], v[200:203], v[88:91]
	v_mfma_f32_16x16x32_bf16 v[76:79], v[144:147], v[212:215], v[76:79]
	v_mfma_f32_16x16x32_bf16 v[72:75], v[160:163], v[212:215], v[72:75]
	v_mfma_f32_16x16x32_bf16 v[124:127], v[156:159], v[188:191], v[124:127]
	v_mfma_f32_16x16x32_bf16 v[120:123], v[164:167], v[188:191], v[120:123]
	v_mfma_f32_16x16x32_bf16 v[108:111], v[156:159], v[196:199], v[108:111]
	v_mfma_f32_16x16x32_bf16 v[104:107], v[164:167], v[196:199], v[104:107]
	v_mfma_f32_16x16x32_bf16 v[92:95], v[156:159], v[208:211], v[92:95]
	v_mfma_f32_16x16x32_bf16 v[88:91], v[164:167], v[208:211], v[88:91]
	v_mfma_f32_16x16x32_bf16 v[76:79], v[156:159], v[216:219], v[76:79]
	v_mfma_f32_16x16x32_bf16 v[72:75], v[164:167], v[216:219], v[72:75]
	v_mfma_f32_16x16x32_bf16 v[116:119], v[168:171], v[184:187], v[116:119]
	v_mfma_f32_16x16x32_bf16 v[112:115], v[176:179], v[184:187], v[112:115]
	v_mfma_f32_16x16x32_bf16 v[100:103], v[168:171], v[192:195], v[100:103]
	v_mfma_f32_16x16x32_bf16 v[96:99], v[176:179], v[192:195], v[96:99]
	v_mfma_f32_16x16x32_bf16 v[84:87], v[168:171], v[200:203], v[84:87]
	v_mfma_f32_16x16x32_bf16 v[80:83], v[176:179], v[200:203], v[80:83]
	v_mfma_f32_16x16x32_bf16 v[68:71], v[168:171], v[212:215], v[68:71]
	v_mfma_f32_16x16x32_bf16 v[64:67], v[176:179], v[212:215], v[64:67]
	v_mfma_f32_16x16x32_bf16 v[116:119], v[172:175], v[188:191], v[116:119]
	v_mfma_f32_16x16x32_bf16 v[112:115], v[180:183], v[188:191], v[112:115]
	v_mfma_f32_16x16x32_bf16 v[100:103], v[172:175], v[196:199], v[100:103]
	v_mfma_f32_16x16x32_bf16 v[96:99], v[180:183], v[196:199], v[96:99]
	v_mfma_f32_16x16x32_bf16 v[84:87], v[172:175], v[208:211], v[84:87]
	v_mfma_f32_16x16x32_bf16 v[80:83], v[180:183], v[208:211], v[80:83]
	v_mfma_f32_16x16x32_bf16 v[68:71], v[172:175], v[216:219], v[68:71]
	v_mfma_f32_16x16x32_bf16 v[64:67], v[180:183], v[216:219], v[64:67]
	s_barrier
	s_add_i32 s54, s46, s38
	s_mov_b32 m0, s54
	ds_read_b128 v[184:187], v153 offset:16384
	ds_read_b128 v[188:191], v153 offset:17408
	ds_read_b128 v[192:195], v153 offset:18432
	ds_read_b128 v[196:199], v153 offset:19456
	ds_read_b128 v[200:203], v153 offset:20480
	ds_read_b128 v[208:211], v153 offset:21504
	ds_read_b128 v[212:215], v153 offset:22528
	ds_read_b128 v[216:219], v153 offset:23552
	global_load_lds_dwordx4 v130, s[26:27]
	s_add_i32 m0, s54, 0x2000
	s_add_u32 s54, s26, 0x40000
	s_mov_b64 s[98:99], s[26:27]
	s_addc_u32 s55, s27, 0
	s_add_i32 s56, s47, s38
	global_load_lds_dwordx4 v134, s[26:27]
	s_mov_b32 m0, s56
	s_mov_b64 s[100:101], s[28:29]
	global_load_lds_dwordx4 v130, s[54:55]
	s_add_i32 m0, s56, 0x2000
	s_nop 0
	global_load_lds_dwordx4 v134, s[54:55]
	s_waitcnt vmcnt(6)
	s_waitcnt lgkmcnt(0)
	s_barrier
	s_waitcnt lgkmcnt(0)
	v_mfma_f32_16x16x32_bf16 v[60:63], v[144:147], v[184:187], v[60:63]
	v_mfma_f32_16x16x32_bf16 v[56:59], v[160:163], v[184:187], v[56:59]
	v_mfma_f32_16x16x32_bf16 v[44:47], v[144:147], v[192:195], v[44:47]
	v_mfma_f32_16x16x32_bf16 v[40:43], v[160:163], v[192:195], v[40:43]
	v_mfma_f32_16x16x32_bf16 v[28:31], v[144:147], v[200:203], v[28:31]
	v_mfma_f32_16x16x32_bf16 v[24:27], v[160:163], v[200:203], v[24:27]
	v_mfma_f32_16x16x32_bf16 v[12:15], v[144:147], v[212:215], v[12:15]
	v_mfma_f32_16x16x32_bf16 v[8:11], v[160:163], v[212:215], v[8:11]
	v_mfma_f32_16x16x32_bf16 v[60:63], v[156:159], v[188:191], v[60:63]
	v_mfma_f32_16x16x32_bf16 v[56:59], v[164:167], v[188:191], v[56:59]
	v_mfma_f32_16x16x32_bf16 v[44:47], v[156:159], v[196:199], v[44:47]
	v_mfma_f32_16x16x32_bf16 v[40:43], v[164:167], v[196:199], v[40:43]
	v_mfma_f32_16x16x32_bf16 v[28:31], v[156:159], v[208:211], v[28:31]
	v_mfma_f32_16x16x32_bf16 v[24:27], v[164:167], v[208:211], v[24:27]
	v_mfma_f32_16x16x32_bf16 v[12:15], v[156:159], v[216:219], v[12:15]
	v_mfma_f32_16x16x32_bf16 v[8:11], v[164:167], v[216:219], v[8:11]
	v_mfma_f32_16x16x32_bf16 v[52:55], v[168:171], v[184:187], v[52:55]
	v_mfma_f32_16x16x32_bf16 v[48:51], v[176:179], v[184:187], v[48:51]
	v_mfma_f32_16x16x32_bf16 v[36:39], v[168:171], v[192:195], v[36:39]
	v_mfma_f32_16x16x32_bf16 v[32:35], v[176:179], v[192:195], v[32:35]
	v_mfma_f32_16x16x32_bf16 v[20:23], v[168:171], v[200:203], v[20:23]
	v_mfma_f32_16x16x32_bf16 v[16:19], v[176:179], v[200:203], v[16:19]
	v_mfma_f32_16x16x32_bf16 v[4:7], v[168:171], v[212:215], v[4:7]
	v_mfma_f32_16x16x32_bf16 v[0:3], v[176:179], v[212:215], v[0:3]
	v_mfma_f32_16x16x32_bf16 v[52:55], v[172:175], v[188:191], v[52:55]
	v_mfma_f32_16x16x32_bf16 v[48:51], v[180:183], v[188:191], v[48:51]
	v_mfma_f32_16x16x32_bf16 v[36:39], v[172:175], v[196:199], v[36:39]
	v_mfma_f32_16x16x32_bf16 v[32:35], v[180:183], v[196:199], v[32:35]
	v_mfma_f32_16x16x32_bf16 v[20:23], v[172:175], v[208:211], v[20:23]
	v_mfma_f32_16x16x32_bf16 v[16:19], v[180:183], v[208:211], v[16:19]
	v_mfma_f32_16x16x32_bf16 v[4:7], v[172:175], v[216:219], v[4:7]
	v_mfma_f32_16x16x32_bf16 v[0:3], v[180:183], v[216:219], v[0:3]
	s_barrier
	s_mov_b32 m0, s39
	s_nop 0
	global_load_lds_dwordx4 v128, s[28:29]
	s_mov_b32 m0, s40
	s_nop 0
	global_load_lds_dwordx4 v132, s[28:29]
	s_add_i32 s54, 0, 0x18000
	v_add_u32_e32 v155, s54, v149
	s_add_i32 s55, 0, 0x1c000
	ds_read_b128 v[144:147], v155
	ds_read_b128 v[156:159], v155 offset:1024
	ds_read_b128 v[160:163], v155 offset:2048
	ds_read_b128 v[164:167], v155 offset:3072
	v_add_u32_e32 v155, s55, v149
	ds_read_b128 v[168:171], v155
	ds_read_b128 v[172:175], v155 offset:1024
	ds_read_b128 v[176:179], v155 offset:2048
	ds_read_b128 v[180:183], v155 offset:3072
	s_add_u32 s28, s28, 0x40000
	s_addc_u32 s29, s29, 0
	s_mov_b32 m0, s41
	ds_read_b128 v[184:187], v153 offset:32768
	ds_read_b128 v[188:191], v153 offset:33792
	ds_read_b128 v[192:195], v153 offset:34816
	ds_read_b128 v[196:199], v153 offset:35840
	ds_read_b128 v[200:203], v153 offset:36864
	ds_read_b128 v[208:211], v153 offset:37888
	ds_read_b128 v[212:215], v153 offset:38912
	ds_read_b128 v[216:219], v153 offset:39936
	global_load_lds_dwordx4 v128, s[28:29]
	s_mov_b32 m0, s42
	s_nop 0
	global_load_lds_dwordx4 v132, s[28:29]
	s_waitcnt vmcnt(8)
	s_waitcnt lgkmcnt(0)
	s_barrier
	s_waitcnt lgkmcnt(0)
	v_mfma_f32_16x16x32_bf16 v[124:127], v[144:147], v[184:187], v[124:127]
	v_mfma_f32_16x16x32_bf16 v[120:123], v[160:163], v[184:187], v[120:123]
	v_mfma_f32_16x16x32_bf16 v[108:111], v[144:147], v[192:195], v[108:111]
	v_mfma_f32_16x16x32_bf16 v[104:107], v[160:163], v[192:195], v[104:107]
	v_mfma_f32_16x16x32_bf16 v[92:95], v[144:147], v[200:203], v[92:95]
	v_mfma_f32_16x16x32_bf16 v[88:91], v[160:163], v[200:203], v[88:91]
	v_mfma_f32_16x16x32_bf16 v[76:79], v[144:147], v[212:215], v[76:79]
	v_mfma_f32_16x16x32_bf16 v[72:75], v[160:163], v[212:215], v[72:75]
	v_mfma_f32_16x16x32_bf16 v[124:127], v[156:159], v[188:191], v[124:127]
	v_mfma_f32_16x16x32_bf16 v[120:123], v[164:167], v[188:191], v[120:123]
	v_mfma_f32_16x16x32_bf16 v[108:111], v[156:159], v[196:199], v[108:111]
	v_mfma_f32_16x16x32_bf16 v[104:107], v[164:167], v[196:199], v[104:107]
	v_mfma_f32_16x16x32_bf16 v[92:95], v[156:159], v[208:211], v[92:95]
	v_mfma_f32_16x16x32_bf16 v[88:91], v[164:167], v[208:211], v[88:91]
	v_mfma_f32_16x16x32_bf16 v[76:79], v[156:159], v[216:219], v[76:79]
	v_mfma_f32_16x16x32_bf16 v[72:75], v[164:167], v[216:219], v[72:75]
	v_mfma_f32_16x16x32_bf16 v[116:119], v[168:171], v[184:187], v[116:119]
	v_mfma_f32_16x16x32_bf16 v[112:115], v[176:179], v[184:187], v[112:115]
	v_mfma_f32_16x16x32_bf16 v[100:103], v[168:171], v[192:195], v[100:103]
	v_mfma_f32_16x16x32_bf16 v[96:99], v[176:179], v[192:195], v[96:99]
	v_mfma_f32_16x16x32_bf16 v[84:87], v[168:171], v[200:203], v[84:87]
	v_mfma_f32_16x16x32_bf16 v[80:83], v[176:179], v[200:203], v[80:83]
	v_mfma_f32_16x16x32_bf16 v[68:71], v[168:171], v[212:215], v[68:71]
	v_mfma_f32_16x16x32_bf16 v[64:67], v[176:179], v[212:215], v[64:67]
	v_mfma_f32_16x16x32_bf16 v[116:119], v[172:175], v[188:191], v[116:119]
	v_mfma_f32_16x16x32_bf16 v[112:115], v[180:183], v[188:191], v[112:115]
	v_mfma_f32_16x16x32_bf16 v[100:103], v[172:175], v[196:199], v[100:103]
	v_mfma_f32_16x16x32_bf16 v[96:99], v[180:183], v[196:199], v[96:99]
	v_mfma_f32_16x16x32_bf16 v[84:87], v[172:175], v[208:211], v[84:87]
	v_mfma_f32_16x16x32_bf16 v[80:83], v[180:183], v[208:211], v[80:83]
	v_mfma_f32_16x16x32_bf16 v[68:71], v[172:175], v[216:219], v[68:71]
	v_mfma_f32_16x16x32_bf16 v[64:67], v[180:183], v[216:219], v[64:67]
	s_barrier
	s_add_i32 s28, s54, s38
	s_mov_b32 m0, s28
	ds_read_b128 v[184:187], v153 offset:49152
	ds_read_b128 v[188:191], v153 offset:50176
	ds_read_b128 v[192:195], v153 offset:51200
	ds_read_b128 v[196:199], v153 offset:52224
	ds_read_b128 v[200:203], v153 offset:53248
	ds_read_b128 v[208:211], v153 offset:54272
	ds_read_b128 v[212:215], v153 offset:55296
	ds_read_b128 v[216:219], v153 offset:56320
	global_load_lds_dwordx4 v205, s[26:27]
	s_add_i32 m0, s28, 0x2000
	s_add_u32 s26, s26, 0x40080
	s_addc_u32 s27, s27, 0
	s_add_i32 s28, s55, s38
	global_load_lds_dwordx4 v221, s[98:99]
	s_mov_b32 m0, s28
	s_nop 0
	global_load_lds_dwordx4 v130, s[26:27]
	s_add_i32 m0, s28, 0x2000
	s_nop 0
	global_load_lds_dwordx4 v134, s[26:27]
	s_cmp_lg_u32 s53, 12
	s_cbranch_scc1 .Lbal_last_13
	s_mov_b32 m0, s44
	s_nop 0
	global_load_lds_dwordx4 v204, s[100:101]
	s_mov_b32 m0, s45
	s_nop 0
	global_load_lds_dwordx4 v220, s[100:101]
.Lbal_last_13:
	s_waitcnt vmcnt(6)
	s_waitcnt lgkmcnt(0)
	s_barrier
	s_waitcnt lgkmcnt(0)
	v_mfma_f32_16x16x32_bf16 v[60:63], v[144:147], v[184:187], v[60:63]
	v_mfma_f32_16x16x32_bf16 v[56:59], v[160:163], v[184:187], v[56:59]
	v_mfma_f32_16x16x32_bf16 v[44:47], v[144:147], v[192:195], v[44:47]
	v_mfma_f32_16x16x32_bf16 v[40:43], v[160:163], v[192:195], v[40:43]
	v_mfma_f32_16x16x32_bf16 v[28:31], v[144:147], v[200:203], v[28:31]
	v_mfma_f32_16x16x32_bf16 v[24:27], v[160:163], v[200:203], v[24:27]
	v_mfma_f32_16x16x32_bf16 v[12:15], v[144:147], v[212:215], v[12:15]
	v_mfma_f32_16x16x32_bf16 v[8:11], v[160:163], v[212:215], v[8:11]
	v_mfma_f32_16x16x32_bf16 v[60:63], v[156:159], v[188:191], v[60:63]
	v_mfma_f32_16x16x32_bf16 v[56:59], v[164:167], v[188:191], v[56:59]
	v_mfma_f32_16x16x32_bf16 v[44:47], v[156:159], v[196:199], v[44:47]
	v_mfma_f32_16x16x32_bf16 v[40:43], v[164:167], v[196:199], v[40:43]
	v_mfma_f32_16x16x32_bf16 v[28:31], v[156:159], v[208:211], v[28:31]
	v_mfma_f32_16x16x32_bf16 v[24:27], v[164:167], v[208:211], v[24:27]
	v_mfma_f32_16x16x32_bf16 v[12:15], v[156:159], v[216:219], v[12:15]
	v_mfma_f32_16x16x32_bf16 v[8:11], v[164:167], v[216:219], v[8:11]
	v_mfma_f32_16x16x32_bf16 v[52:55], v[168:171], v[184:187], v[52:55]
	v_mfma_f32_16x16x32_bf16 v[48:51], v[176:179], v[184:187], v[48:51]
	v_mfma_f32_16x16x32_bf16 v[36:39], v[168:171], v[192:195], v[36:39]
	v_mfma_f32_16x16x32_bf16 v[32:35], v[176:179], v[192:195], v[32:35]
	v_mfma_f32_16x16x32_bf16 v[20:23], v[168:171], v[200:203], v[20:23]
	v_mfma_f32_16x16x32_bf16 v[16:19], v[176:179], v[200:203], v[16:19]
	v_mfma_f32_16x16x32_bf16 v[4:7], v[168:171], v[212:215], v[4:7]
	v_mfma_f32_16x16x32_bf16 v[0:3], v[176:179], v[212:215], v[0:3]
	v_mfma_f32_16x16x32_bf16 v[52:55], v[172:175], v[188:191], v[52:55]
	v_mfma_f32_16x16x32_bf16 v[48:51], v[180:183], v[188:191], v[48:51]
	v_mfma_f32_16x16x32_bf16 v[36:39], v[172:175], v[196:199], v[36:39]
	v_mfma_f32_16x16x32_bf16 v[32:35], v[180:183], v[196:199], v[32:35]
	v_mfma_f32_16x16x32_bf16 v[20:23], v[172:175], v[208:211], v[20:23]
	v_mfma_f32_16x16x32_bf16 v[16:19], v[180:183], v[208:211], v[16:19]
	v_mfma_f32_16x16x32_bf16 v[4:7], v[172:175], v[216:219], v[4:7]
	v_mfma_f32_16x16x32_bf16 v[0:3], v[180:183], v[216:219], v[0:3]
	s_barrier
	s_add_i32 s53, s53, 2
	s_add_u32 s51, s51, 0x100
	s_addc_u32 s52, s52, 0
	s_add_u32 s24, s24, 0x100
	s_addc_u32 s25, s25, 0
	s_cmp_gt_u32 s53, 13
	s_cbranch_scc0 .LBB0_1365
	s_setprio 0
	s_and_b64 vcc, exec, s[14:15]
	s_cbranch_vccz .LBB0_1368
	s_barrier

.LBB0_1561:
	s_cmp_eq_i32 s61, -2
	s_cbranch_scc1 .Lbal_first_11
	s_mov_b32 m0, s51
	s_nop 0
	global_load_lds_dwordx4 v204, s[100:101]
	s_mov_b32 m0, s52
	s_nop 0
	global_load_lds_dwordx4 v205, s[100:101]
.Lbal_first_11:
	ds_read_b128 v[140:143], v151
	ds_read_b128 v[144:147], v151 offset:1024
	ds_read_b128 v[156:159], v151 offset:2048
	ds_read_b128 v[160:163], v151 offset:3072
	ds_read_b128 v[164:167], v152
	ds_read_b128 v[168:171], v152 offset:1024
	ds_read_b128 v[172:175], v152 offset:2048
	ds_read_b128 v[176:179], v152 offset:3072
	s_add_u32 s38, s36, 0xfffc0080
	s_addc_u32 s39, s37, -1
	s_cmp_eq_u32 s61, 12
	s_cselect_b32 s41, s3, s39
	s_cselect_b32 s40, s29, s38
	s_cselect_b32 s39, s27, s60
	s_cselect_b32 s38, s58, s59
	s_add_i32 m0, s46, 0xc000
	ds_read_b128 v[180:183], v153
	ds_read_b128 v[184:187], v153 offset:1024
	ds_read_b128 v[188:191], v153 offset:2048
	ds_read_b128 v[192:195], v153 offset:3072
	ds_read_b128 v[196:199], v153 offset:4096
	ds_read_b128 v[200:203], v153 offset:5120
	ds_read_b128 v[208:211], v153 offset:6144
	ds_read_b128 v[212:215], v153 offset:7168
	global_load_lds_dwordx4 v134, s[36:37]
	s_add_i32 m0, s46, 0xe000
	s_nop 0
	global_load_lds_dwordx4 v132, s[36:37]
	s_waitcnt vmcnt(8)
	s_waitcnt lgkmcnt(0)
	s_barrier
	s_waitcnt lgkmcnt(0)
	v_mfma_f32_16x16x32_bf16 v[124:127], v[140:143], v[180:183], v[124:127]
	v_mfma_f32_16x16x32_bf16 v[120:123], v[156:159], v[180:183], v[120:123]
	v_mfma_f32_16x16x32_bf16 v[108:111], v[140:143], v[188:191], v[108:111]
	v_mfma_f32_16x16x32_bf16 v[104:107], v[156:159], v[188:191], v[104:107]
	v_mfma_f32_16x16x32_bf16 v[92:95], v[140:143], v[196:199], v[92:95]
	v_mfma_f32_16x16x32_bf16 v[88:91], v[156:159], v[196:199], v[88:91]
	v_mfma_f32_16x16x32_bf16 v[76:79], v[140:143], v[208:211], v[76:79]
	v_mfma_f32_16x16x32_bf16 v[72:75], v[156:159], v[208:211], v[72:75]
	v_mfma_f32_16x16x32_bf16 v[124:127], v[144:147], v[184:187], v[124:127]
	v_mfma_f32_16x16x32_bf16 v[120:123], v[160:163], v[184:187], v[120:123]
	v_mfma_f32_16x16x32_bf16 v[108:111], v[144:147], v[192:195], v[108:111]
	v_mfma_f32_16x16x32_bf16 v[104:107], v[160:163], v[192:195], v[104:107]
	v_mfma_f32_16x16x32_bf16 v[92:95], v[144:147], v[200:203], v[92:95]
	v_mfma_f32_16x16x32_bf16 v[88:91], v[160:163], v[200:203], v[88:91]
	v_mfma_f32_16x16x32_bf16 v[76:79], v[144:147], v[212:215], v[76:79]
	v_mfma_f32_16x16x32_bf16 v[72:75], v[160:163], v[212:215], v[72:75]
	v_mfma_f32_16x16x32_bf16 v[116:119], v[164:167], v[180:183], v[116:119]
	v_mfma_f32_16x16x32_bf16 v[112:115], v[172:175], v[180:183], v[112:115]
	v_mfma_f32_16x16x32_bf16 v[100:103], v[164:167], v[188:191], v[100:103]
	v_mfma_f32_16x16x32_bf16 v[96:99], v[172:175], v[188:191], v[96:99]
	v_mfma_f32_16x16x32_bf16 v[84:87], v[164:167], v[196:199], v[84:87]
	v_mfma_f32_16x16x32_bf16 v[80:83], v[172:175], v[196:199], v[80:83]
	v_mfma_f32_16x16x32_bf16 v[68:71], v[164:167], v[208:211], v[68:71]
	v_mfma_f32_16x16x32_bf16 v[64:67], v[172:175], v[208:211], v[64:67]
	v_mfma_f32_16x16x32_bf16 v[116:119], v[168:171], v[184:187], v[116:119]
	v_mfma_f32_16x16x32_bf16 v[112:115], v[176:179], v[184:187], v[112:115]
	v_mfma_f32_16x16x32_bf16 v[100:103], v[168:171], v[192:195], v[100:103]
	v_mfma_f32_16x16x32_bf16 v[96:99], v[176:179], v[192:195], v[96:99]
	v_mfma_f32_16x16x32_bf16 v[84:87], v[168:171], v[200:203], v[84:87]
	v_mfma_f32_16x16x32_bf16 v[80:83], v[176:179], v[200:203], v[80:83]
	v_mfma_f32_16x16x32_bf16 v[68:71], v[168:171], v[212:215], v[68:71]
	v_mfma_f32_16x16x32_bf16 v[64:67], v[176:179], v[212:215], v[64:67]
	s_barrier
	s_add_i32 s62, s54, s45
	s_mov_b32 m0, s62
	ds_read_b128 v[180:183], v153 offset:16384
	ds_read_b128 v[184:187], v153 offset:17408
	ds_read_b128 v[188:191], v153 offset:18432
	ds_read_b128 v[192:195], v153 offset:19456
	ds_read_b128 v[196:199], v153 offset:20480
	ds_read_b128 v[200:203], v153 offset:21504
	ds_read_b128 v[208:211], v153 offset:22528
	ds_read_b128 v[212:215], v153 offset:23552
	global_load_lds_dwordx4 v128, s[38:39]
	s_add_i32 m0, s62, 0x2000
	s_add_u32 s62, s38, 0x40000
	s_mov_b64 s[98:99], s[38:39]
	s_addc_u32 s63, s39, 0
	s_add_i32 s64, s55, s45
	global_load_lds_dwordx4 v130, s[38:39]
	s_mov_b32 m0, s64
	s_mov_b64 s[100:101], s[40:41]
	global_load_lds_dwordx4 v128, s[62:63]
	s_add_i32 m0, s64, 0x2000
	s_nop 0
	global_load_lds_dwordx4 v130, s[62:63]
	s_waitcnt vmcnt(6)
	s_waitcnt lgkmcnt(0)
	s_barrier
	s_waitcnt lgkmcnt(0)
	v_mfma_f32_16x16x32_bf16 v[60:63], v[140:143], v[180:183], v[60:63]
	v_mfma_f32_16x16x32_bf16 v[56:59], v[156:159], v[180:183], v[56:59]
	v_mfma_f32_16x16x32_bf16 v[44:47], v[140:143], v[188:191], v[44:47]
	v_mfma_f32_16x16x32_bf16 v[40:43], v[156:159], v[188:191], v[40:43]
	v_mfma_f32_16x16x32_bf16 v[28:31], v[140:143], v[196:199], v[28:31]
	v_mfma_f32_16x16x32_bf16 v[24:27], v[156:159], v[196:199], v[24:27]
	v_mfma_f32_16x16x32_bf16 v[12:15], v[140:143], v[208:211], v[12:15]
	v_mfma_f32_16x16x32_bf16 v[8:11], v[156:159], v[208:211], v[8:11]
	v_mfma_f32_16x16x32_bf16 v[60:63], v[144:147], v[184:187], v[60:63]
	v_mfma_f32_16x16x32_bf16 v[56:59], v[160:163], v[184:187], v[56:59]
	v_mfma_f32_16x16x32_bf16 v[44:47], v[144:147], v[192:195], v[44:47]
	v_mfma_f32_16x16x32_bf16 v[40:43], v[160:163], v[192:195], v[40:43]
	v_mfma_f32_16x16x32_bf16 v[28:31], v[144:147], v[200:203], v[28:31]
	v_mfma_f32_16x16x32_bf16 v[24:27], v[160:163], v[200:203], v[24:27]
	v_mfma_f32_16x16x32_bf16 v[12:15], v[144:147], v[212:215], v[12:15]
	v_mfma_f32_16x16x32_bf16 v[8:11], v[160:163], v[212:215], v[8:11]
	v_mfma_f32_16x16x32_bf16 v[52:55], v[164:167], v[180:183], v[52:55]
	v_mfma_f32_16x16x32_bf16 v[48:51], v[172:175], v[180:183], v[48:51]
	v_mfma_f32_16x16x32_bf16 v[36:39], v[164:167], v[188:191], v[36:39]
	v_mfma_f32_16x16x32_bf16 v[32:35], v[172:175], v[188:191], v[32:35]
	v_mfma_f32_16x16x32_bf16 v[20:23], v[164:167], v[196:199], v[20:23]
	v_mfma_f32_16x16x32_bf16 v[16:19], v[172:175], v[196:199], v[16:19]
	v_mfma_f32_16x16x32_bf16 v[4:7], v[164:167], v[208:211], v[4:7]
	v_mfma_f32_16x16x32_bf16 v[0:3], v[172:175], v[208:211], v[0:3]
	v_mfma_f32_16x16x32_bf16 v[52:55], v[168:171], v[184:187], v[52:55]
	v_mfma_f32_16x16x32_bf16 v[48:51], v[176:179], v[184:187], v[48:51]
	v_mfma_f32_16x16x32_bf16 v[36:39], v[168:171], v[192:195], v[36:39]
	v_mfma_f32_16x16x32_bf16 v[32:35], v[176:179], v[192:195], v[32:35]
	v_mfma_f32_16x16x32_bf16 v[20:23], v[168:171], v[200:203], v[20:23]
	v_mfma_f32_16x16x32_bf16 v[16:19], v[176:179], v[200:203], v[16:19]
	v_mfma_f32_16x16x32_bf16 v[4:7], v[168:171], v[212:215], v[4:7]
	v_mfma_f32_16x16x32_bf16 v[0:3], v[176:179], v[212:215], v[0:3]
	s_barrier
	s_mov_b32 m0, s46
	s_nop 0
	global_load_lds_dwordx4 v128, s[40:41]
	s_mov_b32 m0, s47
	s_nop 0
	global_load_lds_dwordx4 v130, s[40:41]
	s_add_i32 s62, 0, 0x18000
	v_add_u32_e32 v155, s62, v149
	s_add_i32 s63, 0, 0x1c000
	ds_read_b128 v[140:143], v155
	ds_read_b128 v[144:147], v155 offset:1024
	ds_read_b128 v[156:159], v155 offset:2048
	ds_read_b128 v[160:163], v155 offset:3072
	v_add_u32_e32 v155, s63, v149
	ds_read_b128 v[164:167], v155
	ds_read_b128 v[168:171], v155 offset:1024
	ds_read_b128 v[172:175], v155 offset:2048
	ds_read_b128 v[176:179], v155 offset:3072
	s_add_u32 s40, s40, 0x40000
	s_addc_u32 s41, s41, 0
	s_mov_b32 m0, s48
	ds_read_b128 v[180:183], v153 offset:32768
	ds_read_b128 v[184:187], v153 offset:33792
	ds_read_b128 v[188:191], v153 offset:34816
	ds_read_b128 v[192:195], v153 offset:35840
	ds_read_b128 v[196:199], v153 offset:36864
	ds_read_b128 v[200:203], v153 offset:37888
	ds_read_b128 v[208:211], v153 offset:38912
	ds_read_b128 v[212:215], v153 offset:39936
	global_load_lds_dwordx4 v128, s[40:41]
	s_mov_b32 m0, s49
	s_nop 0
	global_load_lds_dwordx4 v130, s[40:41]
	s_waitcnt vmcnt(8)
	s_waitcnt lgkmcnt(0)
	s_barrier
	s_waitcnt lgkmcnt(0)
	v_mfma_f32_16x16x32_bf16 v[124:127], v[140:143], v[180:183], v[124:127]
	v_mfma_f32_16x16x32_bf16 v[120:123], v[156:159], v[180:183], v[120:123]
	v_mfma_f32_16x16x32_bf16 v[108:111], v[140:143], v[188:191], v[108:111]
	v_mfma_f32_16x16x32_bf16 v[104:107], v[156:159], v[188:191], v[104:107]
	v_mfma_f32_16x16x32_bf16 v[92:95], v[140:143], v[196:199], v[92:95]
	v_mfma_f32_16x16x32_bf16 v[88:91], v[156:159], v[196:199], v[88:91]
	v_mfma_f32_16x16x32_bf16 v[76:79], v[140:143], v[208:211], v[76:79]
	v_mfma_f32_16x16x32_bf16 v[72:75], v[156:159], v[208:211], v[72:75]
	v_mfma_f32_16x16x32_bf16 v[124:127], v[144:147], v[184:187], v[124:127]
	v_mfma_f32_16x16x32_bf16 v[120:123], v[160:163], v[184:187], v[120:123]
	v_mfma_f32_16x16x32_bf16 v[108:111], v[144:147], v[192:195], v[108:111]
	v_mfma_f32_16x16x32_bf16 v[104:107], v[160:163], v[192:195], v[104:107]
	v_mfma_f32_16x16x32_bf16 v[92:95], v[144:147], v[200:203], v[92:95]
	v_mfma_f32_16x16x32_bf16 v[88:91], v[160:163], v[200:203], v[88:91]
	v_mfma_f32_16x16x32_bf16 v[76:79], v[144:147], v[212:215], v[76:79]
	v_mfma_f32_16x16x32_bf16 v[72:75], v[160:163], v[212:215], v[72:75]
	v_mfma_f32_16x16x32_bf16 v[116:119], v[164:167], v[180:183], v[116:119]
	v_mfma_f32_16x16x32_bf16 v[112:115], v[172:175], v[180:183], v[112:115]
	v_mfma_f32_16x16x32_bf16 v[100:103], v[164:167], v[188:191], v[100:103]
	v_mfma_f32_16x16x32_bf16 v[96:99], v[172:175], v[188:191], v[96:99]
	v_mfma_f32_16x16x32_bf16 v[84:87], v[164:167], v[196:199], v[84:87]
	v_mfma_f32_16x16x32_bf16 v[80:83], v[172:175], v[196:199], v[80:83]
	v_mfma_f32_16x16x32_bf16 v[68:71], v[164:167], v[208:211], v[68:71]
	v_mfma_f32_16x16x32_bf16 v[64:67], v[172:175], v[208:211], v[64:67]
	v_mfma_f32_16x16x32_bf16 v[116:119], v[168:171], v[184:187], v[116:119]
	v_mfma_f32_16x16x32_bf16 v[112:115], v[176:179], v[184:187], v[112:115]
	v_mfma_f32_16x16x32_bf16 v[100:103], v[168:171], v[192:195], v[100:103]
	v_mfma_f32_16x16x32_bf16 v[96:99], v[176:179], v[192:195], v[96:99]
	v_mfma_f32_16x16x32_bf16 v[84:87], v[168:171], v[200:203], v[84:87]
	v_mfma_f32_16x16x32_bf16 v[80:83], v[176:179], v[200:203], v[80:83]
	v_mfma_f32_16x16x32_bf16 v[68:71], v[168:171], v[212:215], v[68:71]
	v_mfma_f32_16x16x32_bf16 v[64:67], v[176:179], v[212:215], v[64:67]
	s_barrier
	s_add_i32 s40, s62, s45
	s_mov_b32 m0, s40
	ds_read_b128 v[180:183], v153 offset:49152
	ds_read_b128 v[184:187], v153 offset:50176
	ds_read_b128 v[188:191], v153 offset:51200
	ds_read_b128 v[192:195], v153 offset:52224
	ds_read_b128 v[196:199], v153 offset:53248
	ds_read_b128 v[200:203], v153 offset:54272
	ds_read_b128 v[208:211], v153 offset:55296
	ds_read_b128 v[212:215], v153 offset:56320
	global_load_lds_dwordx4 v204, s[38:39]
	s_add_i32 m0, s40, 0x2000
	s_add_u32 s38, s38, 0x40080
	s_addc_u32 s39, s39, 0
	s_add_i32 s40, s63, s45
	global_load_lds_dwordx4 v205, s[98:99]
	s_mov_b32 m0, s40
	s_nop 0
	global_load_lds_dwordx4 v128, s[38:39]
	s_add_i32 m0, s40, 0x2000
	s_nop 0
	global_load_lds_dwordx4 v130, s[38:39]
	s_cmp_lg_u32 s61, 12
	s_cbranch_scc1 .Lbal_last_11
	s_mov_b32 m0, s51
	s_nop 0
	global_load_lds_dwordx4 v204, s[100:101]
	s_mov_b32 m0, s52
	s_nop 0
	global_load_lds_dwordx4 v205, s[100:101]
.Lbal_last_11:
	s_waitcnt vmcnt(6)
	s_waitcnt lgkmcnt(0)
	s_barrier
	s_waitcnt lgkmcnt(0)
	v_mfma_f32_16x16x32_bf16 v[60:63], v[140:143], v[180:183], v[60:63]
	v_mfma_f32_16x16x32_bf16 v[56:59], v[156:159], v[180:183], v[56:59]
	v_mfma_f32_16x16x32_bf16 v[44:47], v[140:143], v[188:191], v[44:47]
	v_mfma_f32_16x16x32_bf16 v[40:43], v[156:159], v[188:191], v[40:43]
	v_mfma_f32_16x16x32_bf16 v[28:31], v[140:143], v[196:199], v[28:31]
	v_mfma_f32_16x16x32_bf16 v[24:27], v[156:159], v[196:199], v[24:27]
	v_mfma_f32_16x16x32_bf16 v[12:15], v[140:143], v[208:211], v[12:15]
	v_mfma_f32_16x16x32_bf16 v[8:11], v[156:159], v[208:211], v[8:11]
	v_mfma_f32_16x16x32_bf16 v[60:63], v[144:147], v[184:187], v[60:63]
	v_mfma_f32_16x16x32_bf16 v[56:59], v[160:163], v[184:187], v[56:59]
	v_mfma_f32_16x16x32_bf16 v[44:47], v[144:147], v[192:195], v[44:47]
	v_mfma_f32_16x16x32_bf16 v[40:43], v[160:163], v[192:195], v[40:43]
	v_mfma_f32_16x16x32_bf16 v[28:31], v[144:147], v[200:203], v[28:31]
	v_mfma_f32_16x16x32_bf16 v[24:27], v[160:163], v[200:203], v[24:27]
	v_mfma_f32_16x16x32_bf16 v[12:15], v[144:147], v[212:215], v[12:15]
	v_mfma_f32_16x16x32_bf16 v[8:11], v[160:163], v[212:215], v[8:11]
	v_mfma_f32_16x16x32_bf16 v[52:55], v[164:167], v[180:183], v[52:55]
	v_mfma_f32_16x16x32_bf16 v[48:51], v[172:175], v[180:183], v[48:51]
	v_mfma_f32_16x16x32_bf16 v[36:39], v[164:167], v[188:191], v[36:39]
	v_mfma_f32_16x16x32_bf16 v[32:35], v[172:175], v[188:191], v[32:35]
	v_mfma_f32_16x16x32_bf16 v[20:23], v[164:167], v[196:199], v[20:23]
	v_mfma_f32_16x16x32_bf16 v[16:19], v[172:175], v[196:199], v[16:19]
	v_mfma_f32_16x16x32_bf16 v[4:7], v[164:167], v[208:211], v[4:7]
	v_mfma_f32_16x16x32_bf16 v[0:3], v[172:175], v[208:211], v[0:3]
	v_mfma_f32_16x16x32_bf16 v[52:55], v[168:171], v[184:187], v[52:55]
	v_mfma_f32_16x16x32_bf16 v[48:51], v[176:179], v[184:187], v[48:51]
	v_mfma_f32_16x16x32_bf16 v[36:39], v[168:171], v[192:195], v[36:39]
	v_mfma_f32_16x16x32_bf16 v[32:35], v[176:179], v[192:195], v[32:35]
	v_mfma_f32_16x16x32_bf16 v[20:23], v[168:171], v[200:203], v[20:23]
	v_mfma_f32_16x16x32_bf16 v[16:19], v[176:179], v[200:203], v[16:19]
	v_mfma_f32_16x16x32_bf16 v[4:7], v[168:171], v[212:215], v[4:7]
	v_mfma_f32_16x16x32_bf16 v[0:3], v[176:179], v[212:215], v[0:3]
	s_barrier
	s_add_i32 s61, s61, 2
	s_add_u32 s59, s59, 0x100
	s_addc_u32 s60, s60, 0
	s_add_u32 s36, s36, 0x100
	s_addc_u32 s37, s37, 0
	s_cmp_gt_u32 s61, 13
	s_cbranch_scc0 .LBB0_1561
	s_setprio 0
	s_and_b64 vcc, exec, s[24:25]
	s_cbranch_vccz .LBB0_1564
	s_barrier

.LBB0_1646:
	s_cmp_eq_i32 s54, -2
	s_cbranch_scc1 .Lbal_first_10
	s_mov_b32 m0, s45
	s_nop 0
	global_load_lds_dwordx4 v221, s[100:101]
	s_mov_b32 m0, s46
	s_nop 0
	global_load_lds_dwordx4 v205, s[100:101]
.Lbal_first_10:
	ds_read_b128 v[144:147], v151
	ds_read_b128 v[156:159], v151 offset:1024
	ds_read_b128 v[160:163], v151 offset:2048
	ds_read_b128 v[164:167], v151 offset:3072
	ds_read_b128 v[168:171], v152
	ds_read_b128 v[172:175], v152 offset:1024
	ds_read_b128 v[176:179], v152 offset:2048
	ds_read_b128 v[180:183], v152 offset:3072
	s_add_u32 s26, s24, 0xfffc0080
	s_addc_u32 s27, s25, -1
	s_cmp_eq_u32 s54, 12
	s_cselect_b32 s29, s19, s27
	s_cselect_b32 s28, s50, s26
	s_cselect_b32 s27, s17, s53
	s_cselect_b32 s26, s51, s52
	s_add_i32 m0, s38, 0xc000
	ds_read_b128 v[184:187], v153
	ds_read_b128 v[188:191], v153 offset:1024
	ds_read_b128 v[192:195], v153 offset:2048
	ds_read_b128 v[196:199], v153 offset:3072
	ds_read_b128 v[200:203], v153 offset:4096
	ds_read_b128 v[208:211], v153 offset:5120
	ds_read_b128 v[212:215], v153 offset:6144
	ds_read_b128 v[216:219], v153 offset:7168
	global_load_lds_dwordx4 v138, s[24:25]
	s_add_i32 m0, s38, 0xe000
	s_nop 0
	global_load_lds_dwordx4 v136, s[24:25]
	s_waitcnt vmcnt(8)
	s_waitcnt lgkmcnt(0)
	s_barrier
	s_waitcnt lgkmcnt(0)
	v_mfma_f32_16x16x32_bf16 v[124:127], v[144:147], v[184:187], v[124:127]
	v_mfma_f32_16x16x32_bf16 v[120:123], v[160:163], v[184:187], v[120:123]
	v_mfma_f32_16x16x32_bf16 v[108:111], v[144:147], v[192:195], v[108:111]
	v_mfma_f32_16x16x32_bf16 v[104:107], v[160:163], v[192:195], v[104:107]
	v_mfma_f32_16x16x32_bf16 v[92:95], v[144:147], v[200:203], v[92:95]
	v_mfma_f32_16x16x32_bf16 v[88:91], v[160:163], v[200:203], v[88:91]
	v_mfma_f32_16x16x32_bf16 v[76:79], v[144:147], v[212:215], v[76:79]
	v_mfma_f32_16x16x32_bf16 v[72:75], v[160:163], v[212:215], v[72:75]
	v_mfma_f32_16x16x32_bf16 v[124:127], v[156:159], v[188:191], v[124:127]
	v_mfma_f32_16x16x32_bf16 v[120:123], v[164:167], v[188:191], v[120:123]
	v_mfma_f32_16x16x32_bf16 v[108:111], v[156:159], v[196:199], v[108:111]
	v_mfma_f32_16x16x32_bf16 v[104:107], v[164:167], v[196:199], v[104:107]
	v_mfma_f32_16x16x32_bf16 v[92:95], v[156:159], v[208:211], v[92:95]
	v_mfma_f32_16x16x32_bf16 v[88:91], v[164:167], v[208:211], v[88:91]
	v_mfma_f32_16x16x32_bf16 v[76:79], v[156:159], v[216:219], v[76:79]
	v_mfma_f32_16x16x32_bf16 v[72:75], v[164:167], v[216:219], v[72:75]
	v_mfma_f32_16x16x32_bf16 v[116:119], v[168:171], v[184:187], v[116:119]
	v_mfma_f32_16x16x32_bf16 v[112:115], v[176:179], v[184:187], v[112:115]
	v_mfma_f32_16x16x32_bf16 v[100:103], v[168:171], v[192:195], v[100:103]
	v_mfma_f32_16x16x32_bf16 v[96:99], v[176:179], v[192:195], v[96:99]
	v_mfma_f32_16x16x32_bf16 v[84:87], v[168:171], v[200:203], v[84:87]
	v_mfma_f32_16x16x32_bf16 v[80:83], v[176:179], v[200:203], v[80:83]
	v_mfma_f32_16x16x32_bf16 v[68:71], v[168:171], v[212:215], v[68:71]
	v_mfma_f32_16x16x32_bf16 v[64:67], v[176:179], v[212:215], v[64:67]
	v_mfma_f32_16x16x32_bf16 v[116:119], v[172:175], v[188:191], v[116:119]
	v_mfma_f32_16x16x32_bf16 v[112:115], v[180:183], v[188:191], v[112:115]
	v_mfma_f32_16x16x32_bf16 v[100:103], v[172:175], v[196:199], v[100:103]
	v_mfma_f32_16x16x32_bf16 v[96:99], v[180:183], v[196:199], v[96:99]
	v_mfma_f32_16x16x32_bf16 v[84:87], v[172:175], v[208:211], v[84:87]
	v_mfma_f32_16x16x32_bf16 v[80:83], v[180:183], v[208:211], v[80:83]
	v_mfma_f32_16x16x32_bf16 v[68:71], v[172:175], v[216:219], v[68:71]
	v_mfma_f32_16x16x32_bf16 v[64:67], v[180:183], v[216:219], v[64:67]
	s_barrier
	s_add_i32 s55, s47, s35
	s_mov_b32 m0, s55
	ds_read_b128 v[184:187], v153 offset:16384
	ds_read_b128 v[188:191], v153 offset:17408
	ds_read_b128 v[192:195], v153 offset:18432
	ds_read_b128 v[196:199], v153 offset:19456
	ds_read_b128 v[200:203], v153 offset:20480
	ds_read_b128 v[208:211], v153 offset:21504
	ds_read_b128 v[212:215], v153 offset:22528
	ds_read_b128 v[216:219], v153 offset:23552
	global_load_lds_dwordx4 v132, s[26:27]
	s_add_i32 m0, s55, 0x2000
	s_add_u32 s56, s26, 0x40000
	s_mov_b64 s[98:99], s[26:27]
	s_addc_u32 s57, s27, 0
	s_add_i32 s55, s48, s35
	global_load_lds_dwordx4 v128, s[26:27]
	s_mov_b32 m0, s55
	s_mov_b64 s[100:101], s[28:29]
	global_load_lds_dwordx4 v132, s[56:57]
	s_add_i32 m0, s55, 0x2000
	s_nop 0
	global_load_lds_dwordx4 v128, s[56:57]
	s_waitcnt vmcnt(6)
	s_waitcnt lgkmcnt(0)
	s_barrier
	s_waitcnt lgkmcnt(0)
	v_mfma_f32_16x16x32_bf16 v[60:63], v[144:147], v[184:187], v[60:63]
	v_mfma_f32_16x16x32_bf16 v[56:59], v[160:163], v[184:187], v[56:59]
	v_mfma_f32_16x16x32_bf16 v[44:47], v[144:147], v[192:195], v[44:47]
	v_mfma_f32_16x16x32_bf16 v[40:43], v[160:163], v[192:195], v[40:43]
	v_mfma_f32_16x16x32_bf16 v[28:31], v[144:147], v[200:203], v[28:31]
	v_mfma_f32_16x16x32_bf16 v[24:27], v[160:163], v[200:203], v[24:27]
	v_mfma_f32_16x16x32_bf16 v[12:15], v[144:147], v[212:215], v[12:15]
	v_mfma_f32_16x16x32_bf16 v[8:11], v[160:163], v[212:215], v[8:11]
	v_mfma_f32_16x16x32_bf16 v[60:63], v[156:159], v[188:191], v[60:63]
	v_mfma_f32_16x16x32_bf16 v[56:59], v[164:167], v[188:191], v[56:59]
	v_mfma_f32_16x16x32_bf16 v[44:47], v[156:159], v[196:199], v[44:47]
	v_mfma_f32_16x16x32_bf16 v[40:43], v[164:167], v[196:199], v[40:43]
	v_mfma_f32_16x16x32_bf16 v[28:31], v[156:159], v[208:211], v[28:31]
	v_mfma_f32_16x16x32_bf16 v[24:27], v[164:167], v[208:211], v[24:27]
	v_mfma_f32_16x16x32_bf16 v[12:15], v[156:159], v[216:219], v[12:15]
	v_mfma_f32_16x16x32_bf16 v[8:11], v[164:167], v[216:219], v[8:11]
	v_mfma_f32_16x16x32_bf16 v[52:55], v[168:171], v[184:187], v[52:55]
	v_mfma_f32_16x16x32_bf16 v[48:51], v[176:179], v[184:187], v[48:51]
	v_mfma_f32_16x16x32_bf16 v[36:39], v[168:171], v[192:195], v[36:39]
	v_mfma_f32_16x16x32_bf16 v[32:35], v[176:179], v[192:195], v[32:35]
	v_mfma_f32_16x16x32_bf16 v[20:23], v[168:171], v[200:203], v[20:23]
	v_mfma_f32_16x16x32_bf16 v[16:19], v[176:179], v[200:203], v[16:19]
	v_mfma_f32_16x16x32_bf16 v[4:7], v[168:171], v[212:215], v[4:7]
	v_mfma_f32_16x16x32_bf16 v[0:3], v[176:179], v[212:215], v[0:3]
	v_mfma_f32_16x16x32_bf16 v[52:55], v[172:175], v[188:191], v[52:55]
	v_mfma_f32_16x16x32_bf16 v[48:51], v[180:183], v[188:191], v[48:51]
	v_mfma_f32_16x16x32_bf16 v[36:39], v[172:175], v[196:199], v[36:39]
	v_mfma_f32_16x16x32_bf16 v[32:35], v[180:183], v[196:199], v[32:35]
	v_mfma_f32_16x16x32_bf16 v[20:23], v[172:175], v[208:211], v[20:23]
	v_mfma_f32_16x16x32_bf16 v[16:19], v[180:183], v[208:211], v[16:19]
	v_mfma_f32_16x16x32_bf16 v[4:7], v[172:175], v[216:219], v[4:7]
	v_mfma_f32_16x16x32_bf16 v[0:3], v[180:183], v[216:219], v[0:3]
	s_barrier
	s_mov_b32 m0, s38
	s_nop 0
	global_load_lds_dwordx4 v134, s[28:29]
	s_mov_b32 m0, s39
	s_nop 0
	global_load_lds_dwordx4 v130, s[28:29]
	s_add_i32 s55, 0, 0x18000
	s_add_i32 s56, 0, 0x1c000
	v_add_u32_e32 v164, s55, v149
	v_add_u32_e32 v180, s56, v149
	ds_read_b128 v[144:147], v164
	ds_read_b128 v[156:159], v164 offset:1024
	ds_read_b128 v[160:163], v164 offset:2048
	ds_read_b128 v[164:167], v164 offset:3072
	ds_read_b128 v[168:171], v180
	ds_read_b128 v[172:175], v180 offset:1024
	ds_read_b128 v[176:179], v180 offset:2048
	ds_read_b128 v[180:183], v180 offset:3072
	s_add_u32 s28, s28, 0x40000
	s_addc_u32 s29, s29, 0
	s_mov_b32 m0, s40
	ds_read_b128 v[184:187], v153 offset:32768
	ds_read_b128 v[188:191], v153 offset:33792
	ds_read_b128 v[192:195], v153 offset:34816
	ds_read_b128 v[196:199], v153 offset:35840
	ds_read_b128 v[200:203], v153 offset:36864
	ds_read_b128 v[208:211], v153 offset:37888
	ds_read_b128 v[212:215], v153 offset:38912
	ds_read_b128 v[216:219], v153 offset:39936
	global_load_lds_dwordx4 v134, s[28:29]
	s_mov_b32 m0, s41
	s_nop 0
	global_load_lds_dwordx4 v130, s[28:29]
	s_waitcnt vmcnt(8)
	s_waitcnt lgkmcnt(0)
	s_barrier
	s_waitcnt lgkmcnt(0)
	v_mfma_f32_16x16x32_bf16 v[124:127], v[144:147], v[184:187], v[124:127]
	v_mfma_f32_16x16x32_bf16 v[120:123], v[160:163], v[184:187], v[120:123]
	v_mfma_f32_16x16x32_bf16 v[108:111], v[144:147], v[192:195], v[108:111]
	v_mfma_f32_16x16x32_bf16 v[104:107], v[160:163], v[192:195], v[104:107]
	v_mfma_f32_16x16x32_bf16 v[92:95], v[144:147], v[200:203], v[92:95]
	v_mfma_f32_16x16x32_bf16 v[88:91], v[160:163], v[200:203], v[88:91]
	v_mfma_f32_16x16x32_bf16 v[76:79], v[144:147], v[212:215], v[76:79]
	v_mfma_f32_16x16x32_bf16 v[72:75], v[160:163], v[212:215], v[72:75]
	v_mfma_f32_16x16x32_bf16 v[124:127], v[156:159], v[188:191], v[124:127]
	v_mfma_f32_16x16x32_bf16 v[120:123], v[164:167], v[188:191], v[120:123]
	v_mfma_f32_16x16x32_bf16 v[108:111], v[156:159], v[196:199], v[108:111]
	v_mfma_f32_16x16x32_bf16 v[104:107], v[164:167], v[196:199], v[104:107]
	v_mfma_f32_16x16x32_bf16 v[92:95], v[156:159], v[208:211], v[92:95]
	v_mfma_f32_16x16x32_bf16 v[88:91], v[164:167], v[208:211], v[88:91]
	v_mfma_f32_16x16x32_bf16 v[76:79], v[156:159], v[216:219], v[76:79]
	v_mfma_f32_16x16x32_bf16 v[72:75], v[164:167], v[216:219], v[72:75]
	v_mfma_f32_16x16x32_bf16 v[116:119], v[168:171], v[184:187], v[116:119]
	v_mfma_f32_16x16x32_bf16 v[112:115], v[176:179], v[184:187], v[112:115]
	v_mfma_f32_16x16x32_bf16 v[100:103], v[168:171], v[192:195], v[100:103]
	v_mfma_f32_16x16x32_bf16 v[96:99], v[176:179], v[192:195], v[96:99]
	v_mfma_f32_16x16x32_bf16 v[84:87], v[168:171], v[200:203], v[84:87]
	v_mfma_f32_16x16x32_bf16 v[80:83], v[176:179], v[200:203], v[80:83]
	v_mfma_f32_16x16x32_bf16 v[68:71], v[168:171], v[212:215], v[68:71]
	v_mfma_f32_16x16x32_bf16 v[64:67], v[176:179], v[212:215], v[64:67]
	v_mfma_f32_16x16x32_bf16 v[116:119], v[172:175], v[188:191], v[116:119]
	v_mfma_f32_16x16x32_bf16 v[112:115], v[180:183], v[188:191], v[112:115]
	v_mfma_f32_16x16x32_bf16 v[100:103], v[172:175], v[196:199], v[100:103]
	v_mfma_f32_16x16x32_bf16 v[96:99], v[180:183], v[196:199], v[96:99]
	v_mfma_f32_16x16x32_bf16 v[84:87], v[172:175], v[208:211], v[84:87]
	v_mfma_f32_16x16x32_bf16 v[80:83], v[180:183], v[208:211], v[80:83]
	v_mfma_f32_16x16x32_bf16 v[68:71], v[172:175], v[216:219], v[68:71]
	v_mfma_f32_16x16x32_bf16 v[64:67], v[180:183], v[216:219], v[64:67]
	s_barrier
	s_add_i32 s28, s55, s35
	s_mov_b32 m0, s28
	ds_read_b128 v[184:187], v153 offset:49152
	ds_read_b128 v[188:191], v153 offset:50176
	ds_read_b128 v[192:195], v153 offset:51200
	ds_read_b128 v[196:199], v153 offset:52224
	ds_read_b128 v[200:203], v153 offset:53248
	ds_read_b128 v[208:211], v153 offset:54272
	ds_read_b128 v[212:215], v153 offset:55296
	ds_read_b128 v[216:219], v153 offset:56320
	global_load_lds_dwordx4 v220, s[26:27]
	s_add_i32 m0, s28, 0x2000
	s_add_u32 s26, s26, 0x40080
	s_addc_u32 s27, s27, 0
	s_add_i32 s28, s56, s35
	global_load_lds_dwordx4 v204, s[98:99]
	s_mov_b32 m0, s28
	s_nop 0
	global_load_lds_dwordx4 v132, s[26:27]
	s_add_i32 m0, s28, 0x2000
	s_nop 0
	global_load_lds_dwordx4 v128, s[26:27]
	s_cmp_lg_u32 s54, 12
	s_cbranch_scc1 .Lbal_last_10
	s_mov_b32 m0, s45
	s_nop 0
	global_load_lds_dwordx4 v221, s[100:101]
	s_mov_b32 m0, s46
	s_nop 0
	global_load_lds_dwordx4 v205, s[100:101]
.Lbal_last_10:
	s_waitcnt vmcnt(6)
	s_waitcnt lgkmcnt(0)
	s_barrier
	s_waitcnt lgkmcnt(0)
	v_mfma_f32_16x16x32_bf16 v[60:63], v[144:147], v[184:187], v[60:63]
	v_mfma_f32_16x16x32_bf16 v[56:59], v[160:163], v[184:187], v[56:59]
	v_mfma_f32_16x16x32_bf16 v[44:47], v[144:147], v[192:195], v[44:47]
	v_mfma_f32_16x16x32_bf16 v[40:43], v[160:163], v[192:195], v[40:43]
	v_mfma_f32_16x16x32_bf16 v[28:31], v[144:147], v[200:203], v[28:31]
	v_mfma_f32_16x16x32_bf16 v[24:27], v[160:163], v[200:203], v[24:27]
	v_mfma_f32_16x16x32_bf16 v[12:15], v[144:147], v[212:215], v[12:15]
	v_mfma_f32_16x16x32_bf16 v[8:11], v[160:163], v[212:215], v[8:11]
	v_mfma_f32_16x16x32_bf16 v[60:63], v[156:159], v[188:191], v[60:63]
	v_mfma_f32_16x16x32_bf16 v[56:59], v[164:167], v[188:191], v[56:59]
	v_mfma_f32_16x16x32_bf16 v[44:47], v[156:159], v[196:199], v[44:47]
	v_mfma_f32_16x16x32_bf16 v[40:43], v[164:167], v[196:199], v[40:43]
	v_mfma_f32_16x16x32_bf16 v[28:31], v[156:159], v[208:211], v[28:31]
	v_mfma_f32_16x16x32_bf16 v[24:27], v[164:167], v[208:211], v[24:27]
	v_mfma_f32_16x16x32_bf16 v[12:15], v[156:159], v[216:219], v[12:15]
	v_mfma_f32_16x16x32_bf16 v[8:11], v[164:167], v[216:219], v[8:11]
	v_mfma_f32_16x16x32_bf16 v[52:55], v[168:171], v[184:187], v[52:55]
	v_mfma_f32_16x16x32_bf16 v[48:51], v[176:179], v[184:187], v[48:51]
	v_mfma_f32_16x16x32_bf16 v[36:39], v[168:171], v[192:195], v[36:39]
	v_mfma_f32_16x16x32_bf16 v[32:35], v[176:179], v[192:195], v[32:35]
	v_mfma_f32_16x16x32_bf16 v[20:23], v[168:171], v[200:203], v[20:23]
	v_mfma_f32_16x16x32_bf16 v[16:19], v[176:179], v[200:203], v[16:19]
	v_mfma_f32_16x16x32_bf16 v[4:7], v[168:171], v[212:215], v[4:7]
	v_mfma_f32_16x16x32_bf16 v[0:3], v[176:179], v[212:215], v[0:3]
	v_mfma_f32_16x16x32_bf16 v[52:55], v[172:175], v[188:191], v[52:55]
	v_mfma_f32_16x16x32_bf16 v[48:51], v[180:183], v[188:191], v[48:51]
	v_mfma_f32_16x16x32_bf16 v[36:39], v[172:175], v[196:199], v[36:39]
	v_mfma_f32_16x16x32_bf16 v[32:35], v[180:183], v[196:199], v[32:35]
	v_mfma_f32_16x16x32_bf16 v[20:23], v[172:175], v[208:211], v[20:23]
	v_mfma_f32_16x16x32_bf16 v[16:19], v[180:183], v[208:211], v[16:19]
	v_mfma_f32_16x16x32_bf16 v[4:7], v[172:175], v[216:219], v[4:7]
	v_mfma_f32_16x16x32_bf16 v[0:3], v[180:183], v[216:219], v[0:3]
	s_barrier
	s_add_i32 s54, s54, 2
	s_add_u32 s52, s52, 0x100
	s_addc_u32 s53, s53, 0
	s_add_u32 s24, s24, 0x100
	s_addc_u32 s25, s25, 0
	s_cmp_gt_u32 s54, 13
	s_cbranch_scc0 .LBB0_1646
	s_setprio 0
	s_and_b64 vcc, exec, s[14:15]
	s_cbranch_vccz .LBB0_1649
	s_barrier
